# snake order: chained pairs ordered and k-flipped so adjacent MFMAs share an A or B operand quad
# speedup vs baseline: 1.0220x; 1.0023x over previous
.LBB0_147:
	ds_read_b128 v[144:147], v165
	v_xor_b32_e32 v177, 64, v165
	ds_read_b128 v[148:151], v177
	ds_read_b128 v[170:173], v165 offset:2048
	ds_read_b128 v[174:177], v177 offset:2048
	s_add_u32 s18, s16, 0xfff80080
	s_addc_u32 s19, s17, -1
	s_cmp_eq_u32 s47, 28
	s_cselect_b32 s21, s11, s19
	s_cselect_b32 s20, s41, s18
	s_cselect_b32 s19, s9, s46
	s_cselect_b32 s18, s44, s45
	v_lshl_add_u64 v[210:211], s[16:17], 0, v[136:137]
	s_add_i32 m0, s1, 0xc000
	ds_read_b128 v[178:181], v166
	v_xor_b32_e32 v209, 64, v166
	ds_read_b128 v[182:185], v209
	ds_read_b128 v[186:189], v166 offset:2048
	ds_read_b128 v[190:193], v209 offset:2048
	ds_read_b128 v[194:197], v166 offset:4096
	ds_read_b128 v[198:201], v209 offset:4096
	ds_read_b128 v[202:205], v166 offset:6144
	ds_read_b128 v[206:209], v209 offset:6144
	global_load_lds_dwordx4 v[210:211], off
	v_lshl_add_u64 v[210:211], s[16:17], 0, v[138:139]
	s_add_i32 m0, s1, 0xe000
	s_nop 0
	global_load_lds_dwordx4 v[210:211], off
	s_waitcnt lgkmcnt(8)
	s_barrier
	s_waitcnt lgkmcnt(0)
	s_setprio 1
	s_waitcnt lgkmcnt(0)
	v_mfma_f32_16x16x32_bf16 v[124:127], v[144:147], v[178:181], v[124:127]
	v_mfma_f32_16x16x32_bf16 v[124:127], v[148:151], v[182:185], v[124:127]
	v_mfma_f32_16x16x32_bf16 v[120:123], v[174:177], v[182:185], v[120:123]
	v_mfma_f32_16x16x32_bf16 v[120:123], v[170:173], v[178:181], v[120:123]
	v_mfma_f32_16x16x32_bf16 v[104:107], v[170:173], v[186:189], v[104:107]
	v_mfma_f32_16x16x32_bf16 v[104:107], v[174:177], v[190:193], v[104:107]
	v_mfma_f32_16x16x32_bf16 v[108:111], v[148:151], v[190:193], v[108:111]
	v_mfma_f32_16x16x32_bf16 v[108:111], v[144:147], v[186:189], v[108:111]
	v_mfma_f32_16x16x32_bf16 v[92:95], v[144:147], v[194:197], v[92:95]
	v_mfma_f32_16x16x32_bf16 v[92:95], v[148:151], v[198:201], v[92:95]
	v_mfma_f32_16x16x32_bf16 v[88:91], v[174:177], v[198:201], v[88:91]
	v_mfma_f32_16x16x32_bf16 v[88:91], v[170:173], v[194:197], v[88:91]
	v_mfma_f32_16x16x32_bf16 v[72:75], v[170:173], v[202:205], v[72:75]
	v_mfma_f32_16x16x32_bf16 v[72:75], v[174:177], v[206:209], v[72:75]
	v_mfma_f32_16x16x32_bf16 v[76:79], v[148:151], v[206:209], v[76:79]
	v_mfma_f32_16x16x32_bf16 v[76:79], v[144:147], v[202:205], v[76:79]
	s_setprio 0
	s_barrier
	s_add_i32 s48, s35, s24
	v_lshl_add_u64 v[220:221], s[18:19], 0, v[132:133]
	s_mov_b32 m0, s48
	ds_read_b128 v[210:213], v167
	v_xor_b32_e32 v233, 64, v167
	ds_read_b128 v[214:217], v233
	ds_read_b128 v[226:229], v167 offset:2048
	ds_read_b128 v[230:233], v233 offset:2048
	global_load_lds_dwordx4 v[220:221], off
	v_lshl_add_u64 v[234:235], s[18:19], 0, v[128:129]
	s_add_i32 m0, s48, 0x2000
	s_nop 0
	global_load_lds_dwordx4 v[234:235], off
	s_barrier
	s_waitcnt lgkmcnt(0)
	s_setprio 1
	s_waitcnt lgkmcnt(0)
	v_mfma_f32_16x16x32_bf16 v[116:119], v[210:213], v[178:181], v[116:119]
	v_mfma_f32_16x16x32_bf16 v[116:119], v[214:217], v[182:185], v[116:119]
	v_mfma_f32_16x16x32_bf16 v[112:115], v[230:233], v[182:185], v[112:115]
	v_mfma_f32_16x16x32_bf16 v[112:115], v[226:229], v[178:181], v[112:115]
	v_mfma_f32_16x16x32_bf16 v[96:99], v[226:229], v[186:189], v[96:99]
	v_mfma_f32_16x16x32_bf16 v[96:99], v[230:233], v[190:193], v[96:99]
	v_mfma_f32_16x16x32_bf16 v[100:103], v[214:217], v[190:193], v[100:103]
	v_mfma_f32_16x16x32_bf16 v[100:103], v[210:213], v[186:189], v[100:103]
	v_mfma_f32_16x16x32_bf16 v[84:87], v[210:213], v[194:197], v[84:87]
	v_mfma_f32_16x16x32_bf16 v[84:87], v[214:217], v[198:201], v[84:87]
	v_mfma_f32_16x16x32_bf16 v[80:83], v[230:233], v[198:201], v[80:83]
	v_mfma_f32_16x16x32_bf16 v[80:83], v[226:229], v[194:197], v[80:83]
	v_mfma_f32_16x16x32_bf16 v[64:67], v[226:229], v[202:205], v[64:67]
	v_mfma_f32_16x16x32_bf16 v[64:67], v[230:233], v[206:209], v[64:67]
	v_mfma_f32_16x16x32_bf16 v[68:71], v[214:217], v[206:209], v[68:71]
	v_mfma_f32_16x16x32_bf16 v[68:71], v[210:213], v[202:205], v[68:71]
	s_setprio 0
	s_mov_b32 m0, s1
	v_lshl_add_u64 v[236:237], s[20:21], 0, v[134:135]
	s_barrier
	ds_read_b128 v[178:181], v166 offset:16384
	v_xor_b32_e32 v209, 64, v166
	ds_read_b128 v[182:185], v209 offset:16384
	ds_read_b128 v[186:189], v166 offset:18432
	ds_read_b128 v[190:193], v209 offset:18432
	ds_read_b128 v[194:197], v166 offset:20480
	ds_read_b128 v[198:201], v209 offset:20480
	ds_read_b128 v[202:205], v166 offset:22528
	ds_read_b128 v[206:209], v209 offset:22528
	global_load_lds_dwordx4 v[236:237], off
	v_lshl_add_u64 v[240:241], s[20:21], 0, v[130:131]
	s_mov_b32 m0, s26
	s_nop 0
	global_load_lds_dwordx4 v[240:241], off
	s_barrier
	s_waitcnt lgkmcnt(0)
	s_setprio 1
	s_waitcnt lgkmcnt(0)
	v_mfma_f32_16x16x32_bf16 v[60:63], v[144:147], v[178:181], v[60:63]
	v_mfma_f32_16x16x32_bf16 v[60:63], v[148:151], v[182:185], v[60:63]
	v_mfma_f32_16x16x32_bf16 v[56:59], v[174:177], v[182:185], v[56:59]
	v_mfma_f32_16x16x32_bf16 v[56:59], v[170:173], v[178:181], v[56:59]
	v_mfma_f32_16x16x32_bf16 v[40:43], v[170:173], v[186:189], v[40:43]
	v_mfma_f32_16x16x32_bf16 v[40:43], v[174:177], v[190:193], v[40:43]
	v_mfma_f32_16x16x32_bf16 v[44:47], v[148:151], v[190:193], v[44:47]
	v_mfma_f32_16x16x32_bf16 v[44:47], v[144:147], v[186:189], v[44:47]
	v_mfma_f32_16x16x32_bf16 v[28:31], v[144:147], v[194:197], v[28:31]
	v_mfma_f32_16x16x32_bf16 v[28:31], v[148:151], v[198:201], v[28:31]
	v_mfma_f32_16x16x32_bf16 v[24:27], v[174:177], v[198:201], v[24:27]
	v_mfma_f32_16x16x32_bf16 v[24:27], v[170:173], v[194:197], v[24:27]
	v_mfma_f32_16x16x32_bf16 v[8:11], v[170:173], v[202:205], v[8:11]
	v_mfma_f32_16x16x32_bf16 v[8:11], v[174:177], v[206:209], v[8:11]
	v_mfma_f32_16x16x32_bf16 v[12:15], v[148:151], v[206:209], v[12:15]
	v_mfma_f32_16x16x32_bf16 v[12:15], v[144:147], v[202:205], v[12:15]
	s_setprio 0
	s_barrier
	s_add_u32 s48, s18, 0x80000
	s_addc_u32 s49, s19, 0
	s_add_i32 s52, s38, s24
	v_lshl_add_u64 v[144:145], s[48:49], 0, v[132:133]
	s_mov_b32 m0, s52
	s_nop 0
	global_load_lds_dwordx4 v[144:145], off
	v_lshl_add_u64 v[144:145], s[48:49], 0, v[128:129]
	s_add_i32 m0, s52, 0x2000
	s_nop 0
	global_load_lds_dwordx4 v[144:145], off
	s_waitcnt vmcnt(6)
	s_barrier
	s_setprio 1
	v_mfma_f32_16x16x32_bf16 v[52:55], v[210:213], v[178:181], v[52:55]
	v_mfma_f32_16x16x32_bf16 v[52:55], v[214:217], v[182:185], v[52:55]
	v_mfma_f32_16x16x32_bf16 v[48:51], v[230:233], v[182:185], v[48:51]
	v_mfma_f32_16x16x32_bf16 v[48:51], v[226:229], v[178:181], v[48:51]
	v_mfma_f32_16x16x32_bf16 v[32:35], v[226:229], v[186:189], v[32:35]
	v_mfma_f32_16x16x32_bf16 v[32:35], v[230:233], v[190:193], v[32:35]
	v_mfma_f32_16x16x32_bf16 v[36:39], v[214:217], v[190:193], v[36:39]
	v_mfma_f32_16x16x32_bf16 v[36:39], v[210:213], v[186:189], v[36:39]
	v_mfma_f32_16x16x32_bf16 v[20:23], v[210:213], v[194:197], v[20:23]
	v_mfma_f32_16x16x32_bf16 v[20:23], v[214:217], v[198:201], v[20:23]
	v_mfma_f32_16x16x32_bf16 v[16:19], v[230:233], v[198:201], v[16:19]
	v_mfma_f32_16x16x32_bf16 v[16:19], v[226:229], v[194:197], v[16:19]
	v_mfma_f32_16x16x32_bf16 v[0:3], v[226:229], v[202:205], v[0:3]
	v_mfma_f32_16x16x32_bf16 v[0:3], v[230:233], v[206:209], v[0:3]
	v_mfma_f32_16x16x32_bf16 v[4:7], v[214:217], v[206:209], v[4:7]
	v_mfma_f32_16x16x32_bf16 v[4:7], v[210:213], v[202:205], v[4:7]
	s_setprio 0
	s_add_i32 s48, 0, 0x18000
	v_add_u32_e32 v169, s48, v161
	s_barrier
	ds_read_b128 v[144:147], v169
	v_xor_b32_e32 v177, 64, v169
	ds_read_b128 v[148:151], v177
	ds_read_b128 v[170:173], v169 offset:2048
	ds_read_b128 v[174:177], v177 offset:2048
	s_add_u32 s20, s20, 0x80000
	s_addc_u32 s21, s21, 0
	s_mov_b32 m0, s27
	v_lshl_add_u64 v[210:211], s[20:21], 0, v[134:135]
	ds_read_b128 v[178:181], v166 offset:32768
	v_xor_b32_e32 v209, 64, v166
	ds_read_b128 v[182:185], v209 offset:32768
	ds_read_b128 v[186:189], v166 offset:34816
	ds_read_b128 v[190:193], v209 offset:34816
	ds_read_b128 v[194:197], v166 offset:36864
	ds_read_b128 v[198:201], v209 offset:36864
	ds_read_b128 v[202:205], v166 offset:38912
	ds_read_b128 v[206:209], v209 offset:38912
	global_load_lds_dwordx4 v[210:211], off
	v_lshl_add_u64 v[210:211], s[20:21], 0, v[130:131]
	s_mov_b32 m0, s28
	s_nop 0
	global_load_lds_dwordx4 v[210:211], off
	s_waitcnt lgkmcnt(8)
	s_barrier
	s_waitcnt lgkmcnt(0)
	s_setprio 1
	s_waitcnt lgkmcnt(0)
	v_mfma_f32_16x16x32_bf16 v[124:127], v[144:147], v[178:181], v[124:127]
	v_mfma_f32_16x16x32_bf16 v[124:127], v[148:151], v[182:185], v[124:127]
	v_mfma_f32_16x16x32_bf16 v[120:123], v[174:177], v[182:185], v[120:123]
	v_mfma_f32_16x16x32_bf16 v[120:123], v[170:173], v[178:181], v[120:123]
	v_mfma_f32_16x16x32_bf16 v[104:107], v[170:173], v[186:189], v[104:107]
	v_mfma_f32_16x16x32_bf16 v[104:107], v[174:177], v[190:193], v[104:107]
	v_mfma_f32_16x16x32_bf16 v[108:111], v[148:151], v[190:193], v[108:111]
	v_mfma_f32_16x16x32_bf16 v[108:111], v[144:147], v[186:189], v[108:111]
	v_mfma_f32_16x16x32_bf16 v[92:95], v[144:147], v[194:197], v[92:95]
	v_mfma_f32_16x16x32_bf16 v[92:95], v[148:151], v[198:201], v[92:95]
	v_mfma_f32_16x16x32_bf16 v[88:91], v[174:177], v[198:201], v[88:91]
	v_mfma_f32_16x16x32_bf16 v[88:91], v[170:173], v[194:197], v[88:91]
	v_mfma_f32_16x16x32_bf16 v[72:75], v[170:173], v[202:205], v[72:75]
	v_mfma_f32_16x16x32_bf16 v[72:75], v[174:177], v[206:209], v[72:75]
	v_mfma_f32_16x16x32_bf16 v[76:79], v[148:151], v[206:209], v[76:79]
	v_mfma_f32_16x16x32_bf16 v[76:79], v[144:147], v[202:205], v[76:79]
	s_setprio 0
	s_barrier
	s_add_i32 s20, 0, 0x1c000
	s_add_i32 s21, s48, s24
	v_add_u32_e32 v169, s20, v161
	v_lshl_add_u64 v[220:221], v[220:221], 0, s[6:7]
	s_mov_b32 m0, s21
	ds_read_b128 v[210:213], v169
	v_xor_b32_e32 v233, 64, v169
	ds_read_b128 v[214:217], v233
	ds_read_b128 v[226:229], v169 offset:2048
	ds_read_b128 v[230:233], v233 offset:2048
	global_load_lds_dwordx4 v[220:221], off
	v_lshl_add_u64 v[220:221], v[234:235], 0, s[6:7]
	s_add_i32 m0, s21, 0x2000
	s_nop 0
	global_load_lds_dwordx4 v[220:221], off
	s_barrier
	s_waitcnt lgkmcnt(0)
	s_setprio 1
	s_waitcnt lgkmcnt(0)
	v_mfma_f32_16x16x32_bf16 v[116:119], v[210:213], v[178:181], v[116:119]
	v_mfma_f32_16x16x32_bf16 v[116:119], v[214:217], v[182:185], v[116:119]
	v_mfma_f32_16x16x32_bf16 v[112:115], v[230:233], v[182:185], v[112:115]
	v_mfma_f32_16x16x32_bf16 v[112:115], v[226:229], v[178:181], v[112:115]
	v_mfma_f32_16x16x32_bf16 v[96:99], v[226:229], v[186:189], v[96:99]
	v_mfma_f32_16x16x32_bf16 v[96:99], v[230:233], v[190:193], v[96:99]
	v_mfma_f32_16x16x32_bf16 v[100:103], v[214:217], v[190:193], v[100:103]
	v_mfma_f32_16x16x32_bf16 v[100:103], v[210:213], v[186:189], v[100:103]
	v_mfma_f32_16x16x32_bf16 v[84:87], v[210:213], v[194:197], v[84:87]
	v_mfma_f32_16x16x32_bf16 v[84:87], v[214:217], v[198:201], v[84:87]
	v_mfma_f32_16x16x32_bf16 v[80:83], v[230:233], v[198:201], v[80:83]
	v_mfma_f32_16x16x32_bf16 v[80:83], v[226:229], v[194:197], v[80:83]
	v_mfma_f32_16x16x32_bf16 v[64:67], v[226:229], v[202:205], v[64:67]
	v_mfma_f32_16x16x32_bf16 v[64:67], v[230:233], v[206:209], v[64:67]
	v_mfma_f32_16x16x32_bf16 v[68:71], v[214:217], v[206:209], v[68:71]
	v_mfma_f32_16x16x32_bf16 v[68:71], v[210:213], v[202:205], v[68:71]
	s_setprio 0
	s_mov_b32 m0, s30
	v_lshl_add_u64 v[220:221], v[236:237], 0, s[6:7]
	s_barrier
	ds_read_b128 v[178:181], v166 offset:49152
	v_xor_b32_e32 v209, 64, v166
	ds_read_b128 v[182:185], v209 offset:49152
	ds_read_b128 v[186:189], v166 offset:51200
	ds_read_b128 v[190:193], v209 offset:51200
	ds_read_b128 v[194:197], v166 offset:53248
	ds_read_b128 v[198:201], v209 offset:53248
	ds_read_b128 v[202:205], v166 offset:55296
	ds_read_b128 v[206:209], v209 offset:55296
	global_load_lds_dwordx4 v[220:221], off
	v_lshl_add_u64 v[220:221], v[240:241], 0, s[6:7]
	s_mov_b32 m0, s31
	s_nop 0
	global_load_lds_dwordx4 v[220:221], off
	s_barrier
	s_waitcnt lgkmcnt(0)
	s_setprio 1
	s_waitcnt lgkmcnt(0)
	v_mfma_f32_16x16x32_bf16 v[60:63], v[144:147], v[178:181], v[60:63]
	v_mfma_f32_16x16x32_bf16 v[60:63], v[148:151], v[182:185], v[60:63]
	v_mfma_f32_16x16x32_bf16 v[56:59], v[174:177], v[182:185], v[56:59]
	v_mfma_f32_16x16x32_bf16 v[56:59], v[170:173], v[178:181], v[56:59]
	v_mfma_f32_16x16x32_bf16 v[40:43], v[170:173], v[186:189], v[40:43]
	v_mfma_f32_16x16x32_bf16 v[40:43], v[174:177], v[190:193], v[40:43]
	v_mfma_f32_16x16x32_bf16 v[44:47], v[148:151], v[190:193], v[44:47]
	v_mfma_f32_16x16x32_bf16 v[44:47], v[144:147], v[186:189], v[44:47]
	v_mfma_f32_16x16x32_bf16 v[28:31], v[144:147], v[194:197], v[28:31]
	v_mfma_f32_16x16x32_bf16 v[28:31], v[148:151], v[198:201], v[28:31]
	v_mfma_f32_16x16x32_bf16 v[24:27], v[174:177], v[198:201], v[24:27]
	v_mfma_f32_16x16x32_bf16 v[24:27], v[170:173], v[194:197], v[24:27]
	v_mfma_f32_16x16x32_bf16 v[8:11], v[170:173], v[202:205], v[8:11]
	v_mfma_f32_16x16x32_bf16 v[8:11], v[174:177], v[206:209], v[8:11]
	v_mfma_f32_16x16x32_bf16 v[12:15], v[148:151], v[206:209], v[12:15]
	v_mfma_f32_16x16x32_bf16 v[12:15], v[144:147], v[202:205], v[12:15]
	s_setprio 0
	s_barrier
	s_add_u32 s18, s18, 0x80080
	s_addc_u32 s19, s19, 0
	s_add_i32 s20, s20, s24
	v_lshl_add_u64 v[144:145], s[18:19], 0, v[132:133]
	s_mov_b32 m0, s20
	s_nop 0
	global_load_lds_dwordx4 v[144:145], off
	v_lshl_add_u64 v[144:145], s[18:19], 0, v[128:129]
	s_add_i32 m0, s20, 0x2000
	s_nop 0
	global_load_lds_dwordx4 v[144:145], off
	s_waitcnt vmcnt(6)
	s_barrier
	s_setprio 1
	v_mfma_f32_16x16x32_bf16 v[52:55], v[210:213], v[178:181], v[52:55]
	v_mfma_f32_16x16x32_bf16 v[52:55], v[214:217], v[182:185], v[52:55]
	v_mfma_f32_16x16x32_bf16 v[48:51], v[230:233], v[182:185], v[48:51]
	v_mfma_f32_16x16x32_bf16 v[48:51], v[226:229], v[178:181], v[48:51]
	v_mfma_f32_16x16x32_bf16 v[32:35], v[226:229], v[186:189], v[32:35]
	v_mfma_f32_16x16x32_bf16 v[32:35], v[230:233], v[190:193], v[32:35]
	v_mfma_f32_16x16x32_bf16 v[36:39], v[214:217], v[190:193], v[36:39]
	v_mfma_f32_16x16x32_bf16 v[36:39], v[210:213], v[186:189], v[36:39]
	v_mfma_f32_16x16x32_bf16 v[20:23], v[210:213], v[194:197], v[20:23]
	v_mfma_f32_16x16x32_bf16 v[20:23], v[214:217], v[198:201], v[20:23]
	v_mfma_f32_16x16x32_bf16 v[16:19], v[230:233], v[198:201], v[16:19]
	v_mfma_f32_16x16x32_bf16 v[16:19], v[226:229], v[194:197], v[16:19]
	v_mfma_f32_16x16x32_bf16 v[0:3], v[226:229], v[202:205], v[0:3]
	v_mfma_f32_16x16x32_bf16 v[0:3], v[230:233], v[206:209], v[0:3]
	v_mfma_f32_16x16x32_bf16 v[4:7], v[214:217], v[206:209], v[4:7]
	v_mfma_f32_16x16x32_bf16 v[4:7], v[210:213], v[202:205], v[4:7]
	s_setprio 0
	s_add_i32 s47, s47, 2
	s_add_u32 s16, s16, 0x100
	s_addc_u32 s17, s17, 0
	s_add_u32 s45, s45, 0x100
	s_addc_u32 s46, s46, 0
	s_cmp_gt_u32 s47, 29
	s_barrier
	s_cbranch_scc0 .LBB0_147
	v_lshl_add_u32 v144, s0, 8, v160
	v_ashrrev_i32_e32 v145, 31, v144
	v_lshl_add_u64 v[150:151], v[144:145], 2, s[92:93]
	global_load_dword v176, v[150:151], off
	global_load_dword v177, v[150:151], off offset:64
	global_load_dword v178, v[150:151], off offset:128
	global_load_dword v179, v[150:151], off offset:192
	global_load_dword v180, v[150:151], off offset:512
	global_load_dword v181, v[150:151], off offset:576
	global_load_dword v182, v[150:151], off offset:640
	global_load_dword v183, v[150:151], off offset:704
	v_lshl_or_b32 v148, s40, 8, v164
	v_mov_b64_e32 v[146:147], s[96:97]
	v_ashrrev_i32_e32 v149, 31, v148
	v_mad_i64_i32 v[172:173], s[16:17], v144, s39, v[146:147]
	v_lshlrev_b64 v[148:149], 1, v[148:149]
	v_lshl_add_u64 v[172:173], v[172:173], 0, v[148:149]
	s_and_b64 vcc, exec, s[4:5]
	s_mov_b32 s40, s8
	s_mov_b32 s0, s10
	s_mov_b64 s[18:19], s[14:15]
	s_waitcnt vmcnt(0)
	v_fmamk_f32 v145, v176, 0x3a000000, v168
	v_rsq_f32_e32 v170, v145
	s_nop 0
	v_pk_mul_f32 v[126:127], v[126:127], v[170:171] op_sel_hi:[1,0]
	v_pk_mul_f32 v[124:125], v[124:125], v[170:171] op_sel_hi:[1,0]
	v_pk_mul_f32 v[122:123], v[122:123], v[170:171] op_sel_hi:[1,0]
	v_pk_mul_f32 v[120:121], v[120:121], v[170:171] op_sel_hi:[1,0]
	v_pk_mul_f32 v[118:119], v[118:119], v[170:171] op_sel_hi:[1,0]
	v_pk_mul_f32 v[116:117], v[116:117], v[170:171] op_sel_hi:[1,0]
	v_pk_mul_f32 v[174:175], v[114:115], v[170:171] op_sel_hi:[1,0]
	v_pk_mul_f32 v[170:171], v[112:113], v[170:171] op_sel_hi:[1,0]
	v_cvt_pk_bf16_f32 v112, v124, v125
	v_cvt_pk_bf16_f32 v113, v126, v127
	v_cvt_pk_bf16_f32 v114, v120, v121
	v_cvt_pk_bf16_f32 v115, v122, v123
	global_store_dwordx4 v[172:173], v[112:115], off
	s_nop 1
	v_cvt_pk_bf16_f32 v112, v116, v117
	v_cvt_pk_bf16_f32 v113, v118, v119
	v_cvt_pk_bf16_f32 v114, v170, v171
	v_cvt_pk_bf16_f32 v115, v174, v175
	global_store_dwordx4 v[172:173], v[112:115], off offset:256
	s_nop 0
	s_nop 0
	v_or_b32_e32 v113, 16, v144
	v_mad_i64_i32 v[114:115], s[16:17], v113, s39, v[146:147]
	v_lshl_add_u64 v[114:115], v[114:115], 0, v[148:149]
	s_nop 0
	v_fmamk_f32 v112, v177, 0x3a000000, v168
	v_rsq_f32_e32 v112, v112
	s_nop 0
	v_pk_mul_f32 v[110:111], v[110:111], v[112:113] op_sel_hi:[1,0]
	v_pk_mul_f32 v[108:109], v[108:109], v[112:113] op_sel_hi:[1,0]
	v_pk_mul_f32 v[106:107], v[106:107], v[112:113] op_sel_hi:[1,0]
	v_pk_mul_f32 v[104:105], v[104:105], v[112:113] op_sel_hi:[1,0]
	v_pk_mul_f32 v[102:103], v[102:103], v[112:113] op_sel_hi:[1,0]
	v_pk_mul_f32 v[100:101], v[100:101], v[112:113] op_sel_hi:[1,0]
	v_pk_mul_f32 v[116:117], v[98:99], v[112:113] op_sel_hi:[1,0]
	v_pk_mul_f32 v[112:113], v[96:97], v[112:113] op_sel_hi:[1,0]
	v_cvt_pk_bf16_f32 v96, v108, v109
	v_cvt_pk_bf16_f32 v97, v110, v111
	v_cvt_pk_bf16_f32 v98, v104, v105
	v_cvt_pk_bf16_f32 v99, v106, v107
	global_store_dwordx4 v[114:115], v[96:99], off
	s_nop 1
	v_cvt_pk_bf16_f32 v96, v100, v101
	v_cvt_pk_bf16_f32 v97, v102, v103
	v_cvt_pk_bf16_f32 v98, v112, v113
	v_cvt_pk_bf16_f32 v99, v116, v117
	global_store_dwordx4 v[114:115], v[96:99], off offset:256
	s_nop 0
	s_nop 0
	v_or_b32_e32 v97, 32, v144
	v_mad_i64_i32 v[98:99], s[16:17], v97, s39, v[146:147]
	v_lshl_add_u64 v[98:99], v[98:99], 0, v[148:149]
	s_nop 0
	v_fmamk_f32 v96, v178, 0x3a000000, v168
	v_rsq_f32_e32 v96, v96
	s_nop 0
	v_pk_mul_f32 v[94:95], v[94:95], v[96:97] op_sel_hi:[1,0]
	v_pk_mul_f32 v[92:93], v[92:93], v[96:97] op_sel_hi:[1,0]
	v_pk_mul_f32 v[90:91], v[90:91], v[96:97] op_sel_hi:[1,0]
	v_pk_mul_f32 v[88:89], v[88:89], v[96:97] op_sel_hi:[1,0]
	v_pk_mul_f32 v[86:87], v[86:87], v[96:97] op_sel_hi:[1,0]
	v_pk_mul_f32 v[84:85], v[84:85], v[96:97] op_sel_hi:[1,0]
	v_pk_mul_f32 v[100:101], v[82:83], v[96:97] op_sel_hi:[1,0]
	v_pk_mul_f32 v[96:97], v[80:81], v[96:97] op_sel_hi:[1,0]
	v_cvt_pk_bf16_f32 v80, v92, v93
	v_cvt_pk_bf16_f32 v81, v94, v95
	v_cvt_pk_bf16_f32 v82, v88, v89
	v_cvt_pk_bf16_f32 v83, v90, v91
	global_store_dwordx4 v[98:99], v[80:83], off
	s_nop 1
	v_cvt_pk_bf16_f32 v80, v84, v85
	v_cvt_pk_bf16_f32 v81, v86, v87
	v_cvt_pk_bf16_f32 v82, v96, v97
	v_cvt_pk_bf16_f32 v83, v100, v101
	global_store_dwordx4 v[98:99], v[80:83], off offset:256
	s_nop 0
	s_nop 0
	v_or_b32_e32 v81, 48, v144
	v_mad_i64_i32 v[82:83], s[16:17], v81, s39, v[146:147]
	v_lshl_add_u64 v[82:83], v[82:83], 0, v[148:149]
	s_nop 0
	v_fmamk_f32 v80, v179, 0x3a000000, v168
	v_rsq_f32_e32 v80, v80
	s_nop 0
	v_pk_mul_f32 v[78:79], v[78:79], v[80:81] op_sel_hi:[1,0]
	v_pk_mul_f32 v[76:77], v[76:77], v[80:81] op_sel_hi:[1,0]
	v_pk_mul_f32 v[74:75], v[74:75], v[80:81] op_sel_hi:[1,0]
	v_pk_mul_f32 v[72:73], v[72:73], v[80:81] op_sel_hi:[1,0]
	v_pk_mul_f32 v[70:71], v[70:71], v[80:81] op_sel_hi:[1,0]
	v_pk_mul_f32 v[68:69], v[68:69], v[80:81] op_sel_hi:[1,0]
	v_pk_mul_f32 v[84:85], v[66:67], v[80:81] op_sel_hi:[1,0]
	v_pk_mul_f32 v[80:81], v[64:65], v[80:81] op_sel_hi:[1,0]
	v_cvt_pk_bf16_f32 v64, v76, v77
	v_cvt_pk_bf16_f32 v65, v78, v79
	v_cvt_pk_bf16_f32 v66, v72, v73
	v_cvt_pk_bf16_f32 v67, v74, v75
	global_store_dwordx4 v[82:83], v[64:67], off
	s_nop 1
	v_cvt_pk_bf16_f32 v64, v68, v69
	v_cvt_pk_bf16_f32 v65, v70, v71
	v_cvt_pk_bf16_f32 v66, v80, v81
	v_cvt_pk_bf16_f32 v67, v84, v85
	global_store_dwordx4 v[82:83], v[64:67], off offset:256
	s_nop 0
	s_nop 0
	v_add_u32_e32 v65, 0x80, v144
	v_mad_i64_i32 v[66:67], s[16:17], v65, s39, v[146:147]
	v_lshl_add_u64 v[66:67], v[66:67], 0, v[148:149]
	s_nop 0
	v_fmamk_f32 v64, v180, 0x3a000000, v168
	v_rsq_f32_e32 v64, v64
	s_nop 0
	v_pk_mul_f32 v[62:63], v[62:63], v[64:65] op_sel_hi:[1,0]
	v_pk_mul_f32 v[60:61], v[60:61], v[64:65] op_sel_hi:[1,0]
	v_pk_mul_f32 v[58:59], v[58:59], v[64:65] op_sel_hi:[1,0]
	v_pk_mul_f32 v[56:57], v[56:57], v[64:65] op_sel_hi:[1,0]
	v_pk_mul_f32 v[54:55], v[54:55], v[64:65] op_sel_hi:[1,0]
	v_pk_mul_f32 v[52:53], v[52:53], v[64:65] op_sel_hi:[1,0]
	v_pk_mul_f32 v[68:69], v[50:51], v[64:65] op_sel_hi:[1,0]
	v_pk_mul_f32 v[64:65], v[48:49], v[64:65] op_sel_hi:[1,0]
	v_cvt_pk_bf16_f32 v48, v60, v61
	v_cvt_pk_bf16_f32 v49, v62, v63
	v_cvt_pk_bf16_f32 v50, v56, v57
	v_cvt_pk_bf16_f32 v51, v58, v59
	global_store_dwordx4 v[66:67], v[48:51], off
	s_nop 1
	v_cvt_pk_bf16_f32 v48, v52, v53
	v_cvt_pk_bf16_f32 v49, v54, v55
	v_cvt_pk_bf16_f32 v50, v64, v65
	v_cvt_pk_bf16_f32 v51, v68, v69
	global_store_dwordx4 v[66:67], v[48:51], off offset:256
	s_nop 0
	s_nop 0
	v_add_u32_e32 v49, 0x90, v144
	v_mad_i64_i32 v[50:51], s[16:17], v49, s39, v[146:147]
	v_lshl_add_u64 v[50:51], v[50:51], 0, v[148:149]
	s_nop 0
	v_fmamk_f32 v48, v181, 0x3a000000, v168
	v_rsq_f32_e32 v48, v48
	s_nop 0
	v_pk_mul_f32 v[46:47], v[46:47], v[48:49] op_sel_hi:[1,0]
	v_pk_mul_f32 v[44:45], v[44:45], v[48:49] op_sel_hi:[1,0]
	v_pk_mul_f32 v[42:43], v[42:43], v[48:49] op_sel_hi:[1,0]
	v_pk_mul_f32 v[40:41], v[40:41], v[48:49] op_sel_hi:[1,0]
	v_pk_mul_f32 v[38:39], v[38:39], v[48:49] op_sel_hi:[1,0]
	v_pk_mul_f32 v[36:37], v[36:37], v[48:49] op_sel_hi:[1,0]
	v_pk_mul_f32 v[52:53], v[34:35], v[48:49] op_sel_hi:[1,0]
	v_pk_mul_f32 v[48:49], v[32:33], v[48:49] op_sel_hi:[1,0]
	v_cvt_pk_bf16_f32 v32, v44, v45
	v_cvt_pk_bf16_f32 v33, v46, v47
	v_cvt_pk_bf16_f32 v34, v40, v41
	v_cvt_pk_bf16_f32 v35, v42, v43
	global_store_dwordx4 v[50:51], v[32:35], off
	s_nop 1
	v_cvt_pk_bf16_f32 v32, v36, v37
	v_cvt_pk_bf16_f32 v33, v38, v39
	v_cvt_pk_bf16_f32 v34, v48, v49
	v_cvt_pk_bf16_f32 v35, v52, v53
	global_store_dwordx4 v[50:51], v[32:35], off offset:256
	s_nop 0
	s_nop 0
	v_add_u32_e32 v33, 0xa0, v144
	v_mad_i64_i32 v[34:35], s[16:17], v33, s39, v[146:147]
	v_lshl_add_u64 v[34:35], v[34:35], 0, v[148:149]
	s_mov_b64 s[16:17], s[12:13]
	s_nop 0
	v_fmamk_f32 v32, v182, 0x3a000000, v168
	v_rsq_f32_e32 v32, v32
	s_nop 0
	v_pk_mul_f32 v[30:31], v[30:31], v[32:33] op_sel_hi:[1,0]
	v_pk_mul_f32 v[28:29], v[28:29], v[32:33] op_sel_hi:[1,0]
	v_pk_mul_f32 v[26:27], v[26:27], v[32:33] op_sel_hi:[1,0]
	v_pk_mul_f32 v[24:25], v[24:25], v[32:33] op_sel_hi:[1,0]
	v_pk_mul_f32 v[22:23], v[22:23], v[32:33] op_sel_hi:[1,0]
	v_pk_mul_f32 v[20:21], v[20:21], v[32:33] op_sel_hi:[1,0]
	v_pk_mul_f32 v[36:37], v[18:19], v[32:33] op_sel_hi:[1,0]
	v_pk_mul_f32 v[32:33], v[16:17], v[32:33] op_sel_hi:[1,0]
	v_cvt_pk_bf16_f32 v16, v28, v29
	v_cvt_pk_bf16_f32 v17, v30, v31
	v_cvt_pk_bf16_f32 v18, v24, v25
	v_cvt_pk_bf16_f32 v19, v26, v27
	global_store_dwordx4 v[34:35], v[16:19], off
	s_nop 1
	v_cvt_pk_bf16_f32 v16, v20, v21
	v_cvt_pk_bf16_f32 v17, v22, v23
	v_cvt_pk_bf16_f32 v18, v32, v33
	v_cvt_pk_bf16_f32 v19, v36, v37
	global_store_dwordx4 v[34:35], v[16:19], off offset:256
	s_nop 0
	s_nop 0
	v_add_u32_e32 v17, 0xb0, v144
	v_mad_i64_i32 v[18:19], s[4:5], v17, s39, v[146:147]
	v_lshl_add_u64 v[18:19], v[18:19], 0, v[148:149]
	s_nop 0
	v_fmamk_f32 v16, v183, 0x3a000000, v168
	v_rsq_f32_e32 v16, v16
	s_nop 0
	v_pk_mul_f32 v[14:15], v[14:15], v[16:17] op_sel_hi:[1,0]
	v_pk_mul_f32 v[12:13], v[12:13], v[16:17] op_sel_hi:[1,0]
	v_pk_mul_f32 v[10:11], v[10:11], v[16:17] op_sel_hi:[1,0]
	v_pk_mul_f32 v[8:9], v[8:9], v[16:17] op_sel_hi:[1,0]
	v_pk_mul_f32 v[6:7], v[6:7], v[16:17] op_sel_hi:[1,0]
	v_pk_mul_f32 v[4:5], v[4:5], v[16:17] op_sel_hi:[1,0]
	v_pk_mul_f32 v[20:21], v[2:3], v[16:17] op_sel_hi:[1,0]
	v_pk_mul_f32 v[16:17], v[0:1], v[16:17] op_sel_hi:[1,0]
	v_cvt_pk_bf16_f32 v0, v12, v13
	v_cvt_pk_bf16_f32 v1, v14, v15
	v_cvt_pk_bf16_f32 v2, v8, v9
	v_cvt_pk_bf16_f32 v3, v10, v11
	global_store_dwordx4 v[18:19], v[0:3], off
	s_nop 1
	v_cvt_pk_bf16_f32 v0, v4, v5
	v_cvt_pk_bf16_f32 v1, v6, v7
	v_cvt_pk_bf16_f32 v2, v16, v17
	v_cvt_pk_bf16_f32 v3, v20, v21
	global_store_dwordx4 v[18:19], v[0:3], off offset:256
	s_cbranch_vccz .LBB0_144
	s_waitcnt vmcnt(0)
	s_cmpk_gt_u32 s3, 0xff
	s_cbranch_scc1 .LBB0_151
	s_barrier

.LBB0_283:
	ds_read_b128 v[140:143], v146
	v_xor_b32_e32 v171, 64, v146
	ds_read_b128 v[154:157], v171
	ds_read_b128 v[158:161], v146 offset:2048
	ds_read_b128 v[168:171], v171 offset:2048
	s_add_u32 s18, s6, 0xffe80080
	s_addc_u32 s19, s7, -1
	s_cmp_eq_u32 s45, 28
	s_cselect_b32 s21, s15, s19
	s_cselect_b32 s20, s14, s18
	s_cselect_b32 s19, s1, s44
	s_cselect_b32 s18, s11, s43
	v_lshl_add_u64 v[150:151], s[6:7], 0, v[132:133]
	s_add_i32 m0, s25, 0xc000
	ds_read_b128 v[172:175], v147
	v_xor_b32_e32 v203, 64, v147
	ds_read_b128 v[176:179], v203
	ds_read_b128 v[180:183], v147 offset:2048
	ds_read_b128 v[184:187], v203 offset:2048
	ds_read_b128 v[188:191], v147 offset:4096
	ds_read_b128 v[192:195], v203 offset:4096
	ds_read_b128 v[196:199], v147 offset:6144
	ds_read_b128 v[200:203], v203 offset:6144
	global_load_lds_dwordx4 v[150:151], off
	v_lshl_add_u64 v[150:151], s[6:7], 0, v[134:135]
	s_add_i32 m0, s25, 0xe000
	s_nop 0
	global_load_lds_dwordx4 v[150:151], off
	s_waitcnt lgkmcnt(8)
	s_barrier
	s_waitcnt lgkmcnt(0)
	s_setprio 1
	s_waitcnt lgkmcnt(0)
	v_mfma_f32_16x16x32_bf16 v[124:127], v[140:143], v[172:175], v[124:127]
	v_mfma_f32_16x16x32_bf16 v[124:127], v[154:157], v[176:179], v[124:127]
	v_mfma_f32_16x16x32_bf16 v[120:123], v[168:171], v[176:179], v[120:123]
	v_mfma_f32_16x16x32_bf16 v[120:123], v[158:161], v[172:175], v[120:123]
	v_mfma_f32_16x16x32_bf16 v[104:107], v[158:161], v[180:183], v[104:107]
	v_mfma_f32_16x16x32_bf16 v[104:107], v[168:171], v[184:187], v[104:107]
	v_mfma_f32_16x16x32_bf16 v[108:111], v[154:157], v[184:187], v[108:111]
	v_mfma_f32_16x16x32_bf16 v[108:111], v[140:143], v[180:183], v[108:111]
	v_mfma_f32_16x16x32_bf16 v[92:95], v[140:143], v[188:191], v[92:95]
	v_mfma_f32_16x16x32_bf16 v[92:95], v[154:157], v[192:195], v[92:95]
	v_mfma_f32_16x16x32_bf16 v[88:91], v[168:171], v[192:195], v[88:91]
	v_mfma_f32_16x16x32_bf16 v[88:91], v[158:161], v[188:191], v[88:91]
	v_mfma_f32_16x16x32_bf16 v[72:75], v[158:161], v[196:199], v[72:75]
	v_mfma_f32_16x16x32_bf16 v[72:75], v[168:171], v[200:203], v[72:75]
	v_mfma_f32_16x16x32_bf16 v[76:79], v[154:157], v[200:203], v[76:79]
	v_mfma_f32_16x16x32_bf16 v[76:79], v[140:143], v[196:199], v[76:79]
	s_setprio 0
	s_barrier
	s_add_i32 s46, s39, s24
	v_lshl_add_u64 v[150:151], s[18:19], 0, v[164:165]
	s_mov_b32 m0, s46
	ds_read_b128 v[204:207], v148
	v_xor_b32_e32 v245, 64, v148
	ds_read_b128 v[208:211], v245
	ds_read_b128 v[212:215], v148 offset:2048
	ds_read_b128 v[242:245], v245 offset:2048
	global_load_lds_dwordx4 v[150:151], off
	v_lshl_add_u64 v[216:217], s[18:19], 0, v[166:167]
	s_add_i32 m0, s46, 0x2000
	s_nop 0
	global_load_lds_dwordx4 v[216:217], off
	s_barrier
	s_waitcnt lgkmcnt(0)
	s_setprio 1
	s_waitcnt lgkmcnt(0)
	v_mfma_f32_16x16x32_bf16 v[116:119], v[204:207], v[172:175], v[116:119]
	v_mfma_f32_16x16x32_bf16 v[116:119], v[208:211], v[176:179], v[116:119]
	v_mfma_f32_16x16x32_bf16 v[112:115], v[242:245], v[176:179], v[112:115]
	v_mfma_f32_16x16x32_bf16 v[112:115], v[212:215], v[172:175], v[112:115]
	v_mfma_f32_16x16x32_bf16 v[96:99], v[212:215], v[180:183], v[96:99]
	v_mfma_f32_16x16x32_bf16 v[96:99], v[242:245], v[184:187], v[96:99]
	v_mfma_f32_16x16x32_bf16 v[100:103], v[208:211], v[184:187], v[100:103]
	v_mfma_f32_16x16x32_bf16 v[100:103], v[204:207], v[180:183], v[100:103]
	v_mfma_f32_16x16x32_bf16 v[84:87], v[204:207], v[188:191], v[84:87]
	v_mfma_f32_16x16x32_bf16 v[84:87], v[208:211], v[192:195], v[84:87]
	v_mfma_f32_16x16x32_bf16 v[80:83], v[242:245], v[192:195], v[80:83]
	v_mfma_f32_16x16x32_bf16 v[80:83], v[212:215], v[188:191], v[80:83]
	v_mfma_f32_16x16x32_bf16 v[64:67], v[212:215], v[196:199], v[64:67]
	v_mfma_f32_16x16x32_bf16 v[64:67], v[242:245], v[200:203], v[64:67]
	v_mfma_f32_16x16x32_bf16 v[68:71], v[208:211], v[200:203], v[68:71]
	v_mfma_f32_16x16x32_bf16 v[68:71], v[204:207], v[196:199], v[68:71]
	s_setprio 0
	s_mov_b32 m0, s25
	v_lshl_add_u64 v[220:221], s[20:21], 0, v[128:129]
	s_barrier
	ds_read_b128 v[172:175], v147 offset:16384
	v_xor_b32_e32 v203, 64, v147
	ds_read_b128 v[176:179], v203 offset:16384
	ds_read_b128 v[180:183], v147 offset:18432
	ds_read_b128 v[184:187], v203 offset:18432
	ds_read_b128 v[188:191], v147 offset:20480
	ds_read_b128 v[192:195], v203 offset:20480
	ds_read_b128 v[196:199], v147 offset:22528
	ds_read_b128 v[200:203], v203 offset:22528
	global_load_lds_dwordx4 v[220:221], off
	v_lshl_add_u64 v[230:231], s[20:21], 0, v[130:131]
	s_mov_b32 m0, s26
	s_nop 0
	global_load_lds_dwordx4 v[230:231], off
	s_barrier
	s_waitcnt lgkmcnt(0)
	s_setprio 1
	s_waitcnt lgkmcnt(0)
	v_mfma_f32_16x16x32_bf16 v[60:63], v[140:143], v[172:175], v[60:63]
	v_mfma_f32_16x16x32_bf16 v[60:63], v[154:157], v[176:179], v[60:63]
	v_mfma_f32_16x16x32_bf16 v[56:59], v[168:171], v[176:179], v[56:59]
	v_mfma_f32_16x16x32_bf16 v[56:59], v[158:161], v[172:175], v[56:59]
	v_mfma_f32_16x16x32_bf16 v[40:43], v[158:161], v[180:183], v[40:43]
	v_mfma_f32_16x16x32_bf16 v[40:43], v[168:171], v[184:187], v[40:43]
	v_mfma_f32_16x16x32_bf16 v[44:47], v[154:157], v[184:187], v[44:47]
	v_mfma_f32_16x16x32_bf16 v[44:47], v[140:143], v[180:183], v[44:47]
	v_mfma_f32_16x16x32_bf16 v[28:31], v[140:143], v[188:191], v[28:31]
	v_mfma_f32_16x16x32_bf16 v[28:31], v[154:157], v[192:195], v[28:31]
	v_mfma_f32_16x16x32_bf16 v[24:27], v[168:171], v[192:195], v[24:27]
	v_mfma_f32_16x16x32_bf16 v[24:27], v[158:161], v[188:191], v[24:27]
	v_mfma_f32_16x16x32_bf16 v[8:11], v[158:161], v[196:199], v[8:11]
	v_mfma_f32_16x16x32_bf16 v[8:11], v[168:171], v[200:203], v[8:11]
	v_mfma_f32_16x16x32_bf16 v[12:15], v[154:157], v[200:203], v[12:15]
	v_mfma_f32_16x16x32_bf16 v[12:15], v[140:143], v[196:199], v[12:15]
	s_setprio 0
	s_barrier
	s_add_u32 s46, s18, 0x80000
	s_addc_u32 s47, s19, 0
	s_add_i32 s48, s40, s24
	v_lshl_add_u64 v[140:141], s[46:47], 0, v[164:165]
	s_mov_b32 m0, s48
	s_nop 0
	global_load_lds_dwordx4 v[140:141], off
	v_lshl_add_u64 v[140:141], s[46:47], 0, v[166:167]
	s_add_i32 m0, s48, 0x2000
	s_nop 0
	global_load_lds_dwordx4 v[140:141], off
	s_waitcnt vmcnt(6)
	s_barrier
	s_setprio 1
	v_mfma_f32_16x16x32_bf16 v[52:55], v[204:207], v[172:175], v[52:55]
	v_mfma_f32_16x16x32_bf16 v[52:55], v[208:211], v[176:179], v[52:55]
	v_mfma_f32_16x16x32_bf16 v[48:51], v[242:245], v[176:179], v[48:51]
	v_mfma_f32_16x16x32_bf16 v[48:51], v[212:215], v[172:175], v[48:51]
	v_mfma_f32_16x16x32_bf16 v[32:35], v[212:215], v[180:183], v[32:35]
	v_mfma_f32_16x16x32_bf16 v[32:35], v[242:245], v[184:187], v[32:35]
	v_mfma_f32_16x16x32_bf16 v[36:39], v[208:211], v[184:187], v[36:39]
	v_mfma_f32_16x16x32_bf16 v[36:39], v[204:207], v[180:183], v[36:39]
	v_mfma_f32_16x16x32_bf16 v[20:23], v[204:207], v[188:191], v[20:23]
	v_mfma_f32_16x16x32_bf16 v[20:23], v[208:211], v[192:195], v[20:23]
	v_mfma_f32_16x16x32_bf16 v[16:19], v[242:245], v[192:195], v[16:19]
	v_mfma_f32_16x16x32_bf16 v[16:19], v[212:215], v[188:191], v[16:19]
	v_mfma_f32_16x16x32_bf16 v[0:3], v[212:215], v[196:199], v[0:3]
	v_mfma_f32_16x16x32_bf16 v[0:3], v[242:245], v[200:203], v[0:3]
	v_mfma_f32_16x16x32_bf16 v[4:7], v[208:211], v[200:203], v[4:7]
	v_mfma_f32_16x16x32_bf16 v[4:7], v[204:207], v[196:199], v[4:7]
	s_setprio 0
	s_add_i32 s46, 0, 0x18000
	v_add_u32_e32 v168, s46, v145
	s_barrier
	ds_read_b128 v[140:143], v168
	v_xor_b32_e32 v171, 64, v168
	ds_read_b128 v[154:157], v171
	ds_read_b128 v[158:161], v168 offset:2048
	ds_read_b128 v[168:171], v171 offset:2048
	s_add_u32 s20, s20, 0x180000
	s_addc_u32 s21, s21, 0
	s_mov_b32 m0, s27
	v_lshl_add_u64 v[204:205], s[20:21], 0, v[128:129]
	ds_read_b128 v[172:175], v147 offset:32768
	v_xor_b32_e32 v203, 64, v147
	ds_read_b128 v[176:179], v203 offset:32768
	ds_read_b128 v[180:183], v147 offset:34816
	ds_read_b128 v[184:187], v203 offset:34816
	ds_read_b128 v[188:191], v147 offset:36864
	ds_read_b128 v[192:195], v203 offset:36864
	ds_read_b128 v[196:199], v147 offset:38912
	ds_read_b128 v[200:203], v203 offset:38912
	global_load_lds_dwordx4 v[204:205], off
	v_lshl_add_u64 v[204:205], s[20:21], 0, v[130:131]
	s_mov_b32 m0, s28
	s_nop 0
	global_load_lds_dwordx4 v[204:205], off
	s_waitcnt lgkmcnt(8)
	s_barrier
	s_waitcnt lgkmcnt(0)
	s_setprio 1
	s_waitcnt lgkmcnt(0)
	v_mfma_f32_16x16x32_bf16 v[124:127], v[140:143], v[172:175], v[124:127]
	v_mfma_f32_16x16x32_bf16 v[124:127], v[154:157], v[176:179], v[124:127]
	v_mfma_f32_16x16x32_bf16 v[120:123], v[168:171], v[176:179], v[120:123]
	v_mfma_f32_16x16x32_bf16 v[120:123], v[158:161], v[172:175], v[120:123]
	v_mfma_f32_16x16x32_bf16 v[104:107], v[158:161], v[180:183], v[104:107]
	v_mfma_f32_16x16x32_bf16 v[104:107], v[168:171], v[184:187], v[104:107]
	v_mfma_f32_16x16x32_bf16 v[108:111], v[154:157], v[184:187], v[108:111]
	v_mfma_f32_16x16x32_bf16 v[108:111], v[140:143], v[180:183], v[108:111]
	v_mfma_f32_16x16x32_bf16 v[92:95], v[140:143], v[188:191], v[92:95]
	v_mfma_f32_16x16x32_bf16 v[92:95], v[154:157], v[192:195], v[92:95]
	v_mfma_f32_16x16x32_bf16 v[88:91], v[168:171], v[192:195], v[88:91]
	v_mfma_f32_16x16x32_bf16 v[88:91], v[158:161], v[188:191], v[88:91]
	v_mfma_f32_16x16x32_bf16 v[72:75], v[158:161], v[196:199], v[72:75]
	v_mfma_f32_16x16x32_bf16 v[72:75], v[168:171], v[200:203], v[72:75]
	v_mfma_f32_16x16x32_bf16 v[76:79], v[154:157], v[200:203], v[76:79]
	v_mfma_f32_16x16x32_bf16 v[76:79], v[140:143], v[196:199], v[76:79]
	s_setprio 0
	s_barrier
	s_add_i32 s20, 0, 0x1c000
	s_add_i32 s21, s46, s24
	v_add_u32_e32 v223, s20, v145
	v_lshl_add_u64 v[150:151], v[150:151], 0, s[8:9]
	s_mov_b32 m0, s21
	ds_read_b128 v[204:207], v223
	v_xor_b32_e32 v245, 64, v223
	ds_read_b128 v[208:211], v245
	ds_read_b128 v[212:215], v223 offset:2048
	ds_read_b128 v[242:245], v245 offset:2048
	global_load_lds_dwordx4 v[150:151], off
	v_lshl_add_u64 v[150:151], v[216:217], 0, s[8:9]
	s_add_i32 m0, s21, 0x2000
	s_nop 0
	global_load_lds_dwordx4 v[150:151], off
	s_barrier
	s_waitcnt lgkmcnt(0)
	s_setprio 1
	s_waitcnt lgkmcnt(0)
	v_mfma_f32_16x16x32_bf16 v[116:119], v[204:207], v[172:175], v[116:119]
	v_mfma_f32_16x16x32_bf16 v[116:119], v[208:211], v[176:179], v[116:119]
	v_mfma_f32_16x16x32_bf16 v[112:115], v[242:245], v[176:179], v[112:115]
	v_mfma_f32_16x16x32_bf16 v[112:115], v[212:215], v[172:175], v[112:115]
	v_mfma_f32_16x16x32_bf16 v[96:99], v[212:215], v[180:183], v[96:99]
	v_mfma_f32_16x16x32_bf16 v[96:99], v[242:245], v[184:187], v[96:99]
	v_mfma_f32_16x16x32_bf16 v[100:103], v[208:211], v[184:187], v[100:103]
	v_mfma_f32_16x16x32_bf16 v[100:103], v[204:207], v[180:183], v[100:103]
	v_mfma_f32_16x16x32_bf16 v[84:87], v[204:207], v[188:191], v[84:87]
	v_mfma_f32_16x16x32_bf16 v[84:87], v[208:211], v[192:195], v[84:87]
	v_mfma_f32_16x16x32_bf16 v[80:83], v[242:245], v[192:195], v[80:83]
	v_mfma_f32_16x16x32_bf16 v[80:83], v[212:215], v[188:191], v[80:83]
	v_mfma_f32_16x16x32_bf16 v[64:67], v[212:215], v[196:199], v[64:67]
	v_mfma_f32_16x16x32_bf16 v[64:67], v[242:245], v[200:203], v[64:67]
	v_mfma_f32_16x16x32_bf16 v[68:71], v[208:211], v[200:203], v[68:71]
	v_mfma_f32_16x16x32_bf16 v[68:71], v[204:207], v[196:199], v[68:71]
	s_setprio 0
	s_mov_b32 m0, s33
	v_lshl_add_u64 v[150:151], v[220:221], 0, s[8:9]
	s_barrier
	ds_read_b128 v[172:175], v147 offset:49152
	v_xor_b32_e32 v203, 64, v147
	ds_read_b128 v[176:179], v203 offset:49152
	ds_read_b128 v[180:183], v147 offset:51200
	ds_read_b128 v[184:187], v203 offset:51200
	ds_read_b128 v[188:191], v147 offset:53248
	ds_read_b128 v[192:195], v203 offset:53248
	ds_read_b128 v[196:199], v147 offset:55296
	ds_read_b128 v[200:203], v203 offset:55296
	global_load_lds_dwordx4 v[150:151], off
	v_lshl_add_u64 v[150:151], v[230:231], 0, s[8:9]
	s_mov_b32 m0, s34
	s_nop 0
	global_load_lds_dwordx4 v[150:151], off
	s_barrier
	s_waitcnt lgkmcnt(0)
	s_setprio 1
	s_waitcnt lgkmcnt(0)
	v_mfma_f32_16x16x32_bf16 v[60:63], v[140:143], v[172:175], v[60:63]
	v_mfma_f32_16x16x32_bf16 v[60:63], v[154:157], v[176:179], v[60:63]
	v_mfma_f32_16x16x32_bf16 v[56:59], v[168:171], v[176:179], v[56:59]
	v_mfma_f32_16x16x32_bf16 v[56:59], v[158:161], v[172:175], v[56:59]
	v_mfma_f32_16x16x32_bf16 v[40:43], v[158:161], v[180:183], v[40:43]
	v_mfma_f32_16x16x32_bf16 v[40:43], v[168:171], v[184:187], v[40:43]
	v_mfma_f32_16x16x32_bf16 v[44:47], v[154:157], v[184:187], v[44:47]
	v_mfma_f32_16x16x32_bf16 v[44:47], v[140:143], v[180:183], v[44:47]
	v_mfma_f32_16x16x32_bf16 v[28:31], v[140:143], v[188:191], v[28:31]
	v_mfma_f32_16x16x32_bf16 v[28:31], v[154:157], v[192:195], v[28:31]
	v_mfma_f32_16x16x32_bf16 v[24:27], v[168:171], v[192:195], v[24:27]
	v_mfma_f32_16x16x32_bf16 v[24:27], v[158:161], v[188:191], v[24:27]
	v_mfma_f32_16x16x32_bf16 v[8:11], v[158:161], v[196:199], v[8:11]
	v_mfma_f32_16x16x32_bf16 v[8:11], v[168:171], v[200:203], v[8:11]
	v_mfma_f32_16x16x32_bf16 v[12:15], v[154:157], v[200:203], v[12:15]
	v_mfma_f32_16x16x32_bf16 v[12:15], v[140:143], v[196:199], v[12:15]
	s_setprio 0
	s_barrier
	s_add_u32 s18, s18, 0x80080
	s_addc_u32 s19, s19, 0
	s_add_i32 s20, s20, s24
	v_lshl_add_u64 v[140:141], s[18:19], 0, v[164:165]
	s_mov_b32 m0, s20
	s_nop 0
	global_load_lds_dwordx4 v[140:141], off
	v_lshl_add_u64 v[140:141], s[18:19], 0, v[166:167]
	s_add_i32 m0, s20, 0x2000
	s_nop 0
	global_load_lds_dwordx4 v[140:141], off
	s_waitcnt vmcnt(6)
	s_barrier
	s_setprio 1
	v_mfma_f32_16x16x32_bf16 v[52:55], v[204:207], v[172:175], v[52:55]
	v_mfma_f32_16x16x32_bf16 v[52:55], v[208:211], v[176:179], v[52:55]
	v_mfma_f32_16x16x32_bf16 v[48:51], v[242:245], v[176:179], v[48:51]
	v_mfma_f32_16x16x32_bf16 v[48:51], v[212:215], v[172:175], v[48:51]
	v_mfma_f32_16x16x32_bf16 v[32:35], v[212:215], v[180:183], v[32:35]
	v_mfma_f32_16x16x32_bf16 v[32:35], v[242:245], v[184:187], v[32:35]
	v_mfma_f32_16x16x32_bf16 v[36:39], v[208:211], v[184:187], v[36:39]
	v_mfma_f32_16x16x32_bf16 v[36:39], v[204:207], v[180:183], v[36:39]
	v_mfma_f32_16x16x32_bf16 v[20:23], v[204:207], v[188:191], v[20:23]
	v_mfma_f32_16x16x32_bf16 v[20:23], v[208:211], v[192:195], v[20:23]
	v_mfma_f32_16x16x32_bf16 v[16:19], v[242:245], v[192:195], v[16:19]
	v_mfma_f32_16x16x32_bf16 v[16:19], v[212:215], v[188:191], v[16:19]
	v_mfma_f32_16x16x32_bf16 v[0:3], v[212:215], v[196:199], v[0:3]
	v_mfma_f32_16x16x32_bf16 v[0:3], v[242:245], v[200:203], v[0:3]
	v_mfma_f32_16x16x32_bf16 v[4:7], v[208:211], v[200:203], v[4:7]
	v_mfma_f32_16x16x32_bf16 v[4:7], v[204:207], v[196:199], v[4:7]
	s_setprio 0
	s_add_i32 s45, s45, 2
	s_add_u32 s6, s6, 0x100
	s_addc_u32 s7, s7, 0
	s_add_u32 s43, s43, 0x100
	s_addc_u32 s44, s44, 0
	s_cmp_gt_u32 s45, 29
	s_barrier
	s_cbranch_scc0 .LBB0_283
	v_lshl_add_u32 v217, s42, 8, v163
	v_add_u32_e32 v217, s30, v217
	v_lshlrev_b32_e32 v208, 2, v217
	v_lshl_add_u32 v214, v225, 3, s31
	v_lshl_add_u32 v214, s0, 8, v214
	v_lshl_add_u32 v209, v217, 11, v214
	v_lshlrev_b32_e32 v209, 1, v209
	v_lshlrev_b32_e32 v210, 1, v209
	v_lshl_add_u32 v217, v225, 4, v163
	v_xor_b32_e32 v215, 16, v217
	v_lshlrev_b32_e32 v215, 2, v215
	v_xor_b32_e32 v216, 32, v217
	v_lshlrev_b32_e32 v216, 2, v216
	v_add_u32_e32 v212, 0x0, v210
	global_load_dwordx4 v[176:179], v212, s[36:37]
	global_load_dwordx4 v[180:183], v212, s[36:37] offset:16
	global_load_dwordx4 v[184:187], v212, s[36:37] offset:512
	global_load_dwordx4 v[188:191], v212, s[36:37] offset:528
	v_add_u32_e32 v212, 0x20000, v210
	global_load_dwordx4 v[192:195], v212, s[36:37]
	global_load_dwordx4 v[196:199], v212, s[36:37] offset:16
	global_load_dwordx4 v[200:203], v212, s[36:37] offset:512
	global_load_dwordx4 v[204:207], v212, s[36:37] offset:528
	s_waitcnt vmcnt(4)
	v_pk_add_f32 v[124:125], v[124:125], v[176:177]
	v_pk_add_f32 v[126:127], v[126:127], v[178:179]
	v_pk_add_f32 v[120:121], v[120:121], v[180:181]
	v_pk_add_f32 v[122:123], v[122:123], v[182:183]
	v_mul_f32_e32 v213, v124, v124
	v_fmac_f32_e32 v213, v125, v125
	v_fmac_f32_e32 v213, v126, v126
	v_fmac_f32_e32 v213, v127, v127
	v_fmac_f32_e32 v213, v120, v120
	v_fmac_f32_e32 v213, v121, v121
	v_fmac_f32_e32 v213, v122, v122
	v_fmac_f32_e32 v213, v123, v123
	v_cvt_pk_bf16_f32 v176, v124, v125
	v_cvt_pk_bf16_f32 v177, v126, v127
	v_cvt_pk_bf16_f32 v178, v120, v121
	v_cvt_pk_bf16_f32 v179, v122, v123
	v_add_u32_e32 v217, 0x0, v209
	global_store_dwordx4 v217, v[176:179], s[80:81]
	v_pk_add_f32 v[116:117], v[116:117], v[184:185]
	v_pk_add_f32 v[118:119], v[118:119], v[186:187]
	v_pk_add_f32 v[112:113], v[112:113], v[188:189]
	v_pk_add_f32 v[114:115], v[114:115], v[190:191]
	v_fmac_f32_e32 v213, v116, v116
	v_fmac_f32_e32 v213, v117, v117
	v_fmac_f32_e32 v213, v118, v118
	v_fmac_f32_e32 v213, v119, v119
	v_fmac_f32_e32 v213, v112, v112
	v_fmac_f32_e32 v213, v113, v113
	v_fmac_f32_e32 v213, v114, v114
	v_fmac_f32_e32 v213, v115, v115
	v_cvt_pk_bf16_f32 v184, v116, v117
	v_cvt_pk_bf16_f32 v185, v118, v119
	v_cvt_pk_bf16_f32 v186, v112, v113
	v_cvt_pk_bf16_f32 v187, v114, v115
	global_store_dwordx4 v217, v[184:187], s[80:81] offset:256
	ds_bpermute_b32 v214, v215, v213
	s_waitcnt lgkmcnt(0)
	v_add_f32_e32 v213, v213, v214
	ds_bpermute_b32 v214, v216, v213
	s_waitcnt lgkmcnt(0)
	v_add_f32_e32 v213, v213, v214
	s_mov_b64 exec, 0xffff
	global_atomic_add_f32 v208, v213, s[12:13]
	s_mov_b64 exec, -1
	v_add_u32_e32 v212, 0x40000, v210
	global_load_dwordx4 v[176:179], v212, s[36:37]
	global_load_dwordx4 v[180:183], v212, s[36:37] offset:16
	global_load_dwordx4 v[184:187], v212, s[36:37] offset:512
	global_load_dwordx4 v[188:191], v212, s[36:37] offset:528
	s_waitcnt vmcnt(7)
	v_pk_add_f32 v[108:109], v[108:109], v[192:193]
	v_pk_add_f32 v[110:111], v[110:111], v[194:195]
	v_pk_add_f32 v[104:105], v[104:105], v[196:197]
	v_pk_add_f32 v[106:107], v[106:107], v[198:199]
	v_mul_f32_e32 v213, v108, v108
	v_fmac_f32_e32 v213, v109, v109
	v_fmac_f32_e32 v213, v110, v110
	v_fmac_f32_e32 v213, v111, v111
	v_fmac_f32_e32 v213, v104, v104
	v_fmac_f32_e32 v213, v105, v105
	v_fmac_f32_e32 v213, v106, v106
	v_fmac_f32_e32 v213, v107, v107
	v_cvt_pk_bf16_f32 v192, v108, v109
	v_cvt_pk_bf16_f32 v193, v110, v111
	v_cvt_pk_bf16_f32 v194, v104, v105
	v_cvt_pk_bf16_f32 v195, v106, v107
	v_add_u32_e32 v217, 0x10000, v209
	global_store_dwordx4 v217, v[192:195], s[80:81]
	v_pk_add_f32 v[100:101], v[100:101], v[200:201]
	v_pk_add_f32 v[102:103], v[102:103], v[202:203]
	v_pk_add_f32 v[96:97], v[96:97], v[204:205]
	v_pk_add_f32 v[98:99], v[98:99], v[206:207]
	v_fmac_f32_e32 v213, v100, v100
	v_fmac_f32_e32 v213, v101, v101
	v_fmac_f32_e32 v213, v102, v102
	v_fmac_f32_e32 v213, v103, v103
	v_fmac_f32_e32 v213, v96, v96
	v_fmac_f32_e32 v213, v97, v97
	v_fmac_f32_e32 v213, v98, v98
	v_fmac_f32_e32 v213, v99, v99
	v_cvt_pk_bf16_f32 v200, v100, v101
	v_cvt_pk_bf16_f32 v201, v102, v103
	v_cvt_pk_bf16_f32 v202, v96, v97
	v_cvt_pk_bf16_f32 v203, v98, v99
	global_store_dwordx4 v217, v[200:203], s[80:81] offset:256
	ds_bpermute_b32 v214, v215, v213
	s_waitcnt lgkmcnt(0)
	v_add_f32_e32 v213, v213, v214
	ds_bpermute_b32 v214, v216, v213
	s_waitcnt lgkmcnt(0)
	v_add_f32_e32 v213, v213, v214
	s_mov_b64 exec, 0xffff
	global_atomic_add_f32 v208, v213, s[12:13] offset:64
	s_mov_b64 exec, -1
	v_add_u32_e32 v212, 0x60000, v210
	global_load_dwordx4 v[192:195], v212, s[36:37]
	global_load_dwordx4 v[196:199], v212, s[36:37] offset:16
	global_load_dwordx4 v[200:203], v212, s[36:37] offset:512
	global_load_dwordx4 v[204:207], v212, s[36:37] offset:528
	s_waitcnt vmcnt(7)
	v_pk_add_f32 v[92:93], v[92:93], v[176:177]
	v_pk_add_f32 v[94:95], v[94:95], v[178:179]
	v_pk_add_f32 v[88:89], v[88:89], v[180:181]
	v_pk_add_f32 v[90:91], v[90:91], v[182:183]
	v_mul_f32_e32 v213, v92, v92
	v_fmac_f32_e32 v213, v93, v93
	v_fmac_f32_e32 v213, v94, v94
	v_fmac_f32_e32 v213, v95, v95
	v_fmac_f32_e32 v213, v88, v88
	v_fmac_f32_e32 v213, v89, v89
	v_fmac_f32_e32 v213, v90, v90
	v_fmac_f32_e32 v213, v91, v91
	v_cvt_pk_bf16_f32 v176, v92, v93
	v_cvt_pk_bf16_f32 v177, v94, v95
	v_cvt_pk_bf16_f32 v178, v88, v89
	v_cvt_pk_bf16_f32 v179, v90, v91
	v_add_u32_e32 v217, 0x20000, v209
	global_store_dwordx4 v217, v[176:179], s[80:81]
	v_pk_add_f32 v[84:85], v[84:85], v[184:185]
	v_pk_add_f32 v[86:87], v[86:87], v[186:187]
	v_pk_add_f32 v[80:81], v[80:81], v[188:189]
	v_pk_add_f32 v[82:83], v[82:83], v[190:191]
	v_fmac_f32_e32 v213, v84, v84
	v_fmac_f32_e32 v213, v85, v85
	v_fmac_f32_e32 v213, v86, v86
	v_fmac_f32_e32 v213, v87, v87
	v_fmac_f32_e32 v213, v80, v80
	v_fmac_f32_e32 v213, v81, v81
	v_fmac_f32_e32 v213, v82, v82
	v_fmac_f32_e32 v213, v83, v83
	v_cvt_pk_bf16_f32 v184, v84, v85
	v_cvt_pk_bf16_f32 v185, v86, v87
	v_cvt_pk_bf16_f32 v186, v80, v81
	v_cvt_pk_bf16_f32 v187, v82, v83
	global_store_dwordx4 v217, v[184:187], s[80:81] offset:256
	ds_bpermute_b32 v214, v215, v213
	s_waitcnt lgkmcnt(0)
	v_add_f32_e32 v213, v213, v214
	ds_bpermute_b32 v214, v216, v213
	s_waitcnt lgkmcnt(0)
	v_add_f32_e32 v213, v213, v214
	s_mov_b64 exec, 0xffff
	global_atomic_add_f32 v208, v213, s[12:13] offset:128
	s_mov_b64 exec, -1
	v_add_u32_e32 v212, 0x100000, v210
	global_load_dwordx4 v[176:179], v212, s[36:37]
	global_load_dwordx4 v[180:183], v212, s[36:37] offset:16
	global_load_dwordx4 v[184:187], v212, s[36:37] offset:512
	global_load_dwordx4 v[188:191], v212, s[36:37] offset:528
	s_waitcnt vmcnt(7)
	v_pk_add_f32 v[76:77], v[76:77], v[192:193]
	v_pk_add_f32 v[78:79], v[78:79], v[194:195]
	v_pk_add_f32 v[72:73], v[72:73], v[196:197]
	v_pk_add_f32 v[74:75], v[74:75], v[198:199]
	v_mul_f32_e32 v213, v76, v76
	v_fmac_f32_e32 v213, v77, v77
	v_fmac_f32_e32 v213, v78, v78
	v_fmac_f32_e32 v213, v79, v79
	v_fmac_f32_e32 v213, v72, v72
	v_fmac_f32_e32 v213, v73, v73
	v_fmac_f32_e32 v213, v74, v74
	v_fmac_f32_e32 v213, v75, v75
	v_cvt_pk_bf16_f32 v192, v76, v77
	v_cvt_pk_bf16_f32 v193, v78, v79
	v_cvt_pk_bf16_f32 v194, v72, v73
	v_cvt_pk_bf16_f32 v195, v74, v75
	v_add_u32_e32 v217, 0x30000, v209
	global_store_dwordx4 v217, v[192:195], s[80:81]
	v_pk_add_f32 v[68:69], v[68:69], v[200:201]
	v_pk_add_f32 v[70:71], v[70:71], v[202:203]
	v_pk_add_f32 v[64:65], v[64:65], v[204:205]
	v_pk_add_f32 v[66:67], v[66:67], v[206:207]
	v_fmac_f32_e32 v213, v68, v68
	v_fmac_f32_e32 v213, v69, v69
	v_fmac_f32_e32 v213, v70, v70
	v_fmac_f32_e32 v213, v71, v71
	v_fmac_f32_e32 v213, v64, v64
	v_fmac_f32_e32 v213, v65, v65
	v_fmac_f32_e32 v213, v66, v66
	v_fmac_f32_e32 v213, v67, v67
	v_cvt_pk_bf16_f32 v200, v68, v69
	v_cvt_pk_bf16_f32 v201, v70, v71
	v_cvt_pk_bf16_f32 v202, v64, v65
	v_cvt_pk_bf16_f32 v203, v66, v67
	global_store_dwordx4 v217, v[200:203], s[80:81] offset:256
	ds_bpermute_b32 v214, v215, v213
	s_waitcnt lgkmcnt(0)
	v_add_f32_e32 v213, v213, v214
	ds_bpermute_b32 v214, v216, v213
	s_waitcnt lgkmcnt(0)
	v_add_f32_e32 v213, v213, v214
	s_mov_b64 exec, 0xffff
	global_atomic_add_f32 v208, v213, s[12:13] offset:192
	s_mov_b64 exec, -1
	v_add_u32_e32 v212, 0x120000, v210
	global_load_dwordx4 v[192:195], v212, s[36:37]
	global_load_dwordx4 v[196:199], v212, s[36:37] offset:16
	global_load_dwordx4 v[200:203], v212, s[36:37] offset:512
	global_load_dwordx4 v[204:207], v212, s[36:37] offset:528
	s_waitcnt vmcnt(7)
	v_pk_add_f32 v[60:61], v[60:61], v[176:177]
	v_pk_add_f32 v[62:63], v[62:63], v[178:179]
	v_pk_add_f32 v[56:57], v[56:57], v[180:181]
	v_pk_add_f32 v[58:59], v[58:59], v[182:183]
	v_mul_f32_e32 v213, v60, v60
	v_fmac_f32_e32 v213, v61, v61
	v_fmac_f32_e32 v213, v62, v62
	v_fmac_f32_e32 v213, v63, v63
	v_fmac_f32_e32 v213, v56, v56
	v_fmac_f32_e32 v213, v57, v57
	v_fmac_f32_e32 v213, v58, v58
	v_fmac_f32_e32 v213, v59, v59
	v_cvt_pk_bf16_f32 v176, v60, v61
	v_cvt_pk_bf16_f32 v177, v62, v63
	v_cvt_pk_bf16_f32 v178, v56, v57
	v_cvt_pk_bf16_f32 v179, v58, v59
	v_add_u32_e32 v217, 0x80000, v209
	global_store_dwordx4 v217, v[176:179], s[80:81]
	v_pk_add_f32 v[52:53], v[52:53], v[184:185]
	v_pk_add_f32 v[54:55], v[54:55], v[186:187]
	v_pk_add_f32 v[48:49], v[48:49], v[188:189]
	v_pk_add_f32 v[50:51], v[50:51], v[190:191]
	v_fmac_f32_e32 v213, v52, v52
	v_fmac_f32_e32 v213, v53, v53
	v_fmac_f32_e32 v213, v54, v54
	v_fmac_f32_e32 v213, v55, v55
	v_fmac_f32_e32 v213, v48, v48
	v_fmac_f32_e32 v213, v49, v49
	v_fmac_f32_e32 v213, v50, v50
	v_fmac_f32_e32 v213, v51, v51
	v_cvt_pk_bf16_f32 v184, v52, v53
	v_cvt_pk_bf16_f32 v185, v54, v55
	v_cvt_pk_bf16_f32 v186, v48, v49
	v_cvt_pk_bf16_f32 v187, v50, v51
	global_store_dwordx4 v217, v[184:187], s[80:81] offset:256
	ds_bpermute_b32 v214, v215, v213
	s_waitcnt lgkmcnt(0)
	v_add_f32_e32 v213, v213, v214
	ds_bpermute_b32 v214, v216, v213
	s_waitcnt lgkmcnt(0)
	v_add_f32_e32 v213, v213, v214
	s_mov_b64 exec, 0xffff
	global_atomic_add_f32 v208, v213, s[12:13] offset:512
	s_mov_b64 exec, -1
	v_add_u32_e32 v212, 0x140000, v210
	global_load_dwordx4 v[176:179], v212, s[36:37]
	global_load_dwordx4 v[180:183], v212, s[36:37] offset:16
	global_load_dwordx4 v[184:187], v212, s[36:37] offset:512
	global_load_dwordx4 v[188:191], v212, s[36:37] offset:528
	s_waitcnt vmcnt(7)
	v_pk_add_f32 v[44:45], v[44:45], v[192:193]
	v_pk_add_f32 v[46:47], v[46:47], v[194:195]
	v_pk_add_f32 v[40:41], v[40:41], v[196:197]
	v_pk_add_f32 v[42:43], v[42:43], v[198:199]
	v_mul_f32_e32 v213, v44, v44
	v_fmac_f32_e32 v213, v45, v45
	v_fmac_f32_e32 v213, v46, v46
	v_fmac_f32_e32 v213, v47, v47
	v_fmac_f32_e32 v213, v40, v40
	v_fmac_f32_e32 v213, v41, v41
	v_fmac_f32_e32 v213, v42, v42
	v_fmac_f32_e32 v213, v43, v43
	v_cvt_pk_bf16_f32 v192, v44, v45
	v_cvt_pk_bf16_f32 v193, v46, v47
	v_cvt_pk_bf16_f32 v194, v40, v41
	v_cvt_pk_bf16_f32 v195, v42, v43
	v_add_u32_e32 v217, 0x90000, v209
	global_store_dwordx4 v217, v[192:195], s[80:81]
	v_pk_add_f32 v[36:37], v[36:37], v[200:201]
	v_pk_add_f32 v[38:39], v[38:39], v[202:203]
	v_pk_add_f32 v[32:33], v[32:33], v[204:205]
	v_pk_add_f32 v[34:35], v[34:35], v[206:207]
	v_fmac_f32_e32 v213, v36, v36
	v_fmac_f32_e32 v213, v37, v37
	v_fmac_f32_e32 v213, v38, v38
	v_fmac_f32_e32 v213, v39, v39
	v_fmac_f32_e32 v213, v32, v32
	v_fmac_f32_e32 v213, v33, v33
	v_fmac_f32_e32 v213, v34, v34
	v_fmac_f32_e32 v213, v35, v35
	v_cvt_pk_bf16_f32 v200, v36, v37
	v_cvt_pk_bf16_f32 v201, v38, v39
	v_cvt_pk_bf16_f32 v202, v32, v33
	v_cvt_pk_bf16_f32 v203, v34, v35
	global_store_dwordx4 v217, v[200:203], s[80:81] offset:256
	ds_bpermute_b32 v214, v215, v213
	s_waitcnt lgkmcnt(0)
	v_add_f32_e32 v213, v213, v214
	ds_bpermute_b32 v214, v216, v213
	s_waitcnt lgkmcnt(0)
	v_add_f32_e32 v213, v213, v214
	s_mov_b64 exec, 0xffff
	global_atomic_add_f32 v208, v213, s[12:13] offset:576
	s_mov_b64 exec, -1
	v_add_u32_e32 v212, 0x160000, v210
	global_load_dwordx4 v[192:195], v212, s[36:37]
	global_load_dwordx4 v[196:199], v212, s[36:37] offset:16
	global_load_dwordx4 v[200:203], v212, s[36:37] offset:512
	global_load_dwordx4 v[204:207], v212, s[36:37] offset:528
	s_waitcnt vmcnt(7)
	v_pk_add_f32 v[28:29], v[28:29], v[176:177]
	v_pk_add_f32 v[30:31], v[30:31], v[178:179]
	v_pk_add_f32 v[24:25], v[24:25], v[180:181]
	v_pk_add_f32 v[26:27], v[26:27], v[182:183]
	v_mul_f32_e32 v213, v28, v28
	v_fmac_f32_e32 v213, v29, v29
	v_fmac_f32_e32 v213, v30, v30
	v_fmac_f32_e32 v213, v31, v31
	v_fmac_f32_e32 v213, v24, v24
	v_fmac_f32_e32 v213, v25, v25
	v_fmac_f32_e32 v213, v26, v26
	v_fmac_f32_e32 v213, v27, v27
	v_cvt_pk_bf16_f32 v176, v28, v29
	v_cvt_pk_bf16_f32 v177, v30, v31
	v_cvt_pk_bf16_f32 v178, v24, v25
	v_cvt_pk_bf16_f32 v179, v26, v27
	v_add_u32_e32 v217, 0xa0000, v209
	global_store_dwordx4 v217, v[176:179], s[80:81]
	v_pk_add_f32 v[20:21], v[20:21], v[184:185]
	v_pk_add_f32 v[22:23], v[22:23], v[186:187]
	v_pk_add_f32 v[16:17], v[16:17], v[188:189]
	v_pk_add_f32 v[18:19], v[18:19], v[190:191]
	v_fmac_f32_e32 v213, v20, v20
	v_fmac_f32_e32 v213, v21, v21
	v_fmac_f32_e32 v213, v22, v22
	v_fmac_f32_e32 v213, v23, v23
	v_fmac_f32_e32 v213, v16, v16
	v_fmac_f32_e32 v213, v17, v17
	v_fmac_f32_e32 v213, v18, v18
	v_fmac_f32_e32 v213, v19, v19
	v_cvt_pk_bf16_f32 v184, v20, v21
	v_cvt_pk_bf16_f32 v185, v22, v23
	v_cvt_pk_bf16_f32 v186, v16, v17
	v_cvt_pk_bf16_f32 v187, v18, v19
	global_store_dwordx4 v217, v[184:187], s[80:81] offset:256
	ds_bpermute_b32 v214, v215, v213
	s_waitcnt lgkmcnt(0)
	v_add_f32_e32 v213, v213, v214
	ds_bpermute_b32 v214, v216, v213
	s_waitcnt lgkmcnt(0)
	v_add_f32_e32 v213, v213, v214
	s_mov_b64 exec, 0xffff
	global_atomic_add_f32 v208, v213, s[12:13] offset:640
	s_mov_b64 exec, -1
	s_waitcnt vmcnt(3)
	v_pk_add_f32 v[12:13], v[12:13], v[192:193]
	v_pk_add_f32 v[14:15], v[14:15], v[194:195]
	v_pk_add_f32 v[8:9], v[8:9], v[196:197]
	v_pk_add_f32 v[10:11], v[10:11], v[198:199]
	v_mul_f32_e32 v213, v12, v12
	v_fmac_f32_e32 v213, v13, v13
	v_fmac_f32_e32 v213, v14, v14
	v_fmac_f32_e32 v213, v15, v15
	v_fmac_f32_e32 v213, v8, v8
	v_fmac_f32_e32 v213, v9, v9
	v_fmac_f32_e32 v213, v10, v10
	v_fmac_f32_e32 v213, v11, v11
	v_cvt_pk_bf16_f32 v192, v12, v13
	v_cvt_pk_bf16_f32 v193, v14, v15
	v_cvt_pk_bf16_f32 v194, v8, v9
	v_cvt_pk_bf16_f32 v195, v10, v11
	v_add_u32_e32 v217, 0xb0000, v209
	global_store_dwordx4 v217, v[192:195], s[80:81]
	v_pk_add_f32 v[4:5], v[4:5], v[200:201]
	v_pk_add_f32 v[6:7], v[6:7], v[202:203]
	v_pk_add_f32 v[0:1], v[0:1], v[204:205]
	v_pk_add_f32 v[2:3], v[2:3], v[206:207]
	v_fmac_f32_e32 v213, v4, v4
	v_fmac_f32_e32 v213, v5, v5
	v_fmac_f32_e32 v213, v6, v6
	v_fmac_f32_e32 v213, v7, v7
	v_fmac_f32_e32 v213, v0, v0
	v_fmac_f32_e32 v213, v1, v1
	v_fmac_f32_e32 v213, v2, v2
	v_fmac_f32_e32 v213, v3, v3
	v_cvt_pk_bf16_f32 v200, v4, v5
	v_cvt_pk_bf16_f32 v201, v6, v7
	v_cvt_pk_bf16_f32 v202, v0, v1
	v_cvt_pk_bf16_f32 v203, v2, v3
	global_store_dwordx4 v217, v[200:203], s[80:81] offset:256
	ds_bpermute_b32 v214, v215, v213
	s_waitcnt lgkmcnt(0)
	v_add_f32_e32 v213, v213, v214
	ds_bpermute_b32 v214, v216, v213
	s_waitcnt lgkmcnt(0)
	v_add_f32_e32 v213, v213, v214
	s_mov_b64 exec, 0xffff
	global_atomic_add_f32 v208, v213, s[12:13] offset:704
	s_mov_b64 exec, -1
	s_branch .LBB0_273

.LBB0_363:
	ds_read_b128 v[76:79], v231
	v_xor_b32_e32 v91, 64, v231
	ds_read_b128 v[80:83], v91
	ds_read_b128 v[84:87], v231 offset:2048
	ds_read_b128 v[88:91], v91 offset:2048
	s_add_u32 s8, s6, 0x100
	s_addc_u32 s9, s7, 0
	s_cmp_eq_u32 s65, 28
	s_cselect_b32 s39, s31, s9
	s_cselect_b32 s38, s33, s8
	s_cselect_b32 s11, s29, s64
	s_cselect_b32 s10, s62, s63
	v_lshl_add_u64 v[108:109], s[6:7], 0, v[172:173]
	s_add_i32 m0, s44, 0xc000
	ds_read_b128 v[92:95], v241
	v_xor_b32_e32 v195, 64, v241
	ds_read_b128 v[96:99], v195
	ds_read_b128 v[100:103], v241 offset:2048
	ds_read_b128 v[104:107], v195 offset:2048
	ds_read_b128 v[180:183], v241 offset:4096
	ds_read_b128 v[184:187], v195 offset:4096
	ds_read_b128 v[188:191], v241 offset:6144
	ds_read_b128 v[192:195], v195 offset:6144
	global_load_lds_dwordx4 v[108:109], off
	v_lshl_add_u64 v[108:109], s[6:7], 0, v[174:175]
	s_add_i32 m0, s44, 0xe000
	s_nop 0
	global_load_lds_dwordx4 v[108:109], off
	s_waitcnt lgkmcnt(8)
	s_barrier
	s_waitcnt lgkmcnt(0)
	s_setprio 1
	s_waitcnt lgkmcnt(0)
	v_mfma_f32_16x16x32_bf16 v[158:161], v[76:79], v[92:95], v[158:161]
	v_mfma_f32_16x16x32_bf16 v[158:161], v[80:83], v[96:99], v[158:161]
	v_mfma_f32_16x16x32_bf16 v[60:63], v[88:91], v[96:99], v[60:63]
	v_mfma_f32_16x16x32_bf16 v[60:63], v[84:87], v[92:95], v[60:63]
	v_mfma_f32_16x16x32_bf16 v[52:55], v[84:87], v[100:103], v[52:55]
	v_mfma_f32_16x16x32_bf16 v[52:55], v[88:91], v[104:107], v[52:55]
	v_mfma_f32_16x16x32_bf16 v[150:153], v[80:83], v[104:107], v[150:153]
	v_mfma_f32_16x16x32_bf16 v[150:153], v[76:79], v[100:103], v[150:153]
	v_mfma_f32_16x16x32_bf16 v[146:149], v[76:79], v[180:183], v[146:149]
	v_mfma_f32_16x16x32_bf16 v[146:149], v[80:83], v[184:187], v[146:149]
	v_mfma_f32_16x16x32_bf16 v[48:51], v[88:91], v[184:187], v[48:51]
	v_mfma_f32_16x16x32_bf16 v[48:51], v[84:87], v[180:183], v[48:51]
	v_mfma_f32_16x16x32_bf16 v[40:43], v[84:87], v[188:191], v[40:43]
	v_mfma_f32_16x16x32_bf16 v[40:43], v[88:91], v[192:195], v[40:43]
	v_mfma_f32_16x16x32_bf16 v[138:141], v[80:83], v[192:195], v[138:141]
	v_mfma_f32_16x16x32_bf16 v[138:141], v[76:79], v[188:191], v[138:141]
	s_setprio 0
	s_barrier
	s_add_i32 s6, s58, s42
	v_lshl_add_u64 v[216:217], s[10:11], 0, v[164:165]
	s_mov_b32 m0, s6
	ds_read_b128 v[196:199], v242
	v_xor_b32_e32 v211, 64, v242
	ds_read_b128 v[200:203], v211
	ds_read_b128 v[204:207], v242 offset:2048
	ds_read_b128 v[208:211], v211 offset:2048
	global_load_lds_dwordx4 v[216:217], off
	v_lshl_add_u64 v[244:245], s[10:11], 0, v[166:167]
	s_add_i32 m0, s6, 0x2000
	s_nop 0
	global_load_lds_dwordx4 v[244:245], off
	s_barrier
	s_waitcnt lgkmcnt(0)
	s_setprio 1
	s_waitcnt lgkmcnt(0)
	v_mfma_f32_16x16x32_bf16 v[154:157], v[196:199], v[92:95], v[154:157]
	v_mfma_f32_16x16x32_bf16 v[154:157], v[200:203], v[96:99], v[154:157]
	v_mfma_f32_16x16x32_bf16 v[56:59], v[208:211], v[96:99], v[56:59]
	v_mfma_f32_16x16x32_bf16 v[56:59], v[204:207], v[92:95], v[56:59]
	v_mfma_f32_16x16x32_bf16 v[44:47], v[204:207], v[100:103], v[44:47]
	v_mfma_f32_16x16x32_bf16 v[44:47], v[208:211], v[104:107], v[44:47]
	v_mfma_f32_16x16x32_bf16 v[36:39], v[208:211], v[184:187], v[36:39]
	v_mfma_f32_16x16x32_bf16 v[36:39], v[204:207], v[180:183], v[36:39]
	v_mfma_f32_16x16x32_bf16 v[32:35], v[204:207], v[188:191], v[32:35]
	v_mfma_f32_16x16x32_bf16 v[32:35], v[208:211], v[192:195], v[32:35]
	v_mfma_f32_16x16x32_bf16 v[92:95], v[196:199], v[100:103], v[142:145]
	v_mfma_f32_16x16x32_bf16 v[92:95], v[200:203], v[104:107], v[92:95]
	v_mfma_f32_16x16x32_bf16 v[96:99], v[200:203], v[184:187], v[134:137]
	v_mfma_f32_16x16x32_bf16 v[96:99], v[196:199], v[180:183], v[96:99]
	v_mfma_f32_16x16x32_bf16 v[100:103], v[196:199], v[188:191], v[130:133]
	v_mfma_f32_16x16x32_bf16 v[100:103], v[200:203], v[192:195], v[100:103]
	s_setprio 0
	s_mov_b32 m0, s44
	v_lshl_add_u64 v[246:247], s[38:39], 0, v[170:171]
	s_barrier
	ds_read_b128 v[104:107], v241 offset:16384
	v_xor_b32_e32 v195, 64, v241
	ds_read_b128 v[130:133], v195 offset:16384
	ds_read_b128 v[134:137], v241 offset:18432
	ds_read_b128 v[142:145], v195 offset:18432
	ds_read_b128 v[180:183], v241 offset:20480
	ds_read_b128 v[184:187], v195 offset:20480
	ds_read_b128 v[188:191], v241 offset:22528
	ds_read_b128 v[192:195], v195 offset:22528
	global_load_lds_dwordx4 v[246:247], off
	v_lshl_add_u64 v[248:249], s[38:39], 0, v[168:169]
	s_mov_b32 m0, s45
	s_nop 0
	global_load_lds_dwordx4 v[248:249], off
	s_barrier
	s_waitcnt lgkmcnt(0)
	s_setprio 1
	s_waitcnt lgkmcnt(0)
	v_mfma_f32_16x16x32_bf16 v[126:129], v[76:79], v[104:107], v[126:129]
	v_mfma_f32_16x16x32_bf16 v[126:129], v[80:83], v[130:133], v[126:129]
	v_mfma_f32_16x16x32_bf16 v[28:31], v[88:91], v[130:133], v[28:31]
	v_mfma_f32_16x16x32_bf16 v[28:31], v[84:87], v[104:107], v[28:31]
	v_mfma_f32_16x16x32_bf16 v[24:27], v[84:87], v[134:137], v[24:27]
	v_mfma_f32_16x16x32_bf16 v[24:27], v[88:91], v[142:145], v[24:27]
	v_mfma_f32_16x16x32_bf16 v[122:125], v[80:83], v[142:145], v[122:125]
	v_mfma_f32_16x16x32_bf16 v[122:125], v[76:79], v[134:137], v[122:125]
	v_mfma_f32_16x16x32_bf16 v[114:117], v[76:79], v[180:183], v[114:117]
	v_mfma_f32_16x16x32_bf16 v[114:117], v[80:83], v[184:187], v[114:117]
	v_mfma_f32_16x16x32_bf16 v[20:23], v[88:91], v[184:187], v[20:23]
	v_mfma_f32_16x16x32_bf16 v[20:23], v[84:87], v[180:183], v[20:23]
	v_mfma_f32_16x16x32_bf16 v[4:7], v[84:87], v[188:191], v[4:7]
	v_mfma_f32_16x16x32_bf16 v[4:7], v[88:91], v[192:195], v[4:7]
	v_mfma_f32_16x16x32_bf16 v[72:75], v[80:83], v[192:195], v[72:75]
	v_mfma_f32_16x16x32_bf16 v[72:75], v[76:79], v[188:191], v[72:75]
	s_setprio 0
	s_barrier
	s_add_u32 s6, s10, 0x1600000
	s_addc_u32 s7, s11, 0
	s_add_i32 s66, s59, s42
	v_lshl_add_u64 v[76:77], s[6:7], 0, v[164:165]
	s_mov_b32 m0, s66
	s_nop 0
	global_load_lds_dwordx4 v[76:77], off
	v_lshl_add_u64 v[76:77], s[6:7], 0, v[166:167]
	s_add_i32 m0, s66, 0x2000
	s_nop 0
	global_load_lds_dwordx4 v[76:77], off
	s_waitcnt vmcnt(6)
	s_barrier
	s_setprio 1
	v_mfma_f32_16x16x32_bf16 v[16:19], v[204:207], v[104:107], v[16:19]
	v_mfma_f32_16x16x32_bf16 v[16:19], v[208:211], v[130:133], v[16:19]
	v_mfma_f32_16x16x32_bf16 v[12:15], v[208:211], v[142:145], v[12:15]
	v_mfma_f32_16x16x32_bf16 v[12:15], v[204:207], v[134:137], v[12:15]
	v_mfma_f32_16x16x32_bf16 v[8:11], v[204:207], v[180:183], v[8:11]
	v_mfma_f32_16x16x32_bf16 v[8:11], v[208:211], v[184:187], v[8:11]
	v_mfma_f32_16x16x32_bf16 v[68:71], v[200:203], v[184:187], v[68:71]
	v_mfma_f32_16x16x32_bf16 v[68:71], v[196:199], v[180:183], v[68:71]
	v_mfma_f32_16x16x32_bf16 v[64:67], v[196:199], v[188:191], v[64:67]
	v_mfma_f32_16x16x32_bf16 v[64:67], v[200:203], v[192:195], v[64:67]
	v_mfma_f32_16x16x32_bf16 v[0:3], v[208:211], v[192:195], v[0:3]
	v_mfma_f32_16x16x32_bf16 v[0:3], v[204:207], v[188:191], v[0:3]
	v_mfma_f32_16x16x32_bf16 v[76:79], v[196:199], v[104:107], v[118:121]
	v_mfma_f32_16x16x32_bf16 v[76:79], v[200:203], v[130:133], v[76:79]
	v_mfma_f32_16x16x32_bf16 v[80:83], v[200:203], v[142:145], v[110:113]
	v_mfma_f32_16x16x32_bf16 v[80:83], v[196:199], v[134:137], v[80:83]
	s_setprio 0
	s_add_i32 s66, 0, 0x18000
	v_add_u32_e32 v108, s66, v229
	s_barrier
	ds_read_b128 v[84:87], v108
	v_xor_b32_e32 v111, 64, v108
	ds_read_b128 v[88:91], v111
	ds_read_b128 v[104:107], v108 offset:2048
	ds_read_b128 v[108:111], v111 offset:2048
	s_add_u32 s6, s38, 0x40000
	s_addc_u32 s7, s39, 0
	s_mov_b32 m0, s46
	v_lshl_add_u64 v[112:113], s[6:7], 0, v[170:171]
	ds_read_b128 v[118:121], v241 offset:32768
	v_xor_b32_e32 v199, 64, v241
	ds_read_b128 v[130:133], v199 offset:32768
	ds_read_b128 v[134:137], v241 offset:34816
	ds_read_b128 v[180:183], v199 offset:34816
	ds_read_b128 v[184:187], v241 offset:36864
	ds_read_b128 v[188:191], v199 offset:36864
	ds_read_b128 v[192:195], v241 offset:38912
	ds_read_b128 v[196:199], v199 offset:38912
	global_load_lds_dwordx4 v[112:113], off
	v_lshl_add_u64 v[112:113], s[6:7], 0, v[168:169]
	s_mov_b32 m0, s47
	s_nop 0
	global_load_lds_dwordx4 v[112:113], off
	s_waitcnt lgkmcnt(8)
	s_barrier
	s_waitcnt lgkmcnt(0)
	s_setprio 1
	s_waitcnt lgkmcnt(0)
	v_mfma_f32_16x16x32_bf16 v[142:145], v[84:87], v[118:121], v[158:161]
	v_mfma_f32_16x16x32_bf16 v[158:161], v[88:91], v[130:133], v[142:145]
	v_mfma_f32_16x16x32_bf16 v[60:63], v[108:111], v[130:133], v[60:63]
	v_mfma_f32_16x16x32_bf16 v[60:63], v[104:107], v[118:121], v[60:63]
	v_mfma_f32_16x16x32_bf16 v[52:55], v[104:107], v[134:137], v[52:55]
	v_mfma_f32_16x16x32_bf16 v[52:55], v[108:111], v[180:183], v[52:55]
	v_mfma_f32_16x16x32_bf16 v[48:51], v[108:111], v[188:191], v[48:51]
	v_mfma_f32_16x16x32_bf16 v[48:51], v[104:107], v[184:187], v[48:51]
	v_mfma_f32_16x16x32_bf16 v[40:43], v[104:107], v[192:195], v[40:43]
	v_mfma_f32_16x16x32_bf16 v[40:43], v[108:111], v[196:199], v[40:43]
	v_mfma_f32_16x16x32_bf16 v[138:141], v[88:91], v[196:199], v[138:141]
	v_mfma_f32_16x16x32_bf16 v[138:141], v[84:87], v[192:195], v[138:141]
	v_mfma_f32_16x16x32_bf16 v[142:145], v[84:87], v[134:137], v[150:153]
	v_mfma_f32_16x16x32_bf16 v[150:153], v[88:91], v[180:183], v[142:145]
	v_mfma_f32_16x16x32_bf16 v[142:145], v[84:87], v[184:187], v[146:149]
	v_mfma_f32_16x16x32_bf16 v[146:149], v[88:91], v[188:191], v[142:145]
	s_setprio 0
	s_barrier
	s_add_i32 s38, 0, 0x1c000
	v_add_u32_e32 v112, s38, v229
	s_add_i32 s6, s66, s42
	ds_read_b128 v[200:203], v112
	v_xor_b32_e32 v215, 64, v112
	ds_read_b128 v[204:207], v215
	ds_read_b128 v[208:211], v112 offset:2048
	ds_read_b128 v[212:215], v215 offset:2048
	v_lshl_add_u64 v[112:113], v[216:217], 0, s[14:15]
	s_mov_b32 m0, s6
	s_nop 0
	global_load_lds_dwordx4 v[112:113], off
	v_lshl_add_u64 v[112:113], v[244:245], 0, s[14:15]
	s_add_i32 m0, s6, 0x2000
	s_nop 0
	global_load_lds_dwordx4 v[112:113], off
	s_barrier
	s_waitcnt lgkmcnt(0)
	s_setprio 1
	s_waitcnt lgkmcnt(0)
	v_mfma_f32_16x16x32_bf16 v[142:145], v[200:203], v[118:121], v[154:157]
	v_mfma_f32_16x16x32_bf16 v[154:157], v[204:207], v[130:133], v[142:145]
	v_mfma_f32_16x16x32_bf16 v[56:59], v[212:215], v[130:133], v[56:59]
	v_mfma_f32_16x16x32_bf16 v[56:59], v[208:211], v[118:121], v[56:59]
	v_mfma_f32_16x16x32_bf16 v[44:47], v[208:211], v[134:137], v[44:47]
	v_mfma_f32_16x16x32_bf16 v[44:47], v[212:215], v[180:183], v[44:47]
	v_mfma_f32_16x16x32_bf16 v[36:39], v[212:215], v[188:191], v[36:39]
	v_mfma_f32_16x16x32_bf16 v[36:39], v[208:211], v[184:187], v[36:39]
	v_mfma_f32_16x16x32_bf16 v[32:35], v[208:211], v[192:195], v[32:35]
	v_mfma_f32_16x16x32_bf16 v[32:35], v[212:215], v[196:199], v[32:35]
	v_mfma_f32_16x16x32_bf16 v[92:95], v[200:203], v[134:137], v[92:95]
	v_mfma_f32_16x16x32_bf16 v[142:145], v[204:207], v[180:183], v[92:95]
	v_mfma_f32_16x16x32_bf16 v[92:95], v[200:203], v[184:187], v[96:99]
	v_mfma_f32_16x16x32_bf16 v[134:137], v[204:207], v[188:191], v[92:95]
	v_mfma_f32_16x16x32_bf16 v[92:95], v[200:203], v[192:195], v[100:103]
	v_mfma_f32_16x16x32_bf16 v[130:133], v[204:207], v[196:199], v[92:95]
	s_setprio 0
	s_mov_b32 m0, s52
	v_lshl_add_u64 v[112:113], v[246:247], 0, s[14:15]
	s_barrier
	ds_read_b128 v[92:95], v241 offset:49152
	v_xor_b32_e32 v199, 64, v241
	ds_read_b128 v[96:99], v199 offset:49152
	ds_read_b128 v[100:103], v241 offset:51200
	ds_read_b128 v[180:183], v199 offset:51200
	ds_read_b128 v[184:187], v241 offset:53248
	ds_read_b128 v[188:191], v199 offset:53248
	ds_read_b128 v[192:195], v241 offset:55296
	ds_read_b128 v[196:199], v199 offset:55296
	global_load_lds_dwordx4 v[112:113], off
	v_lshl_add_u64 v[112:113], v[248:249], 0, s[14:15]
	s_mov_b32 m0, s53
	s_nop 0
	global_load_lds_dwordx4 v[112:113], off
	s_barrier
	s_waitcnt lgkmcnt(0)
	s_setprio 1
	s_waitcnt lgkmcnt(0)
	v_mfma_f32_16x16x32_bf16 v[118:121], v[84:87], v[92:95], v[126:129]
	v_mfma_f32_16x16x32_bf16 v[126:129], v[88:91], v[96:99], v[118:121]
	v_mfma_f32_16x16x32_bf16 v[28:31], v[108:111], v[96:99], v[28:31]
	v_mfma_f32_16x16x32_bf16 v[28:31], v[104:107], v[92:95], v[28:31]
	v_mfma_f32_16x16x32_bf16 v[24:27], v[104:107], v[100:103], v[24:27]
	v_mfma_f32_16x16x32_bf16 v[24:27], v[108:111], v[180:183], v[24:27]
	v_mfma_f32_16x16x32_bf16 v[20:23], v[108:111], v[188:191], v[20:23]
	v_mfma_f32_16x16x32_bf16 v[20:23], v[104:107], v[184:187], v[20:23]
	v_mfma_f32_16x16x32_bf16 v[112:115], v[84:87], v[184:187], v[114:117]
	v_mfma_f32_16x16x32_bf16 v[114:117], v[88:91], v[188:191], v[112:115]
	v_mfma_f32_16x16x32_bf16 v[72:75], v[88:91], v[196:199], v[72:75]
	v_mfma_f32_16x16x32_bf16 v[72:75], v[84:87], v[192:195], v[72:75]
	v_mfma_f32_16x16x32_bf16 v[118:121], v[84:87], v[100:103], v[122:125]
	v_mfma_f32_16x16x32_bf16 v[122:125], v[88:91], v[180:183], v[118:121]
	v_mfma_f32_16x16x32_bf16 v[4:7], v[104:107], v[192:195], v[4:7]
	v_mfma_f32_16x16x32_bf16 v[4:7], v[108:111], v[196:199], v[4:7]
	s_setprio 0
	s_barrier
	s_add_u32 s6, s10, 0x1600080
	s_addc_u32 s7, s11, 0
	s_add_i32 s10, s38, s42
	v_lshl_add_u64 v[84:85], s[6:7], 0, v[164:165]
	s_mov_b32 m0, s10
	s_nop 0
	global_load_lds_dwordx4 v[84:85], off
	v_lshl_add_u64 v[84:85], s[6:7], 0, v[166:167]
	s_add_i32 m0, s10, 0x2000
	s_nop 0
	global_load_lds_dwordx4 v[84:85], off
	s_waitcnt vmcnt(6)
	s_barrier
	s_setprio 1
	v_mfma_f32_16x16x32_bf16 v[76:79], v[200:203], v[92:95], v[76:79]
	v_mfma_f32_16x16x32_bf16 v[118:121], v[204:207], v[96:99], v[76:79]
	v_mfma_f32_16x16x32_bf16 v[16:19], v[212:215], v[96:99], v[16:19]
	v_mfma_f32_16x16x32_bf16 v[16:19], v[208:211], v[92:95], v[16:19]
	v_mfma_f32_16x16x32_bf16 v[12:15], v[208:211], v[100:103], v[12:15]
	v_mfma_f32_16x16x32_bf16 v[12:15], v[212:215], v[180:183], v[12:15]
	v_mfma_f32_16x16x32_bf16 v[8:11], v[212:215], v[188:191], v[8:11]
	v_mfma_f32_16x16x32_bf16 v[8:11], v[208:211], v[184:187], v[8:11]
	v_mfma_f32_16x16x32_bf16 v[68:71], v[200:203], v[184:187], v[68:71]
	v_mfma_f32_16x16x32_bf16 v[68:71], v[204:207], v[188:191], v[68:71]
	v_mfma_f32_16x16x32_bf16 v[64:67], v[204:207], v[196:199], v[64:67]
	v_mfma_f32_16x16x32_bf16 v[64:67], v[200:203], v[192:195], v[64:67]
	v_mfma_f32_16x16x32_bf16 v[76:79], v[200:203], v[100:103], v[80:83]
	v_mfma_f32_16x16x32_bf16 v[110:113], v[204:207], v[180:183], v[76:79]
	v_mfma_f32_16x16x32_bf16 v[0:3], v[208:211], v[192:195], v[0:3]
	v_mfma_f32_16x16x32_bf16 v[0:3], v[212:215], v[196:199], v[0:3]
	s_setprio 0
	s_add_i32 s65, s65, 2
	s_add_u32 s63, s63, 0x100
	s_addc_u32 s64, s64, 0
	s_cmp_gt_u32 s65, 29
	s_mov_b64 s[6:7], s[8:9]
	s_barrier
	s_cbranch_scc0 .LBB0_363
	s_lshl_b32 s6, s0, 8
	s_lshl_b32 s1, s1, 7
	v_mov_b32_e32 v185, v163
	v_mov_b32_e32 v80, v225
	s_add_i32 s6, s6, s56
	s_or_b32 s1, s1, s49
	s_lshl_b32 s0, s0, 3
	v_add_u32_e32 v182, s6, v185
	v_lshl_add_u32 v180, v80, 3, s1
	v_ashrrev_i32_e32 v183, 31, v182
	v_ashrrev_i32_e32 v181, 31, v180
	v_lshl_add_u64 v[78:79], v[182:183], 2, s[12:13]
	v_lshlrev_b64 v[90:91], 2, v[180:181]
	global_load_dword v188, v[78:79], off
	global_load_dword v184, v[78:79], off offset:64
	global_load_dword v186, v[78:79], off offset:128
	global_load_dword v196, v[78:79], off offset:192
	global_load_dword v195, v[78:79], off offset:256
	global_load_dword v77, v[78:79], off offset:320
	global_load_dword v76, v[78:79], off offset:384
	global_load_dword v183, v[78:79], off offset:448
	v_lshl_add_u64 v[190:191], s[82:83], 0, v[90:91]
	v_lshl_add_u64 v[78:79], s[16:17], 0, v[90:91]
	v_lshl_add_u64 v[80:81], s[18:19], 0, v[90:91]
	global_load_dwordx4 v[94:97], v[190:191], off
	global_load_dwordx4 v[102:105], v[78:79], off
	global_load_dwordx4 v[98:101], v[80:81], off
	v_lshl_add_u64 v[192:193], s[84:85], 0, v[90:91]
	v_lshl_add_u64 v[78:79], s[20:21], 0, v[90:91]
	v_lshl_add_u64 v[80:81], s[22:23], 0, v[90:91]
	v_lshl_add_u64 v[82:83], s[24:25], 0, v[90:91]
	v_lshl_add_u64 v[90:91], s[26:27], 0, v[90:91]
	global_load_dwordx4 v[106:109], v[192:193], off
	global_load_dwordx4 v[86:89], v[78:79], off
	s_nop 0
	global_load_dwordx4 v[78:81], v[80:81], off
	s_add_i32 s0, s0, s57
	global_load_dwordx4 v[82:85], v[82:83], off
	v_add_u32_e32 v187, s0, v185
	global_load_dwordx4 v[90:93], v[90:91], off
	v_cmp_gt_i32_e64 s[10:11], 2, v185
	s_waitcnt vmcnt(0)
	v_fmamk_f32 v188, v188, 0x3a000000, v243
	v_rsq_f32_e32 v194, v188
	v_mad_i64_i32 v[188:189], s[0:1], v187, s60, 0
	v_lshl_add_u64 v[188:189], s[70:71], 0, v[188:189]
	v_pk_mul_f32 v[160:161], v[160:161], v[194:195] op_sel_hi:[1,0]
	v_pk_mul_f32 v[158:159], v[158:159], v[194:195] op_sel_hi:[1,0]
	v_pk_mul_f32 v[156:157], v[156:157], v[194:195] op_sel_hi:[1,0]
	v_pk_mul_f32 v[154:155], v[154:155], v[194:195] op_sel_hi:[1,0]
	v_lshl_add_u64 v[188:189], v[180:181], 2, v[188:189]
	s_and_saveexec_b64 s[0:1], s[10:11]
	s_cbranch_execz .LBB0_366
	v_add_co_u32_e32 v198, vcc, 0x5000, v188
	global_store_dwordx4 v[188:189], v[158:161], off
	s_nop 0
	v_addc_co_u32_e32 v199, vcc, 0, v189, vcc
	global_store_dwordx4 v[198:199], v[154:157], off offset:2048

.LBB0_508:
	ds_read_b128 v[136:139], v141
	v_xor_b32_e32 v157, 64, v141
	ds_read_b128 v[146:149], v157
	ds_read_b128 v[150:153], v141 offset:2048
	ds_read_b128 v[154:157], v157 offset:2048
	s_add_u32 s8, s0, 0xffea0080
	s_addc_u32 s9, s1, -1
	s_cmpk_eq_i32 s41, 0x54
	s_cselect_b32 s17, s13, s9
	s_cselect_b32 s16, s12, s8
	s_cselect_b32 s9, s11, s40
	s_cselect_b32 s8, s10, s39
	v_lshl_add_u64 v[204:205], s[0:1], 0, v[128:129]
	s_add_i32 m0, s21, 0xc000
	ds_read_b128 v[158:161], v142
	v_xor_b32_e32 v203, 64, v142
	ds_read_b128 v[176:179], v203
	ds_read_b128 v[180:183], v142 offset:2048
	ds_read_b128 v[184:187], v203 offset:2048
	ds_read_b128 v[188:191], v142 offset:4096
	ds_read_b128 v[192:195], v203 offset:4096
	ds_read_b128 v[196:199], v142 offset:6144
	ds_read_b128 v[200:203], v203 offset:6144
	global_load_lds_dwordx4 v[204:205], off
	v_lshl_add_u64 v[204:205], s[0:1], 0, v[130:131]
	s_add_i32 m0, s21, 0xe000
	s_nop 0
	global_load_lds_dwordx4 v[204:205], off
	s_waitcnt lgkmcnt(8)
	s_barrier
	s_waitcnt lgkmcnt(0)
	s_setprio 1
	s_waitcnt lgkmcnt(0)
	v_mfma_f32_16x16x32_bf16 v[124:127], v[136:139], v[158:161], v[124:127]
	v_mfma_f32_16x16x32_bf16 v[124:127], v[146:149], v[176:179], v[124:127]
	v_mfma_f32_16x16x32_bf16 v[120:123], v[154:157], v[176:179], v[120:123]
	v_mfma_f32_16x16x32_bf16 v[120:123], v[150:153], v[158:161], v[120:123]
	v_mfma_f32_16x16x32_bf16 v[104:107], v[150:153], v[180:183], v[104:107]
	v_mfma_f32_16x16x32_bf16 v[104:107], v[154:157], v[184:187], v[104:107]
	v_mfma_f32_16x16x32_bf16 v[108:111], v[146:149], v[184:187], v[108:111]
	v_mfma_f32_16x16x32_bf16 v[108:111], v[136:139], v[180:183], v[108:111]
	v_mfma_f32_16x16x32_bf16 v[92:95], v[136:139], v[188:191], v[92:95]
	v_mfma_f32_16x16x32_bf16 v[92:95], v[146:149], v[192:195], v[92:95]
	v_mfma_f32_16x16x32_bf16 v[88:91], v[154:157], v[192:195], v[88:91]
	v_mfma_f32_16x16x32_bf16 v[88:91], v[150:153], v[188:191], v[88:91]
	v_mfma_f32_16x16x32_bf16 v[72:75], v[150:153], v[196:199], v[72:75]
	v_mfma_f32_16x16x32_bf16 v[72:75], v[154:157], v[200:203], v[72:75]
	v_mfma_f32_16x16x32_bf16 v[76:79], v[146:149], v[200:203], v[76:79]
	v_mfma_f32_16x16x32_bf16 v[76:79], v[136:139], v[196:199], v[76:79]
	s_setprio 0
	s_barrier
	s_add_i32 s42, s33, s20
	v_lshl_add_u64 v[216:217], s[8:9], 0, v[170:171]
	s_mov_b32 m0, s42
	ds_read_b128 v[204:207], v143
	v_xor_b32_e32 v243, 64, v143
	ds_read_b128 v[208:211], v243
	ds_read_b128 v[212:215], v143 offset:2048
	ds_read_b128 v[240:243], v243 offset:2048
	global_load_lds_dwordx4 v[216:217], off
	v_lshl_add_u64 v[244:245], s[8:9], 0, v[174:175]
	s_add_i32 m0, s42, 0x2000
	s_nop 0
	global_load_lds_dwordx4 v[244:245], off
	s_barrier
	s_waitcnt lgkmcnt(0)
	s_setprio 1
	s_waitcnt lgkmcnt(0)
	v_mfma_f32_16x16x32_bf16 v[116:119], v[204:207], v[158:161], v[116:119]
	v_mfma_f32_16x16x32_bf16 v[116:119], v[208:211], v[176:179], v[116:119]
	v_mfma_f32_16x16x32_bf16 v[112:115], v[240:243], v[176:179], v[112:115]
	v_mfma_f32_16x16x32_bf16 v[112:115], v[212:215], v[158:161], v[112:115]
	v_mfma_f32_16x16x32_bf16 v[96:99], v[212:215], v[180:183], v[96:99]
	v_mfma_f32_16x16x32_bf16 v[96:99], v[240:243], v[184:187], v[96:99]
	v_mfma_f32_16x16x32_bf16 v[100:103], v[208:211], v[184:187], v[100:103]
	v_mfma_f32_16x16x32_bf16 v[100:103], v[204:207], v[180:183], v[100:103]
	v_mfma_f32_16x16x32_bf16 v[84:87], v[204:207], v[188:191], v[84:87]
	v_mfma_f32_16x16x32_bf16 v[84:87], v[208:211], v[192:195], v[84:87]
	v_mfma_f32_16x16x32_bf16 v[80:83], v[240:243], v[192:195], v[80:83]
	v_mfma_f32_16x16x32_bf16 v[80:83], v[212:215], v[188:191], v[80:83]
	v_mfma_f32_16x16x32_bf16 v[64:67], v[212:215], v[196:199], v[64:67]
	v_mfma_f32_16x16x32_bf16 v[64:67], v[240:243], v[200:203], v[64:67]
	v_mfma_f32_16x16x32_bf16 v[68:71], v[208:211], v[200:203], v[68:71]
	v_mfma_f32_16x16x32_bf16 v[68:71], v[204:207], v[196:199], v[68:71]
	s_setprio 0
	s_mov_b32 m0, s21
	v_lshl_add_u64 v[246:247], s[16:17], 0, v[168:169]
	s_barrier
	ds_read_b128 v[158:161], v142 offset:16384
	v_xor_b32_e32 v203, 64, v142
	ds_read_b128 v[176:179], v203 offset:16384
	ds_read_b128 v[180:183], v142 offset:18432
	ds_read_b128 v[184:187], v203 offset:18432
	ds_read_b128 v[188:191], v142 offset:20480
	ds_read_b128 v[192:195], v203 offset:20480
	ds_read_b128 v[196:199], v142 offset:22528
	ds_read_b128 v[200:203], v203 offset:22528
	global_load_lds_dwordx4 v[246:247], off
	v_lshl_add_u64 v[248:249], s[16:17], 0, v[172:173]
	s_mov_b32 m0, s22
	s_nop 0
	global_load_lds_dwordx4 v[248:249], off
	s_barrier
	s_waitcnt lgkmcnt(0)
	s_setprio 1
	s_waitcnt lgkmcnt(0)
	v_mfma_f32_16x16x32_bf16 v[60:63], v[136:139], v[158:161], v[60:63]
	v_mfma_f32_16x16x32_bf16 v[60:63], v[146:149], v[176:179], v[60:63]
	v_mfma_f32_16x16x32_bf16 v[56:59], v[154:157], v[176:179], v[56:59]
	v_mfma_f32_16x16x32_bf16 v[56:59], v[150:153], v[158:161], v[56:59]
	v_mfma_f32_16x16x32_bf16 v[40:43], v[150:153], v[180:183], v[40:43]
	v_mfma_f32_16x16x32_bf16 v[40:43], v[154:157], v[184:187], v[40:43]
	v_mfma_f32_16x16x32_bf16 v[44:47], v[146:149], v[184:187], v[44:47]
	v_mfma_f32_16x16x32_bf16 v[44:47], v[136:139], v[180:183], v[44:47]
	v_mfma_f32_16x16x32_bf16 v[28:31], v[136:139], v[188:191], v[28:31]
	v_mfma_f32_16x16x32_bf16 v[28:31], v[146:149], v[192:195], v[28:31]
	v_mfma_f32_16x16x32_bf16 v[24:27], v[154:157], v[192:195], v[24:27]
	v_mfma_f32_16x16x32_bf16 v[24:27], v[150:153], v[188:191], v[24:27]
	v_mfma_f32_16x16x32_bf16 v[8:11], v[150:153], v[196:199], v[8:11]
	v_mfma_f32_16x16x32_bf16 v[8:11], v[154:157], v[200:203], v[8:11]
	v_mfma_f32_16x16x32_bf16 v[12:15], v[146:149], v[200:203], v[12:15]
	v_mfma_f32_16x16x32_bf16 v[12:15], v[136:139], v[196:199], v[12:15]
	s_setprio 0
	s_barrier
	s_add_u32 s42, s8, 0x160000
	s_addc_u32 s43, s9, 0
	s_add_i32 s44, s34, s20
	v_lshl_add_u64 v[136:137], s[42:43], 0, v[170:171]
	s_mov_b32 m0, s44
	s_nop 0
	global_load_lds_dwordx4 v[136:137], off
	v_lshl_add_u64 v[136:137], s[42:43], 0, v[174:175]
	s_add_i32 m0, s44, 0x2000
	s_nop 0
	global_load_lds_dwordx4 v[136:137], off
	s_waitcnt vmcnt(6)
	s_barrier
	s_setprio 1
	v_mfma_f32_16x16x32_bf16 v[52:55], v[204:207], v[158:161], v[52:55]
	v_mfma_f32_16x16x32_bf16 v[52:55], v[208:211], v[176:179], v[52:55]
	v_mfma_f32_16x16x32_bf16 v[48:51], v[240:243], v[176:179], v[48:51]
	v_mfma_f32_16x16x32_bf16 v[48:51], v[212:215], v[158:161], v[48:51]
	v_mfma_f32_16x16x32_bf16 v[32:35], v[212:215], v[180:183], v[32:35]
	v_mfma_f32_16x16x32_bf16 v[32:35], v[240:243], v[184:187], v[32:35]
	v_mfma_f32_16x16x32_bf16 v[36:39], v[208:211], v[184:187], v[36:39]
	v_mfma_f32_16x16x32_bf16 v[36:39], v[204:207], v[180:183], v[36:39]
	v_mfma_f32_16x16x32_bf16 v[20:23], v[204:207], v[188:191], v[20:23]
	v_mfma_f32_16x16x32_bf16 v[20:23], v[208:211], v[192:195], v[20:23]
	v_mfma_f32_16x16x32_bf16 v[16:19], v[240:243], v[192:195], v[16:19]
	v_mfma_f32_16x16x32_bf16 v[16:19], v[212:215], v[188:191], v[16:19]
	v_mfma_f32_16x16x32_bf16 v[0:3], v[212:215], v[196:199], v[0:3]
	v_mfma_f32_16x16x32_bf16 v[0:3], v[240:243], v[200:203], v[0:3]
	v_mfma_f32_16x16x32_bf16 v[4:7], v[208:211], v[200:203], v[4:7]
	v_mfma_f32_16x16x32_bf16 v[4:7], v[204:207], v[196:199], v[4:7]
	s_setprio 0
	s_add_i32 s42, 0, 0x18000
	v_add_u32_e32 v145, s42, v140
	s_barrier
	ds_read_b128 v[136:139], v145
	v_xor_b32_e32 v157, 64, v145
	ds_read_b128 v[146:149], v157
	ds_read_b128 v[150:153], v145 offset:2048
	ds_read_b128 v[154:157], v157 offset:2048
	s_add_u32 s16, s16, 0x160000
	s_addc_u32 s17, s17, 0
	s_mov_b32 m0, s23
	v_lshl_add_u64 v[204:205], s[16:17], 0, v[168:169]
	ds_read_b128 v[158:161], v142 offset:32768
	v_xor_b32_e32 v203, 64, v142
	ds_read_b128 v[176:179], v203 offset:32768
	ds_read_b128 v[180:183], v142 offset:34816
	ds_read_b128 v[184:187], v203 offset:34816
	ds_read_b128 v[188:191], v142 offset:36864
	ds_read_b128 v[192:195], v203 offset:36864
	ds_read_b128 v[196:199], v142 offset:38912
	ds_read_b128 v[200:203], v203 offset:38912
	global_load_lds_dwordx4 v[204:205], off
	v_lshl_add_u64 v[204:205], s[16:17], 0, v[172:173]
	s_mov_b32 m0, s24
	s_nop 0
	global_load_lds_dwordx4 v[204:205], off
	s_waitcnt lgkmcnt(8)
	s_barrier
	s_waitcnt lgkmcnt(0)
	s_setprio 1
	s_waitcnt lgkmcnt(0)
	v_mfma_f32_16x16x32_bf16 v[124:127], v[136:139], v[158:161], v[124:127]
	v_mfma_f32_16x16x32_bf16 v[124:127], v[146:149], v[176:179], v[124:127]
	v_mfma_f32_16x16x32_bf16 v[120:123], v[154:157], v[176:179], v[120:123]
	v_mfma_f32_16x16x32_bf16 v[120:123], v[150:153], v[158:161], v[120:123]
	v_mfma_f32_16x16x32_bf16 v[104:107], v[150:153], v[180:183], v[104:107]
	v_mfma_f32_16x16x32_bf16 v[104:107], v[154:157], v[184:187], v[104:107]
	v_mfma_f32_16x16x32_bf16 v[108:111], v[146:149], v[184:187], v[108:111]
	v_mfma_f32_16x16x32_bf16 v[108:111], v[136:139], v[180:183], v[108:111]
	v_mfma_f32_16x16x32_bf16 v[92:95], v[136:139], v[188:191], v[92:95]
	v_mfma_f32_16x16x32_bf16 v[92:95], v[146:149], v[192:195], v[92:95]
	v_mfma_f32_16x16x32_bf16 v[88:91], v[154:157], v[192:195], v[88:91]
	v_mfma_f32_16x16x32_bf16 v[88:91], v[150:153], v[188:191], v[88:91]
	v_mfma_f32_16x16x32_bf16 v[72:75], v[150:153], v[196:199], v[72:75]
	v_mfma_f32_16x16x32_bf16 v[72:75], v[154:157], v[200:203], v[72:75]
	v_mfma_f32_16x16x32_bf16 v[76:79], v[146:149], v[200:203], v[76:79]
	v_mfma_f32_16x16x32_bf16 v[76:79], v[136:139], v[196:199], v[76:79]
	s_setprio 0
	s_barrier
	s_add_i32 s16, 0, 0x1c000
	s_add_i32 s17, s42, s20
	v_add_u32_e32 v145, s16, v140
	v_lshl_add_u64 v[216:217], v[216:217], 0, s[4:5]
	s_mov_b32 m0, s17
	ds_read_b128 v[204:207], v145
	v_xor_b32_e32 v243, 64, v145
	ds_read_b128 v[208:211], v243
	ds_read_b128 v[212:215], v145 offset:2048
	ds_read_b128 v[240:243], v243 offset:2048
	global_load_lds_dwordx4 v[216:217], off
	v_lshl_add_u64 v[216:217], v[244:245], 0, s[4:5]
	s_add_i32 m0, s17, 0x2000
	s_nop 0
	global_load_lds_dwordx4 v[216:217], off
	s_barrier
	s_waitcnt lgkmcnt(0)
	s_setprio 1
	s_waitcnt lgkmcnt(0)
	v_mfma_f32_16x16x32_bf16 v[116:119], v[204:207], v[158:161], v[116:119]
	v_mfma_f32_16x16x32_bf16 v[116:119], v[208:211], v[176:179], v[116:119]
	v_mfma_f32_16x16x32_bf16 v[112:115], v[240:243], v[176:179], v[112:115]
	v_mfma_f32_16x16x32_bf16 v[112:115], v[212:215], v[158:161], v[112:115]
	v_mfma_f32_16x16x32_bf16 v[96:99], v[212:215], v[180:183], v[96:99]
	v_mfma_f32_16x16x32_bf16 v[96:99], v[240:243], v[184:187], v[96:99]
	v_mfma_f32_16x16x32_bf16 v[100:103], v[208:211], v[184:187], v[100:103]
	v_mfma_f32_16x16x32_bf16 v[100:103], v[204:207], v[180:183], v[100:103]
	v_mfma_f32_16x16x32_bf16 v[84:87], v[204:207], v[188:191], v[84:87]
	v_mfma_f32_16x16x32_bf16 v[84:87], v[208:211], v[192:195], v[84:87]
	v_mfma_f32_16x16x32_bf16 v[80:83], v[240:243], v[192:195], v[80:83]
	v_mfma_f32_16x16x32_bf16 v[80:83], v[212:215], v[188:191], v[80:83]
	v_mfma_f32_16x16x32_bf16 v[64:67], v[212:215], v[196:199], v[64:67]
	v_mfma_f32_16x16x32_bf16 v[64:67], v[240:243], v[200:203], v[64:67]
	v_mfma_f32_16x16x32_bf16 v[68:71], v[208:211], v[200:203], v[68:71]
	v_mfma_f32_16x16x32_bf16 v[68:71], v[204:207], v[196:199], v[68:71]
	s_setprio 0
	s_mov_b32 m0, s28
	v_lshl_add_u64 v[216:217], v[246:247], 0, s[4:5]
	s_barrier
	ds_read_b128 v[158:161], v142 offset:49152
	v_xor_b32_e32 v203, 64, v142
	ds_read_b128 v[176:179], v203 offset:49152
	ds_read_b128 v[180:183], v142 offset:51200
	ds_read_b128 v[184:187], v203 offset:51200
	ds_read_b128 v[188:191], v142 offset:53248
	ds_read_b128 v[192:195], v203 offset:53248
	ds_read_b128 v[196:199], v142 offset:55296
	ds_read_b128 v[200:203], v203 offset:55296
	global_load_lds_dwordx4 v[216:217], off
	v_lshl_add_u64 v[216:217], v[248:249], 0, s[4:5]
	s_mov_b32 m0, s29
	s_nop 0
	global_load_lds_dwordx4 v[216:217], off
	s_barrier
	s_waitcnt lgkmcnt(0)
	s_setprio 1
	s_waitcnt lgkmcnt(0)
	v_mfma_f32_16x16x32_bf16 v[60:63], v[136:139], v[158:161], v[60:63]
	v_mfma_f32_16x16x32_bf16 v[60:63], v[146:149], v[176:179], v[60:63]
	v_mfma_f32_16x16x32_bf16 v[56:59], v[154:157], v[176:179], v[56:59]
	v_mfma_f32_16x16x32_bf16 v[56:59], v[150:153], v[158:161], v[56:59]
	v_mfma_f32_16x16x32_bf16 v[40:43], v[150:153], v[180:183], v[40:43]
	v_mfma_f32_16x16x32_bf16 v[40:43], v[154:157], v[184:187], v[40:43]
	v_mfma_f32_16x16x32_bf16 v[44:47], v[146:149], v[184:187], v[44:47]
	v_mfma_f32_16x16x32_bf16 v[44:47], v[136:139], v[180:183], v[44:47]
	v_mfma_f32_16x16x32_bf16 v[28:31], v[136:139], v[188:191], v[28:31]
	v_mfma_f32_16x16x32_bf16 v[28:31], v[146:149], v[192:195], v[28:31]
	v_mfma_f32_16x16x32_bf16 v[24:27], v[154:157], v[192:195], v[24:27]
	v_mfma_f32_16x16x32_bf16 v[24:27], v[150:153], v[188:191], v[24:27]
	v_mfma_f32_16x16x32_bf16 v[8:11], v[150:153], v[196:199], v[8:11]
	v_mfma_f32_16x16x32_bf16 v[8:11], v[154:157], v[200:203], v[8:11]
	v_mfma_f32_16x16x32_bf16 v[12:15], v[146:149], v[200:203], v[12:15]
	v_mfma_f32_16x16x32_bf16 v[12:15], v[136:139], v[196:199], v[12:15]
	s_setprio 0
	s_barrier
	s_add_u32 s8, s8, 0x160080
	s_addc_u32 s9, s9, 0
	s_add_i32 s16, s16, s20
	v_lshl_add_u64 v[136:137], s[8:9], 0, v[170:171]
	s_mov_b32 m0, s16
	s_nop 0
	global_load_lds_dwordx4 v[136:137], off
	v_lshl_add_u64 v[136:137], s[8:9], 0, v[174:175]
	s_add_i32 m0, s16, 0x2000
	s_nop 0
	global_load_lds_dwordx4 v[136:137], off
	s_waitcnt vmcnt(6)
	s_barrier
	s_setprio 1
	v_mfma_f32_16x16x32_bf16 v[52:55], v[204:207], v[158:161], v[52:55]
	v_mfma_f32_16x16x32_bf16 v[52:55], v[208:211], v[176:179], v[52:55]
	v_mfma_f32_16x16x32_bf16 v[48:51], v[240:243], v[176:179], v[48:51]
	v_mfma_f32_16x16x32_bf16 v[48:51], v[212:215], v[158:161], v[48:51]
	v_mfma_f32_16x16x32_bf16 v[32:35], v[212:215], v[180:183], v[32:35]
	v_mfma_f32_16x16x32_bf16 v[32:35], v[240:243], v[184:187], v[32:35]
	v_mfma_f32_16x16x32_bf16 v[36:39], v[208:211], v[184:187], v[36:39]
	v_mfma_f32_16x16x32_bf16 v[36:39], v[204:207], v[180:183], v[36:39]
	v_mfma_f32_16x16x32_bf16 v[20:23], v[204:207], v[188:191], v[20:23]
	v_mfma_f32_16x16x32_bf16 v[20:23], v[208:211], v[192:195], v[20:23]
	v_mfma_f32_16x16x32_bf16 v[16:19], v[240:243], v[192:195], v[16:19]
	v_mfma_f32_16x16x32_bf16 v[16:19], v[212:215], v[188:191], v[16:19]
	v_mfma_f32_16x16x32_bf16 v[0:3], v[212:215], v[196:199], v[0:3]
	v_mfma_f32_16x16x32_bf16 v[0:3], v[240:243], v[200:203], v[0:3]
	v_mfma_f32_16x16x32_bf16 v[4:7], v[208:211], v[200:203], v[4:7]
	v_mfma_f32_16x16x32_bf16 v[4:7], v[204:207], v[196:199], v[4:7]
	s_setprio 0
	s_add_i32 s41, s41, 2
	s_add_u32 s0, s0, 0x100
	s_addc_u32 s1, s1, 0
	s_add_u32 s39, s39, 0x100
	s_addc_u32 s40, s40, 0
	s_cmpk_gt_u32 s41, 0x55
	s_barrier
	s_cbranch_scc0 .LBB0_508
	v_lshl_add_u32 v217, s38, 8, v163
	v_add_u32_e32 v217, s26, v217
	v_lshlrev_b32_e32 v208, 2, v217
	v_lshl_add_u32 v214, v225, 3, s27
	v_lshl_add_u32 v214, s37, 8, v214
	v_lshl_add_u32 v209, v217, 11, v214
	v_lshlrev_b32_e32 v209, 1, v209
	v_lshlrev_b32_e32 v210, 1, v209
	v_lshl_add_u32 v217, v225, 4, v163
	v_xor_b32_e32 v215, 16, v217
	v_lshlrev_b32_e32 v215, 2, v215
	v_xor_b32_e32 v216, 32, v217
	v_lshlrev_b32_e32 v216, 2, v216
	v_add_u32_e32 v211, 0x0, v209
	global_load_dwordx4 v[176:179], v211, s[80:81]
	global_load_dwordx4 v[180:183], v211, s[80:81] offset:256
	v_add_u32_e32 v211, 0x10000, v209
	global_load_dwordx4 v[192:195], v211, s[80:81]
	global_load_dwordx4 v[196:199], v211, s[80:81] offset:256
	s_waitcnt vmcnt(2)
	v_lshlrev_b32_e32 v184, 16, v176
	v_and_b32_e32 v185, 0xffff0000, v176
	v_lshlrev_b32_e32 v186, 16, v177
	v_and_b32_e32 v187, 0xffff0000, v177
	v_lshlrev_b32_e32 v188, 16, v178
	v_and_b32_e32 v189, 0xffff0000, v178
	v_lshlrev_b32_e32 v190, 16, v179
	v_and_b32_e32 v191, 0xffff0000, v179
	v_pk_add_f32 v[124:125], v[124:125], v[184:185]
	v_pk_add_f32 v[126:127], v[126:127], v[186:187]
	v_pk_add_f32 v[120:121], v[120:121], v[188:189]
	v_pk_add_f32 v[122:123], v[122:123], v[190:191]
	v_mul_f32_e32 v213, v124, v124
	v_fmac_f32_e32 v213, v125, v125
	v_fmac_f32_e32 v213, v126, v126
	v_fmac_f32_e32 v213, v127, v127
	v_fmac_f32_e32 v213, v120, v120
	v_fmac_f32_e32 v213, v121, v121
	v_fmac_f32_e32 v213, v122, v122
	v_fmac_f32_e32 v213, v123, v123
	v_cvt_pk_bf16_f32 v176, v124, v125
	v_cvt_pk_bf16_f32 v177, v126, v127
	v_cvt_pk_bf16_f32 v178, v120, v121
	v_cvt_pk_bf16_f32 v179, v122, v123
	v_add_u32_e32 v217, 0x0, v209
	global_store_dwordx4 v217, v[176:179], s[80:81]
	v_lshlrev_b32_e32 v184, 16, v180
	v_and_b32_e32 v185, 0xffff0000, v180
	v_lshlrev_b32_e32 v186, 16, v181
	v_and_b32_e32 v187, 0xffff0000, v181
	v_lshlrev_b32_e32 v188, 16, v182
	v_and_b32_e32 v189, 0xffff0000, v182
	v_lshlrev_b32_e32 v190, 16, v183
	v_and_b32_e32 v191, 0xffff0000, v183
	v_pk_add_f32 v[116:117], v[116:117], v[184:185]
	v_pk_add_f32 v[118:119], v[118:119], v[186:187]
	v_pk_add_f32 v[112:113], v[112:113], v[188:189]
	v_pk_add_f32 v[114:115], v[114:115], v[190:191]
	v_fmac_f32_e32 v213, v116, v116
	v_fmac_f32_e32 v213, v117, v117
	v_fmac_f32_e32 v213, v118, v118
	v_fmac_f32_e32 v213, v119, v119
	v_fmac_f32_e32 v213, v112, v112
	v_fmac_f32_e32 v213, v113, v113
	v_fmac_f32_e32 v213, v114, v114
	v_fmac_f32_e32 v213, v115, v115
	v_cvt_pk_bf16_f32 v180, v116, v117
	v_cvt_pk_bf16_f32 v181, v118, v119
	v_cvt_pk_bf16_f32 v182, v112, v113
	v_cvt_pk_bf16_f32 v183, v114, v115
	global_store_dwordx4 v217, v[180:183], s[80:81] offset:256
	ds_bpermute_b32 v214, v215, v213
	s_waitcnt lgkmcnt(0)
	v_add_f32_e32 v213, v213, v214
	ds_bpermute_b32 v214, v216, v213
	s_waitcnt lgkmcnt(0)
	v_add_f32_e32 v213, v213, v214
	s_mov_b64 exec, 0xffff
	global_atomic_add_f32 v208, v213, s[14:15]
	s_mov_b64 exec, -1
	v_add_u32_e32 v211, 0x20000, v209
	global_load_dwordx4 v[176:179], v211, s[80:81]
	global_load_dwordx4 v[180:183], v211, s[80:81] offset:256
	s_waitcnt vmcnt(5)
	v_lshlrev_b32_e32 v200, 16, v192
	v_and_b32_e32 v201, 0xffff0000, v192
	v_lshlrev_b32_e32 v202, 16, v193
	v_and_b32_e32 v203, 0xffff0000, v193
	v_lshlrev_b32_e32 v204, 16, v194
	v_and_b32_e32 v205, 0xffff0000, v194
	v_lshlrev_b32_e32 v206, 16, v195
	v_and_b32_e32 v207, 0xffff0000, v195
	v_pk_add_f32 v[108:109], v[108:109], v[200:201]
	v_pk_add_f32 v[110:111], v[110:111], v[202:203]
	v_pk_add_f32 v[104:105], v[104:105], v[204:205]
	v_pk_add_f32 v[106:107], v[106:107], v[206:207]
	v_mul_f32_e32 v213, v108, v108
	v_fmac_f32_e32 v213, v109, v109
	v_fmac_f32_e32 v213, v110, v110
	v_fmac_f32_e32 v213, v111, v111
	v_fmac_f32_e32 v213, v104, v104
	v_fmac_f32_e32 v213, v105, v105
	v_fmac_f32_e32 v213, v106, v106
	v_fmac_f32_e32 v213, v107, v107
	v_cvt_pk_bf16_f32 v192, v108, v109
	v_cvt_pk_bf16_f32 v193, v110, v111
	v_cvt_pk_bf16_f32 v194, v104, v105
	v_cvt_pk_bf16_f32 v195, v106, v107
	v_add_u32_e32 v217, 0x10000, v209
	global_store_dwordx4 v217, v[192:195], s[80:81]
	v_lshlrev_b32_e32 v200, 16, v196
	v_and_b32_e32 v201, 0xffff0000, v196
	v_lshlrev_b32_e32 v202, 16, v197
	v_and_b32_e32 v203, 0xffff0000, v197
	v_lshlrev_b32_e32 v204, 16, v198
	v_and_b32_e32 v205, 0xffff0000, v198
	v_lshlrev_b32_e32 v206, 16, v199
	v_and_b32_e32 v207, 0xffff0000, v199
	v_pk_add_f32 v[100:101], v[100:101], v[200:201]
	v_pk_add_f32 v[102:103], v[102:103], v[202:203]
	v_pk_add_f32 v[96:97], v[96:97], v[204:205]
	v_pk_add_f32 v[98:99], v[98:99], v[206:207]
	v_fmac_f32_e32 v213, v100, v100
	v_fmac_f32_e32 v213, v101, v101
	v_fmac_f32_e32 v213, v102, v102
	v_fmac_f32_e32 v213, v103, v103
	v_fmac_f32_e32 v213, v96, v96
	v_fmac_f32_e32 v213, v97, v97
	v_fmac_f32_e32 v213, v98, v98
	v_fmac_f32_e32 v213, v99, v99
	v_cvt_pk_bf16_f32 v196, v100, v101
	v_cvt_pk_bf16_f32 v197, v102, v103
	v_cvt_pk_bf16_f32 v198, v96, v97
	v_cvt_pk_bf16_f32 v199, v98, v99
	global_store_dwordx4 v217, v[196:199], s[80:81] offset:256
	ds_bpermute_b32 v214, v215, v213
	s_waitcnt lgkmcnt(0)
	v_add_f32_e32 v213, v213, v214
	ds_bpermute_b32 v214, v216, v213
	s_waitcnt lgkmcnt(0)
	v_add_f32_e32 v213, v213, v214
	s_mov_b64 exec, 0xffff
	global_atomic_add_f32 v208, v213, s[14:15] offset:64
	s_mov_b64 exec, -1
	v_add_u32_e32 v211, 0x30000, v209
	global_load_dwordx4 v[192:195], v211, s[80:81]
	global_load_dwordx4 v[196:199], v211, s[80:81] offset:256
	s_waitcnt vmcnt(5)
	v_lshlrev_b32_e32 v184, 16, v176
	v_and_b32_e32 v185, 0xffff0000, v176
	v_lshlrev_b32_e32 v186, 16, v177
	v_and_b32_e32 v187, 0xffff0000, v177
	v_lshlrev_b32_e32 v188, 16, v178
	v_and_b32_e32 v189, 0xffff0000, v178
	v_lshlrev_b32_e32 v190, 16, v179
	v_and_b32_e32 v191, 0xffff0000, v179
	v_pk_add_f32 v[92:93], v[92:93], v[184:185]
	v_pk_add_f32 v[94:95], v[94:95], v[186:187]
	v_pk_add_f32 v[88:89], v[88:89], v[188:189]
	v_pk_add_f32 v[90:91], v[90:91], v[190:191]
	v_mul_f32_e32 v213, v92, v92
	v_fmac_f32_e32 v213, v93, v93
	v_fmac_f32_e32 v213, v94, v94
	v_fmac_f32_e32 v213, v95, v95
	v_fmac_f32_e32 v213, v88, v88
	v_fmac_f32_e32 v213, v89, v89
	v_fmac_f32_e32 v213, v90, v90
	v_fmac_f32_e32 v213, v91, v91
	v_cvt_pk_bf16_f32 v176, v92, v93
	v_cvt_pk_bf16_f32 v177, v94, v95
	v_cvt_pk_bf16_f32 v178, v88, v89
	v_cvt_pk_bf16_f32 v179, v90, v91
	v_add_u32_e32 v217, 0x20000, v209
	global_store_dwordx4 v217, v[176:179], s[80:81]
	v_lshlrev_b32_e32 v184, 16, v180
	v_and_b32_e32 v185, 0xffff0000, v180
	v_lshlrev_b32_e32 v186, 16, v181
	v_and_b32_e32 v187, 0xffff0000, v181
	v_lshlrev_b32_e32 v188, 16, v182
	v_and_b32_e32 v189, 0xffff0000, v182
	v_lshlrev_b32_e32 v190, 16, v183
	v_and_b32_e32 v191, 0xffff0000, v183
	v_pk_add_f32 v[84:85], v[84:85], v[184:185]
	v_pk_add_f32 v[86:87], v[86:87], v[186:187]
	v_pk_add_f32 v[80:81], v[80:81], v[188:189]
	v_pk_add_f32 v[82:83], v[82:83], v[190:191]
	v_fmac_f32_e32 v213, v84, v84
	v_fmac_f32_e32 v213, v85, v85
	v_fmac_f32_e32 v213, v86, v86
	v_fmac_f32_e32 v213, v87, v87
	v_fmac_f32_e32 v213, v80, v80
	v_fmac_f32_e32 v213, v81, v81
	v_fmac_f32_e32 v213, v82, v82
	v_fmac_f32_e32 v213, v83, v83
	v_cvt_pk_bf16_f32 v180, v84, v85
	v_cvt_pk_bf16_f32 v181, v86, v87
	v_cvt_pk_bf16_f32 v182, v80, v81
	v_cvt_pk_bf16_f32 v183, v82, v83
	global_store_dwordx4 v217, v[180:183], s[80:81] offset:256
	ds_bpermute_b32 v214, v215, v213
	s_waitcnt lgkmcnt(0)
	v_add_f32_e32 v213, v213, v214
	ds_bpermute_b32 v214, v216, v213
	s_waitcnt lgkmcnt(0)
	v_add_f32_e32 v213, v213, v214
	s_mov_b64 exec, 0xffff
	global_atomic_add_f32 v208, v213, s[14:15] offset:128
	s_mov_b64 exec, -1
	v_add_u32_e32 v211, 0x80000, v209
	global_load_dwordx4 v[176:179], v211, s[80:81]
	global_load_dwordx4 v[180:183], v211, s[80:81] offset:256
	s_waitcnt vmcnt(5)
	v_lshlrev_b32_e32 v200, 16, v192
	v_and_b32_e32 v201, 0xffff0000, v192
	v_lshlrev_b32_e32 v202, 16, v193
	v_and_b32_e32 v203, 0xffff0000, v193
	v_lshlrev_b32_e32 v204, 16, v194
	v_and_b32_e32 v205, 0xffff0000, v194
	v_lshlrev_b32_e32 v206, 16, v195
	v_and_b32_e32 v207, 0xffff0000, v195
	v_pk_add_f32 v[76:77], v[76:77], v[200:201]
	v_pk_add_f32 v[78:79], v[78:79], v[202:203]
	v_pk_add_f32 v[72:73], v[72:73], v[204:205]
	v_pk_add_f32 v[74:75], v[74:75], v[206:207]
	v_mul_f32_e32 v213, v76, v76
	v_fmac_f32_e32 v213, v77, v77
	v_fmac_f32_e32 v213, v78, v78
	v_fmac_f32_e32 v213, v79, v79
	v_fmac_f32_e32 v213, v72, v72
	v_fmac_f32_e32 v213, v73, v73
	v_fmac_f32_e32 v213, v74, v74
	v_fmac_f32_e32 v213, v75, v75
	v_cvt_pk_bf16_f32 v192, v76, v77
	v_cvt_pk_bf16_f32 v193, v78, v79
	v_cvt_pk_bf16_f32 v194, v72, v73
	v_cvt_pk_bf16_f32 v195, v74, v75
	v_add_u32_e32 v217, 0x30000, v209
	global_store_dwordx4 v217, v[192:195], s[80:81]
	v_lshlrev_b32_e32 v200, 16, v196
	v_and_b32_e32 v201, 0xffff0000, v196
	v_lshlrev_b32_e32 v202, 16, v197
	v_and_b32_e32 v203, 0xffff0000, v197
	v_lshlrev_b32_e32 v204, 16, v198
	v_and_b32_e32 v205, 0xffff0000, v198
	v_lshlrev_b32_e32 v206, 16, v199
	v_and_b32_e32 v207, 0xffff0000, v199
	v_pk_add_f32 v[68:69], v[68:69], v[200:201]
	v_pk_add_f32 v[70:71], v[70:71], v[202:203]
	v_pk_add_f32 v[64:65], v[64:65], v[204:205]
	v_pk_add_f32 v[66:67], v[66:67], v[206:207]
	v_fmac_f32_e32 v213, v68, v68
	v_fmac_f32_e32 v213, v69, v69
	v_fmac_f32_e32 v213, v70, v70
	v_fmac_f32_e32 v213, v71, v71
	v_fmac_f32_e32 v213, v64, v64
	v_fmac_f32_e32 v213, v65, v65
	v_fmac_f32_e32 v213, v66, v66
	v_fmac_f32_e32 v213, v67, v67
	v_cvt_pk_bf16_f32 v196, v68, v69
	v_cvt_pk_bf16_f32 v197, v70, v71
	v_cvt_pk_bf16_f32 v198, v64, v65
	v_cvt_pk_bf16_f32 v199, v66, v67
	global_store_dwordx4 v217, v[196:199], s[80:81] offset:256
	ds_bpermute_b32 v214, v215, v213
	s_waitcnt lgkmcnt(0)
	v_add_f32_e32 v213, v213, v214
	ds_bpermute_b32 v214, v216, v213
	s_waitcnt lgkmcnt(0)
	v_add_f32_e32 v213, v213, v214
	s_mov_b64 exec, 0xffff
	global_atomic_add_f32 v208, v213, s[14:15] offset:192
	s_mov_b64 exec, -1
	v_add_u32_e32 v211, 0x90000, v209
	global_load_dwordx4 v[192:195], v211, s[80:81]
	global_load_dwordx4 v[196:199], v211, s[80:81] offset:256
	s_waitcnt vmcnt(5)
	v_lshlrev_b32_e32 v184, 16, v176
	v_and_b32_e32 v185, 0xffff0000, v176
	v_lshlrev_b32_e32 v186, 16, v177
	v_and_b32_e32 v187, 0xffff0000, v177
	v_lshlrev_b32_e32 v188, 16, v178
	v_and_b32_e32 v189, 0xffff0000, v178
	v_lshlrev_b32_e32 v190, 16, v179
	v_and_b32_e32 v191, 0xffff0000, v179
	v_pk_add_f32 v[60:61], v[60:61], v[184:185]
	v_pk_add_f32 v[62:63], v[62:63], v[186:187]
	v_pk_add_f32 v[56:57], v[56:57], v[188:189]
	v_pk_add_f32 v[58:59], v[58:59], v[190:191]
	v_mul_f32_e32 v213, v60, v60
	v_fmac_f32_e32 v213, v61, v61
	v_fmac_f32_e32 v213, v62, v62
	v_fmac_f32_e32 v213, v63, v63
	v_fmac_f32_e32 v213, v56, v56
	v_fmac_f32_e32 v213, v57, v57
	v_fmac_f32_e32 v213, v58, v58
	v_fmac_f32_e32 v213, v59, v59
	v_cvt_pk_bf16_f32 v176, v60, v61
	v_cvt_pk_bf16_f32 v177, v62, v63
	v_cvt_pk_bf16_f32 v178, v56, v57
	v_cvt_pk_bf16_f32 v179, v58, v59
	v_add_u32_e32 v217, 0x80000, v209
	global_store_dwordx4 v217, v[176:179], s[80:81]
	v_lshlrev_b32_e32 v184, 16, v180
	v_and_b32_e32 v185, 0xffff0000, v180
	v_lshlrev_b32_e32 v186, 16, v181
	v_and_b32_e32 v187, 0xffff0000, v181
	v_lshlrev_b32_e32 v188, 16, v182
	v_and_b32_e32 v189, 0xffff0000, v182
	v_lshlrev_b32_e32 v190, 16, v183
	v_and_b32_e32 v191, 0xffff0000, v183
	v_pk_add_f32 v[52:53], v[52:53], v[184:185]
	v_pk_add_f32 v[54:55], v[54:55], v[186:187]
	v_pk_add_f32 v[48:49], v[48:49], v[188:189]
	v_pk_add_f32 v[50:51], v[50:51], v[190:191]
	v_fmac_f32_e32 v213, v52, v52
	v_fmac_f32_e32 v213, v53, v53
	v_fmac_f32_e32 v213, v54, v54
	v_fmac_f32_e32 v213, v55, v55
	v_fmac_f32_e32 v213, v48, v48
	v_fmac_f32_e32 v213, v49, v49
	v_fmac_f32_e32 v213, v50, v50
	v_fmac_f32_e32 v213, v51, v51
	v_cvt_pk_bf16_f32 v180, v52, v53
	v_cvt_pk_bf16_f32 v181, v54, v55
	v_cvt_pk_bf16_f32 v182, v48, v49
	v_cvt_pk_bf16_f32 v183, v50, v51
	global_store_dwordx4 v217, v[180:183], s[80:81] offset:256
	ds_bpermute_b32 v214, v215, v213
	s_waitcnt lgkmcnt(0)
	v_add_f32_e32 v213, v213, v214
	ds_bpermute_b32 v214, v216, v213
	s_waitcnt lgkmcnt(0)
	v_add_f32_e32 v213, v213, v214
	s_mov_b64 exec, 0xffff
	global_atomic_add_f32 v208, v213, s[14:15] offset:512
	s_mov_b64 exec, -1
	v_add_u32_e32 v211, 0xa0000, v209
	global_load_dwordx4 v[176:179], v211, s[80:81]
	global_load_dwordx4 v[180:183], v211, s[80:81] offset:256
	s_waitcnt vmcnt(5)
	v_lshlrev_b32_e32 v200, 16, v192
	v_and_b32_e32 v201, 0xffff0000, v192
	v_lshlrev_b32_e32 v202, 16, v193
	v_and_b32_e32 v203, 0xffff0000, v193
	v_lshlrev_b32_e32 v204, 16, v194
	v_and_b32_e32 v205, 0xffff0000, v194
	v_lshlrev_b32_e32 v206, 16, v195
	v_and_b32_e32 v207, 0xffff0000, v195
	v_pk_add_f32 v[44:45], v[44:45], v[200:201]
	v_pk_add_f32 v[46:47], v[46:47], v[202:203]
	v_pk_add_f32 v[40:41], v[40:41], v[204:205]
	v_pk_add_f32 v[42:43], v[42:43], v[206:207]
	v_mul_f32_e32 v213, v44, v44
	v_fmac_f32_e32 v213, v45, v45
	v_fmac_f32_e32 v213, v46, v46
	v_fmac_f32_e32 v213, v47, v47
	v_fmac_f32_e32 v213, v40, v40
	v_fmac_f32_e32 v213, v41, v41
	v_fmac_f32_e32 v213, v42, v42
	v_fmac_f32_e32 v213, v43, v43
	v_cvt_pk_bf16_f32 v192, v44, v45
	v_cvt_pk_bf16_f32 v193, v46, v47
	v_cvt_pk_bf16_f32 v194, v40, v41
	v_cvt_pk_bf16_f32 v195, v42, v43
	v_add_u32_e32 v217, 0x90000, v209
	global_store_dwordx4 v217, v[192:195], s[80:81]
	v_lshlrev_b32_e32 v200, 16, v196
	v_and_b32_e32 v201, 0xffff0000, v196
	v_lshlrev_b32_e32 v202, 16, v197
	v_and_b32_e32 v203, 0xffff0000, v197
	v_lshlrev_b32_e32 v204, 16, v198
	v_and_b32_e32 v205, 0xffff0000, v198
	v_lshlrev_b32_e32 v206, 16, v199
	v_and_b32_e32 v207, 0xffff0000, v199
	v_pk_add_f32 v[36:37], v[36:37], v[200:201]
	v_pk_add_f32 v[38:39], v[38:39], v[202:203]
	v_pk_add_f32 v[32:33], v[32:33], v[204:205]
	v_pk_add_f32 v[34:35], v[34:35], v[206:207]
	v_fmac_f32_e32 v213, v36, v36
	v_fmac_f32_e32 v213, v37, v37
	v_fmac_f32_e32 v213, v38, v38
	v_fmac_f32_e32 v213, v39, v39
	v_fmac_f32_e32 v213, v32, v32
	v_fmac_f32_e32 v213, v33, v33
	v_fmac_f32_e32 v213, v34, v34
	v_fmac_f32_e32 v213, v35, v35
	v_cvt_pk_bf16_f32 v196, v36, v37
	v_cvt_pk_bf16_f32 v197, v38, v39
	v_cvt_pk_bf16_f32 v198, v32, v33
	v_cvt_pk_bf16_f32 v199, v34, v35
	global_store_dwordx4 v217, v[196:199], s[80:81] offset:256
	ds_bpermute_b32 v214, v215, v213
	s_waitcnt lgkmcnt(0)
	v_add_f32_e32 v213, v213, v214
	ds_bpermute_b32 v214, v216, v213
	s_waitcnt lgkmcnt(0)
	v_add_f32_e32 v213, v213, v214
	s_mov_b64 exec, 0xffff
	global_atomic_add_f32 v208, v213, s[14:15] offset:576
	s_mov_b64 exec, -1
	v_add_u32_e32 v211, 0xb0000, v209
	global_load_dwordx4 v[192:195], v211, s[80:81]
	global_load_dwordx4 v[196:199], v211, s[80:81] offset:256
	s_waitcnt vmcnt(5)
	v_lshlrev_b32_e32 v184, 16, v176
	v_and_b32_e32 v185, 0xffff0000, v176
	v_lshlrev_b32_e32 v186, 16, v177
	v_and_b32_e32 v187, 0xffff0000, v177
	v_lshlrev_b32_e32 v188, 16, v178
	v_and_b32_e32 v189, 0xffff0000, v178
	v_lshlrev_b32_e32 v190, 16, v179
	v_and_b32_e32 v191, 0xffff0000, v179
	v_pk_add_f32 v[28:29], v[28:29], v[184:185]
	v_pk_add_f32 v[30:31], v[30:31], v[186:187]
	v_pk_add_f32 v[24:25], v[24:25], v[188:189]
	v_pk_add_f32 v[26:27], v[26:27], v[190:191]
	v_mul_f32_e32 v213, v28, v28
	v_fmac_f32_e32 v213, v29, v29
	v_fmac_f32_e32 v213, v30, v30
	v_fmac_f32_e32 v213, v31, v31
	v_fmac_f32_e32 v213, v24, v24
	v_fmac_f32_e32 v213, v25, v25
	v_fmac_f32_e32 v213, v26, v26
	v_fmac_f32_e32 v213, v27, v27
	v_cvt_pk_bf16_f32 v176, v28, v29
	v_cvt_pk_bf16_f32 v177, v30, v31
	v_cvt_pk_bf16_f32 v178, v24, v25
	v_cvt_pk_bf16_f32 v179, v26, v27
	v_add_u32_e32 v217, 0xa0000, v209
	global_store_dwordx4 v217, v[176:179], s[80:81]
	v_lshlrev_b32_e32 v184, 16, v180
	v_and_b32_e32 v185, 0xffff0000, v180
	v_lshlrev_b32_e32 v186, 16, v181
	v_and_b32_e32 v187, 0xffff0000, v181
	v_lshlrev_b32_e32 v188, 16, v182
	v_and_b32_e32 v189, 0xffff0000, v182
	v_lshlrev_b32_e32 v190, 16, v183
	v_and_b32_e32 v191, 0xffff0000, v183
	v_pk_add_f32 v[20:21], v[20:21], v[184:185]
	v_pk_add_f32 v[22:23], v[22:23], v[186:187]
	v_pk_add_f32 v[16:17], v[16:17], v[188:189]
	v_pk_add_f32 v[18:19], v[18:19], v[190:191]
	v_fmac_f32_e32 v213, v20, v20
	v_fmac_f32_e32 v213, v21, v21
	v_fmac_f32_e32 v213, v22, v22
	v_fmac_f32_e32 v213, v23, v23
	v_fmac_f32_e32 v213, v16, v16
	v_fmac_f32_e32 v213, v17, v17
	v_fmac_f32_e32 v213, v18, v18
	v_fmac_f32_e32 v213, v19, v19
	v_cvt_pk_bf16_f32 v180, v20, v21
	v_cvt_pk_bf16_f32 v181, v22, v23
	v_cvt_pk_bf16_f32 v182, v16, v17
	v_cvt_pk_bf16_f32 v183, v18, v19
	global_store_dwordx4 v217, v[180:183], s[80:81] offset:256
	ds_bpermute_b32 v214, v215, v213
	s_waitcnt lgkmcnt(0)
	v_add_f32_e32 v213, v213, v214
	ds_bpermute_b32 v214, v216, v213
	s_waitcnt lgkmcnt(0)
	v_add_f32_e32 v213, v213, v214
	s_mov_b64 exec, 0xffff
	global_atomic_add_f32 v208, v213, s[14:15] offset:640
	s_mov_b64 exec, -1
	s_waitcnt vmcnt(3)
	v_lshlrev_b32_e32 v200, 16, v192
	v_and_b32_e32 v201, 0xffff0000, v192
	v_lshlrev_b32_e32 v202, 16, v193
	v_and_b32_e32 v203, 0xffff0000, v193
	v_lshlrev_b32_e32 v204, 16, v194
	v_and_b32_e32 v205, 0xffff0000, v194
	v_lshlrev_b32_e32 v206, 16, v195
	v_and_b32_e32 v207, 0xffff0000, v195
	v_pk_add_f32 v[12:13], v[12:13], v[200:201]
	v_pk_add_f32 v[14:15], v[14:15], v[202:203]
	v_pk_add_f32 v[8:9], v[8:9], v[204:205]
	v_pk_add_f32 v[10:11], v[10:11], v[206:207]
	v_mul_f32_e32 v213, v12, v12
	v_fmac_f32_e32 v213, v13, v13
	v_fmac_f32_e32 v213, v14, v14
	v_fmac_f32_e32 v213, v15, v15
	v_fmac_f32_e32 v213, v8, v8
	v_fmac_f32_e32 v213, v9, v9
	v_fmac_f32_e32 v213, v10, v10
	v_fmac_f32_e32 v213, v11, v11
	v_cvt_pk_bf16_f32 v192, v12, v13
	v_cvt_pk_bf16_f32 v193, v14, v15
	v_cvt_pk_bf16_f32 v194, v8, v9
	v_cvt_pk_bf16_f32 v195, v10, v11
	v_add_u32_e32 v217, 0xb0000, v209
	global_store_dwordx4 v217, v[192:195], s[80:81]
	v_lshlrev_b32_e32 v200, 16, v196
	v_and_b32_e32 v201, 0xffff0000, v196
	v_lshlrev_b32_e32 v202, 16, v197
	v_and_b32_e32 v203, 0xffff0000, v197
	v_lshlrev_b32_e32 v204, 16, v198
	v_and_b32_e32 v205, 0xffff0000, v198
	v_lshlrev_b32_e32 v206, 16, v199
	v_and_b32_e32 v207, 0xffff0000, v199
	v_pk_add_f32 v[4:5], v[4:5], v[200:201]
	v_pk_add_f32 v[6:7], v[6:7], v[202:203]
	v_pk_add_f32 v[0:1], v[0:1], v[204:205]
	v_pk_add_f32 v[2:3], v[2:3], v[206:207]
	v_fmac_f32_e32 v213, v4, v4
	v_fmac_f32_e32 v213, v5, v5
	v_fmac_f32_e32 v213, v6, v6
	v_fmac_f32_e32 v213, v7, v7
	v_fmac_f32_e32 v213, v0, v0
	v_fmac_f32_e32 v213, v1, v1
	v_fmac_f32_e32 v213, v2, v2
	v_fmac_f32_e32 v213, v3, v3
	v_cvt_pk_bf16_f32 v196, v4, v5
	v_cvt_pk_bf16_f32 v197, v6, v7
	v_cvt_pk_bf16_f32 v198, v0, v1
	v_cvt_pk_bf16_f32 v199, v2, v3
	global_store_dwordx4 v217, v[196:199], s[80:81] offset:256
	ds_bpermute_b32 v214, v215, v213
	s_waitcnt lgkmcnt(0)
	v_add_f32_e32 v213, v213, v214
	ds_bpermute_b32 v214, v216, v213
	s_waitcnt lgkmcnt(0)
	v_add_f32_e32 v213, v213, v214
	s_mov_b64 exec, 0xffff
	global_atomic_add_f32 v208, v213, s[14:15] offset:704
	s_mov_b64 exec, -1
	s_branch .LBB0_496

.LBB0_599:
	ds_read_b128 v[140:143], v149
	v_xor_b32_e32 v179, 64, v149
	ds_read_b128 v[154:157], v179
	ds_read_b128 v[158:161], v149 offset:2048
	ds_read_b128 v[176:179], v179 offset:2048
	s_add_u32 s28, s26, 0xfff80080
	s_addc_u32 s29, s27, -1
	s_cmp_eq_u32 s49, 28
	s_cselect_b32 s31, s1, s29
	s_cselect_b32 s30, s13, s28
	s_cselect_b32 s29, s19, s48
	s_cselect_b32 s28, s21, s33
	v_lshl_add_u64 v[144:145], s[26:27], 0, v[132:133]
	s_add_i32 m0, s37, 0xc000
	ds_read_b128 v[180:183], v150
	v_xor_b32_e32 v211, 64, v150
	ds_read_b128 v[184:187], v211
	ds_read_b128 v[188:191], v150 offset:2048
	ds_read_b128 v[192:195], v211 offset:2048
	ds_read_b128 v[196:199], v150 offset:4096
	ds_read_b128 v[200:203], v211 offset:4096
	ds_read_b128 v[204:207], v150 offset:6144
	ds_read_b128 v[208:211], v211 offset:6144
	global_load_lds_dwordx4 v[144:145], off
	v_lshl_add_u64 v[144:145], s[26:27], 0, v[134:135]
	s_add_i32 m0, s37, 0xe000
	s_nop 0
	global_load_lds_dwordx4 v[144:145], off
	s_waitcnt lgkmcnt(8)
	s_barrier
	s_waitcnt lgkmcnt(0)
	s_setprio 1
	s_waitcnt lgkmcnt(0)
	v_mfma_f32_16x16x32_bf16 v[124:127], v[140:143], v[180:183], v[124:127]
	v_mfma_f32_16x16x32_bf16 v[124:127], v[154:157], v[184:187], v[124:127]
	v_mfma_f32_16x16x32_bf16 v[120:123], v[176:179], v[184:187], v[120:123]
	v_mfma_f32_16x16x32_bf16 v[120:123], v[158:161], v[180:183], v[120:123]
	v_mfma_f32_16x16x32_bf16 v[104:107], v[158:161], v[188:191], v[104:107]
	v_mfma_f32_16x16x32_bf16 v[104:107], v[176:179], v[192:195], v[104:107]
	v_mfma_f32_16x16x32_bf16 v[108:111], v[154:157], v[192:195], v[108:111]
	v_mfma_f32_16x16x32_bf16 v[108:111], v[140:143], v[188:191], v[108:111]
	v_mfma_f32_16x16x32_bf16 v[92:95], v[140:143], v[196:199], v[92:95]
	v_mfma_f32_16x16x32_bf16 v[92:95], v[154:157], v[200:203], v[92:95]
	v_mfma_f32_16x16x32_bf16 v[88:91], v[176:179], v[200:203], v[88:91]
	v_mfma_f32_16x16x32_bf16 v[88:91], v[158:161], v[196:199], v[88:91]
	v_mfma_f32_16x16x32_bf16 v[72:75], v[158:161], v[204:207], v[72:75]
	v_mfma_f32_16x16x32_bf16 v[72:75], v[176:179], v[208:211], v[72:75]
	v_mfma_f32_16x16x32_bf16 v[76:79], v[154:157], v[208:211], v[76:79]
	v_mfma_f32_16x16x32_bf16 v[76:79], v[140:143], v[204:207], v[76:79]
	s_setprio 0
	s_barrier
	s_add_i32 s52, s46, s36
	v_lshl_add_u64 v[144:145], s[28:29], 0, v[164:165]
	s_mov_b32 m0, s52
	ds_read_b128 v[212:215], v151
	v_xor_b32_e32 v251, 64, v151
	ds_read_b128 v[240:243], v251
	ds_read_b128 v[244:247], v151 offset:2048
	ds_read_b128 v[248:251], v251 offset:2048
	global_load_lds_dwordx4 v[144:145], off
	v_lshl_add_u64 v[216:217], s[28:29], 0, v[166:167]
	s_add_i32 m0, s52, 0x2000
	s_nop 0
	global_load_lds_dwordx4 v[216:217], off
	s_barrier
	s_waitcnt lgkmcnt(0)
	s_setprio 1
	s_waitcnt lgkmcnt(0)
	v_mfma_f32_16x16x32_bf16 v[116:119], v[212:215], v[180:183], v[116:119]
	v_mfma_f32_16x16x32_bf16 v[116:119], v[240:243], v[184:187], v[116:119]
	v_mfma_f32_16x16x32_bf16 v[112:115], v[248:251], v[184:187], v[112:115]
	v_mfma_f32_16x16x32_bf16 v[112:115], v[244:247], v[180:183], v[112:115]
	v_mfma_f32_16x16x32_bf16 v[96:99], v[244:247], v[188:191], v[96:99]
	v_mfma_f32_16x16x32_bf16 v[96:99], v[248:251], v[192:195], v[96:99]
	v_mfma_f32_16x16x32_bf16 v[100:103], v[240:243], v[192:195], v[100:103]
	v_mfma_f32_16x16x32_bf16 v[100:103], v[212:215], v[188:191], v[100:103]
	v_mfma_f32_16x16x32_bf16 v[84:87], v[212:215], v[196:199], v[84:87]
	v_mfma_f32_16x16x32_bf16 v[84:87], v[240:243], v[200:203], v[84:87]
	v_mfma_f32_16x16x32_bf16 v[80:83], v[248:251], v[200:203], v[80:83]
	v_mfma_f32_16x16x32_bf16 v[80:83], v[244:247], v[196:199], v[80:83]
	v_mfma_f32_16x16x32_bf16 v[64:67], v[244:247], v[204:207], v[64:67]
	v_mfma_f32_16x16x32_bf16 v[64:67], v[248:251], v[208:211], v[64:67]
	v_mfma_f32_16x16x32_bf16 v[68:71], v[240:243], v[208:211], v[68:71]
	v_mfma_f32_16x16x32_bf16 v[68:71], v[212:215], v[204:207], v[68:71]
	s_setprio 0
	s_mov_b32 m0, s37
	v_lshl_add_u64 v[252:253], s[30:31], 0, v[128:129]
	s_barrier
	ds_read_b128 v[180:183], v150 offset:16384
	v_xor_b32_e32 v211, 64, v150
	ds_read_b128 v[184:187], v211 offset:16384
	ds_read_b128 v[188:191], v150 offset:18432
	ds_read_b128 v[192:195], v211 offset:18432
	ds_read_b128 v[196:199], v150 offset:20480
	ds_read_b128 v[200:203], v211 offset:20480
	ds_read_b128 v[204:207], v150 offset:22528
	ds_read_b128 v[208:211], v211 offset:22528
	global_load_lds_dwordx4 v[252:253], off
	v_lshl_add_u64 v[234:235], s[30:31], 0, v[130:131]
	s_mov_b32 m0, s38
	s_nop 0
	global_load_lds_dwordx4 v[234:235], off
	s_barrier
	s_waitcnt lgkmcnt(0)
	s_setprio 1
	s_waitcnt lgkmcnt(0)
	v_mfma_f32_16x16x32_bf16 v[60:63], v[140:143], v[180:183], v[60:63]
	v_mfma_f32_16x16x32_bf16 v[60:63], v[154:157], v[184:187], v[60:63]
	v_mfma_f32_16x16x32_bf16 v[56:59], v[176:179], v[184:187], v[56:59]
	v_mfma_f32_16x16x32_bf16 v[56:59], v[158:161], v[180:183], v[56:59]
	v_mfma_f32_16x16x32_bf16 v[40:43], v[158:161], v[188:191], v[40:43]
	v_mfma_f32_16x16x32_bf16 v[40:43], v[176:179], v[192:195], v[40:43]
	v_mfma_f32_16x16x32_bf16 v[44:47], v[154:157], v[192:195], v[44:47]
	v_mfma_f32_16x16x32_bf16 v[44:47], v[140:143], v[188:191], v[44:47]
	v_mfma_f32_16x16x32_bf16 v[28:31], v[140:143], v[196:199], v[28:31]
	v_mfma_f32_16x16x32_bf16 v[28:31], v[154:157], v[200:203], v[28:31]
	v_mfma_f32_16x16x32_bf16 v[24:27], v[176:179], v[200:203], v[24:27]
	v_mfma_f32_16x16x32_bf16 v[24:27], v[158:161], v[196:199], v[24:27]
	v_mfma_f32_16x16x32_bf16 v[8:11], v[158:161], v[204:207], v[8:11]
	v_mfma_f32_16x16x32_bf16 v[8:11], v[176:179], v[208:211], v[8:11]
	v_mfma_f32_16x16x32_bf16 v[12:15], v[154:157], v[208:211], v[12:15]
	v_mfma_f32_16x16x32_bf16 v[12:15], v[140:143], v[204:207], v[12:15]
	s_setprio 0
	s_barrier
	s_add_u32 s52, s28, 0x80000
	s_addc_u32 s53, s29, 0
	s_add_i32 s54, s47, s36
	v_lshl_add_u64 v[140:141], s[52:53], 0, v[164:165]
	s_mov_b32 m0, s54
	s_nop 0
	global_load_lds_dwordx4 v[140:141], off
	v_lshl_add_u64 v[140:141], s[52:53], 0, v[166:167]
	s_add_i32 m0, s54, 0x2000
	s_nop 0
	global_load_lds_dwordx4 v[140:141], off
	s_waitcnt vmcnt(6)
	s_barrier
	s_setprio 1
	v_mfma_f32_16x16x32_bf16 v[52:55], v[212:215], v[180:183], v[52:55]
	v_mfma_f32_16x16x32_bf16 v[52:55], v[240:243], v[184:187], v[52:55]
	v_mfma_f32_16x16x32_bf16 v[48:51], v[248:251], v[184:187], v[48:51]
	v_mfma_f32_16x16x32_bf16 v[48:51], v[244:247], v[180:183], v[48:51]
	v_mfma_f32_16x16x32_bf16 v[32:35], v[244:247], v[188:191], v[32:35]
	v_mfma_f32_16x16x32_bf16 v[32:35], v[248:251], v[192:195], v[32:35]
	v_mfma_f32_16x16x32_bf16 v[36:39], v[240:243], v[192:195], v[36:39]
	v_mfma_f32_16x16x32_bf16 v[36:39], v[212:215], v[188:191], v[36:39]
	v_mfma_f32_16x16x32_bf16 v[20:23], v[212:215], v[196:199], v[20:23]
	v_mfma_f32_16x16x32_bf16 v[20:23], v[240:243], v[200:203], v[20:23]
	v_mfma_f32_16x16x32_bf16 v[16:19], v[248:251], v[200:203], v[16:19]
	v_mfma_f32_16x16x32_bf16 v[16:19], v[244:247], v[196:199], v[16:19]
	v_mfma_f32_16x16x32_bf16 v[0:3], v[244:247], v[204:207], v[0:3]
	v_mfma_f32_16x16x32_bf16 v[0:3], v[248:251], v[208:211], v[0:3]
	v_mfma_f32_16x16x32_bf16 v[4:7], v[240:243], v[208:211], v[4:7]
	v_mfma_f32_16x16x32_bf16 v[4:7], v[212:215], v[204:207], v[4:7]
	s_setprio 0
	s_add_i32 s52, 0, 0x18000
	v_add_u32_e32 v169, s52, v147
	s_barrier
	ds_read_b128 v[140:143], v169
	v_xor_b32_e32 v179, 64, v169
	ds_read_b128 v[154:157], v179
	ds_read_b128 v[158:161], v169 offset:2048
	ds_read_b128 v[176:179], v179 offset:2048
	s_add_u32 s30, s30, 0x80000
	s_addc_u32 s31, s31, 0
	s_mov_b32 m0, s39
	v_lshl_add_u64 v[212:213], s[30:31], 0, v[128:129]
	ds_read_b128 v[180:183], v150 offset:32768
	v_xor_b32_e32 v211, 64, v150
	ds_read_b128 v[184:187], v211 offset:32768
	ds_read_b128 v[188:191], v150 offset:34816
	ds_read_b128 v[192:195], v211 offset:34816
	ds_read_b128 v[196:199], v150 offset:36864
	ds_read_b128 v[200:203], v211 offset:36864
	ds_read_b128 v[204:207], v150 offset:38912
	ds_read_b128 v[208:211], v211 offset:38912
	global_load_lds_dwordx4 v[212:213], off
	v_lshl_add_u64 v[212:213], s[30:31], 0, v[130:131]
	s_mov_b32 m0, s40
	s_nop 0
	global_load_lds_dwordx4 v[212:213], off
	s_waitcnt lgkmcnt(8)
	s_barrier
	s_waitcnt lgkmcnt(0)
	s_setprio 1
	s_waitcnt lgkmcnt(0)
	v_mfma_f32_16x16x32_bf16 v[124:127], v[140:143], v[180:183], v[124:127]
	v_mfma_f32_16x16x32_bf16 v[124:127], v[154:157], v[184:187], v[124:127]
	v_mfma_f32_16x16x32_bf16 v[120:123], v[176:179], v[184:187], v[120:123]
	v_mfma_f32_16x16x32_bf16 v[120:123], v[158:161], v[180:183], v[120:123]
	v_mfma_f32_16x16x32_bf16 v[104:107], v[158:161], v[188:191], v[104:107]
	v_mfma_f32_16x16x32_bf16 v[104:107], v[176:179], v[192:195], v[104:107]
	v_mfma_f32_16x16x32_bf16 v[108:111], v[154:157], v[192:195], v[108:111]
	v_mfma_f32_16x16x32_bf16 v[108:111], v[140:143], v[188:191], v[108:111]
	v_mfma_f32_16x16x32_bf16 v[92:95], v[140:143], v[196:199], v[92:95]
	v_mfma_f32_16x16x32_bf16 v[92:95], v[154:157], v[200:203], v[92:95]
	v_mfma_f32_16x16x32_bf16 v[88:91], v[176:179], v[200:203], v[88:91]
	v_mfma_f32_16x16x32_bf16 v[88:91], v[158:161], v[196:199], v[88:91]
	v_mfma_f32_16x16x32_bf16 v[72:75], v[158:161], v[204:207], v[72:75]
	v_mfma_f32_16x16x32_bf16 v[72:75], v[176:179], v[208:211], v[72:75]
	v_mfma_f32_16x16x32_bf16 v[76:79], v[154:157], v[208:211], v[76:79]
	v_mfma_f32_16x16x32_bf16 v[76:79], v[140:143], v[204:207], v[76:79]
	s_setprio 0
	s_barrier
	s_add_i32 s30, 0, 0x1c000
	s_add_i32 s31, s52, s36
	v_add_u32_e32 v169, s30, v147
	v_lshl_add_u64 v[144:145], v[144:145], 0, s[16:17]
	s_mov_b32 m0, s31
	ds_read_b128 v[212:215], v169
	v_xor_b32_e32 v251, 64, v169
	ds_read_b128 v[240:243], v251
	ds_read_b128 v[244:247], v169 offset:2048
	ds_read_b128 v[248:251], v251 offset:2048
	global_load_lds_dwordx4 v[144:145], off
	v_lshl_add_u64 v[144:145], v[216:217], 0, s[16:17]
	s_add_i32 m0, s31, 0x2000
	s_nop 0
	global_load_lds_dwordx4 v[144:145], off
	s_barrier
	s_waitcnt lgkmcnt(0)
	s_setprio 1
	s_waitcnt lgkmcnt(0)
	v_mfma_f32_16x16x32_bf16 v[116:119], v[212:215], v[180:183], v[116:119]
	v_mfma_f32_16x16x32_bf16 v[116:119], v[240:243], v[184:187], v[116:119]
	v_mfma_f32_16x16x32_bf16 v[112:115], v[248:251], v[184:187], v[112:115]
	v_mfma_f32_16x16x32_bf16 v[112:115], v[244:247], v[180:183], v[112:115]
	v_mfma_f32_16x16x32_bf16 v[96:99], v[244:247], v[188:191], v[96:99]
	v_mfma_f32_16x16x32_bf16 v[96:99], v[248:251], v[192:195], v[96:99]
	v_mfma_f32_16x16x32_bf16 v[100:103], v[240:243], v[192:195], v[100:103]
	v_mfma_f32_16x16x32_bf16 v[100:103], v[212:215], v[188:191], v[100:103]
	v_mfma_f32_16x16x32_bf16 v[84:87], v[212:215], v[196:199], v[84:87]
	v_mfma_f32_16x16x32_bf16 v[84:87], v[240:243], v[200:203], v[84:87]
	v_mfma_f32_16x16x32_bf16 v[80:83], v[248:251], v[200:203], v[80:83]
	v_mfma_f32_16x16x32_bf16 v[80:83], v[244:247], v[196:199], v[80:83]
	v_mfma_f32_16x16x32_bf16 v[64:67], v[244:247], v[204:207], v[64:67]
	v_mfma_f32_16x16x32_bf16 v[64:67], v[248:251], v[208:211], v[64:67]
	v_mfma_f32_16x16x32_bf16 v[68:71], v[240:243], v[208:211], v[68:71]
	v_mfma_f32_16x16x32_bf16 v[68:71], v[212:215], v[204:207], v[68:71]
	s_setprio 0
	s_mov_b32 m0, s42
	v_lshl_add_u64 v[144:145], v[252:253], 0, s[16:17]
	s_barrier
	ds_read_b128 v[180:183], v150 offset:49152
	v_xor_b32_e32 v211, 64, v150
	ds_read_b128 v[184:187], v211 offset:49152
	ds_read_b128 v[188:191], v150 offset:51200
	ds_read_b128 v[192:195], v211 offset:51200
	ds_read_b128 v[196:199], v150 offset:53248
	ds_read_b128 v[200:203], v211 offset:53248
	ds_read_b128 v[204:207], v150 offset:55296
	ds_read_b128 v[208:211], v211 offset:55296
	global_load_lds_dwordx4 v[144:145], off
	v_lshl_add_u64 v[144:145], v[234:235], 0, s[16:17]
	s_mov_b32 m0, s43
	s_nop 0
	global_load_lds_dwordx4 v[144:145], off
	s_barrier
	s_waitcnt lgkmcnt(0)
	s_setprio 1
	s_waitcnt lgkmcnt(0)
	v_mfma_f32_16x16x32_bf16 v[60:63], v[140:143], v[180:183], v[60:63]
	v_mfma_f32_16x16x32_bf16 v[60:63], v[154:157], v[184:187], v[60:63]
	v_mfma_f32_16x16x32_bf16 v[56:59], v[176:179], v[184:187], v[56:59]
	v_mfma_f32_16x16x32_bf16 v[56:59], v[158:161], v[180:183], v[56:59]
	v_mfma_f32_16x16x32_bf16 v[40:43], v[158:161], v[188:191], v[40:43]
	v_mfma_f32_16x16x32_bf16 v[40:43], v[176:179], v[192:195], v[40:43]
	v_mfma_f32_16x16x32_bf16 v[44:47], v[154:157], v[192:195], v[44:47]
	v_mfma_f32_16x16x32_bf16 v[44:47], v[140:143], v[188:191], v[44:47]
	v_mfma_f32_16x16x32_bf16 v[28:31], v[140:143], v[196:199], v[28:31]
	v_mfma_f32_16x16x32_bf16 v[28:31], v[154:157], v[200:203], v[28:31]
	v_mfma_f32_16x16x32_bf16 v[24:27], v[176:179], v[200:203], v[24:27]
	v_mfma_f32_16x16x32_bf16 v[24:27], v[158:161], v[196:199], v[24:27]
	v_mfma_f32_16x16x32_bf16 v[8:11], v[158:161], v[204:207], v[8:11]
	v_mfma_f32_16x16x32_bf16 v[8:11], v[176:179], v[208:211], v[8:11]
	v_mfma_f32_16x16x32_bf16 v[12:15], v[154:157], v[208:211], v[12:15]
	v_mfma_f32_16x16x32_bf16 v[12:15], v[140:143], v[204:207], v[12:15]
	s_setprio 0
	s_barrier
	s_add_u32 s28, s28, 0x80080
	s_addc_u32 s29, s29, 0
	s_add_i32 s30, s30, s36
	v_lshl_add_u64 v[140:141], s[28:29], 0, v[164:165]
	s_mov_b32 m0, s30
	s_nop 0
	global_load_lds_dwordx4 v[140:141], off
	v_lshl_add_u64 v[140:141], s[28:29], 0, v[166:167]
	s_add_i32 m0, s30, 0x2000
	s_nop 0
	global_load_lds_dwordx4 v[140:141], off
	s_waitcnt vmcnt(6)
	s_barrier
	s_setprio 1
	v_mfma_f32_16x16x32_bf16 v[52:55], v[212:215], v[180:183], v[52:55]
	v_mfma_f32_16x16x32_bf16 v[52:55], v[240:243], v[184:187], v[52:55]
	v_mfma_f32_16x16x32_bf16 v[48:51], v[248:251], v[184:187], v[48:51]
	v_mfma_f32_16x16x32_bf16 v[48:51], v[244:247], v[180:183], v[48:51]
	v_mfma_f32_16x16x32_bf16 v[32:35], v[244:247], v[188:191], v[32:35]
	v_mfma_f32_16x16x32_bf16 v[32:35], v[248:251], v[192:195], v[32:35]
	v_mfma_f32_16x16x32_bf16 v[36:39], v[240:243], v[192:195], v[36:39]
	v_mfma_f32_16x16x32_bf16 v[36:39], v[212:215], v[188:191], v[36:39]
	v_mfma_f32_16x16x32_bf16 v[20:23], v[212:215], v[196:199], v[20:23]
	v_mfma_f32_16x16x32_bf16 v[20:23], v[240:243], v[200:203], v[20:23]
	v_mfma_f32_16x16x32_bf16 v[16:19], v[248:251], v[200:203], v[16:19]
	v_mfma_f32_16x16x32_bf16 v[16:19], v[244:247], v[196:199], v[16:19]
	v_mfma_f32_16x16x32_bf16 v[0:3], v[244:247], v[204:207], v[0:3]
	v_mfma_f32_16x16x32_bf16 v[0:3], v[248:251], v[208:211], v[0:3]
	v_mfma_f32_16x16x32_bf16 v[4:7], v[240:243], v[208:211], v[4:7]
	v_mfma_f32_16x16x32_bf16 v[4:7], v[212:215], v[204:207], v[4:7]
	s_setprio 0
	s_add_i32 s49, s49, 2
	s_add_u32 s26, s26, 0x100
	s_addc_u32 s27, s27, 0
	s_add_u32 s33, s33, 0x100
	s_addc_u32 s48, s48, 0
	s_cmp_gt_u32 s49, 29
	s_barrier
	s_cbranch_scc0 .LBB0_599
	v_lshl_add_u32 v142, s12, 8, v146
	v_ashrrev_i32_e32 v143, 31, v142
	v_lshl_add_u64 v[144:145], v[142:143], 2, s[14:15]
	global_load_dword v179, v[144:145], off
	global_load_dword v180, v[144:145], off offset:64
	global_load_dword v181, v[144:145], off offset:128
	global_load_dword v182, v[144:145], off offset:192
	global_load_dword v183, v[144:145], off offset:512
	global_load_dword v184, v[144:145], off offset:576
	global_load_dword v185, v[144:145], off offset:640
	global_load_dword v186, v[144:145], off offset:704
	v_lshl_or_b32 v140, s0, 8, v148
	v_lshlrev_b64 v[156:157], 13, v[142:143]
	v_ashrrev_i32_e32 v141, 31, v140
	v_lshl_add_u64 v[156:157], s[96:97], 0, v[156:157]
	v_lshl_add_u64 v[158:159], v[140:141], 1, v[156:157]
	s_cmp_gt_i32 s0, 7
	s_cselect_b64 s[26:27], -1, 0
	s_cmp_lt_i32 s0, 8
	s_waitcnt vmcnt(0)
	v_fmamk_f32 v154, v179, 0x3a000000, v152
	v_rsq_f32_e32 v154, v154
	s_nop 0
	v_pk_mul_f32 v[126:127], v[126:127], v[154:155] op_sel_hi:[1,0]
	v_pk_mul_f32 v[124:125], v[124:125], v[154:155] op_sel_hi:[1,0]
	v_pk_mul_f32 v[120:121], v[120:121], v[154:155] op_sel_hi:[1,0]
	v_pk_mul_f32 v[122:123], v[122:123], v[154:155] op_sel_hi:[1,0]
	v_pk_mul_f32 v[156:157], v[118:119], v[154:155] op_sel_hi:[1,0]
	v_pk_mul_f32 v[160:161], v[116:117], v[154:155] op_sel_hi:[1,0]
	v_pk_mul_f32 v[176:177], v[114:115], v[154:155] op_sel_hi:[1,0]
	v_pk_mul_f32 v[154:155], v[112:113], v[154:155] op_sel_hi:[1,0]
	v_mul_f32_e32 v112, 0x3d372713, v124
	v_mul_f32_e32 v113, 0x3d372713, v120
	v_mul_f32_e32 v114, 0x3d372713, v125
	v_mul_f32_e32 v115, 0x3d372713, v121
	v_mul_f32_e32 v116, 0x3d372713, v126
	v_mul_f32_e32 v118, 0x3d372713, v127
	v_mul_f32_e32 v117, 0x3d372713, v122
	v_mul_f32_e32 v119, 0x3d372713, v123
	v_mul_f32_e32 v112, v124, v112
	v_mul_f32_e32 v113, v120, v113
	v_mul_f32_e32 v114, v125, v114
	v_mul_f32_e32 v115, v121, v115
	v_mul_f32_e32 v116, v126, v116
	v_mul_f32_e32 v118, v127, v118
	v_mul_f32_e32 v117, v122, v117
	v_mul_f32_e32 v119, v123, v119
	v_fma_f32 v112, v124, v112, v124
	v_fma_f32 v113, v120, v113, v120
	v_fma_f32 v114, v125, v114, v125
	v_fma_f32 v115, v121, v115, v121
	v_fma_f32 v116, v126, v116, v126
	v_fma_f32 v118, v127, v118, v127
	v_fma_f32 v117, v122, v117, v122
	v_fma_f32 v119, v123, v119, v123
	v_mul_f32_e32 v112, 0x3f4c422a, v112
	v_mul_f32_e32 v113, 0x3f4c422a, v113
	v_mul_f32_e32 v114, 0x3f4c422a, v114
	v_mul_f32_e32 v115, 0x3f4c422a, v115
	v_mul_f32_e32 v116, 0x3f4c422a, v116
	v_mul_f32_e32 v118, 0x3f4c422a, v118
	v_mul_f32_e32 v117, 0x3f4c422a, v117
	v_mul_f32_e32 v119, 0x3f4c422a, v119
	v_mul_f32_e32 v112, 0xc038aa3b, v112
	v_mul_f32_e32 v113, 0xc038aa3b, v113
	v_mul_f32_e32 v114, 0xc038aa3b, v114
	v_mul_f32_e32 v115, 0xc038aa3b, v115
	v_mul_f32_e32 v116, 0xc038aa3b, v116
	v_mul_f32_e32 v118, 0xc038aa3b, v118
	v_mul_f32_e32 v117, 0xc038aa3b, v117
	v_mul_f32_e32 v119, 0xc038aa3b, v119
	v_exp_f32_e32 v112, v112
	v_exp_f32_e32 v113, v113
	v_exp_f32_e32 v114, v114
	v_exp_f32_e32 v115, v115
	v_exp_f32_e32 v116, v116
	v_exp_f32_e32 v118, v118
	v_exp_f32_e32 v117, v117
	v_exp_f32_e32 v119, v119
	v_add_f32_e32 v112, 1.0, v112
	v_add_f32_e32 v113, 1.0, v113
	v_add_f32_e32 v114, 1.0, v114
	v_add_f32_e32 v115, 1.0, v115
	v_add_f32_e32 v116, 1.0, v116
	v_add_f32_e32 v118, 1.0, v118
	v_add_f32_e32 v117, 1.0, v117
	v_add_f32_e32 v119, 1.0, v119
	v_rcp_f32_e32 v112, v112
	v_rcp_f32_e32 v113, v113
	v_rcp_f32_e32 v114, v114
	v_rcp_f32_e32 v171, v115
	v_rcp_f32_e32 v173, v116
	v_rcp_f32_e32 v175, v118
	v_rcp_f32_e32 v117, v117
	v_rcp_f32_e32 v178, v119
	v_mul_f32_e32 v116, v124, v112
	v_mul_f32_e32 v119, v120, v113
	v_mul_f32_e32 v115, v125, v114
	v_mul_f32_e32 v118, v121, v171
	v_mul_f32_e32 v113, v126, v173
	v_mul_f32_e32 v112, v127, v175
	v_cvt_pk_bf16_f32 v120, v116, v115
	v_cvt_pk_bf16_f32 v121, v113, v112
	v_mul_f32_e32 v117, v122, v117
	v_mul_f32_e32 v114, v123, v178
	v_cvt_pk_bf16_f32 v122, v119, v118
	v_cvt_pk_bf16_f32 v123, v117, v114
	global_store_dwordx4 v[158:159], v[120:123], off
	v_mul_f32_e32 v169, 0x3d372713, v160
	v_mul_f32_e32 v169, v160, v169
	v_mul_f32_e32 v121, 0x3d372713, v161
	v_mul_f32_e32 v121, v161, v121
	v_fma_f32 v121, v161, v121, v161
	v_mul_f32_e32 v121, 0x3f4c422a, v121
	v_mul_f32_e32 v121, 0xc038aa3b, v121
	v_mul_f32_e32 v120, 0x3d372713, v154
	v_exp_f32_e32 v121, v121
	v_mul_f32_e32 v120, v154, v120
	v_fma_f32 v169, v160, v169, v160
	v_fma_f32 v120, v154, v120, v154
	v_mul_f32_e32 v169, 0x3f4c422a, v169
	v_mul_f32_e32 v120, 0x3f4c422a, v120
	v_mul_f32_e32 v169, 0xc038aa3b, v169
	v_mul_f32_e32 v120, 0xc038aa3b, v120
	v_add_f32_e32 v121, 1.0, v121
	v_exp_f32_e32 v169, v169
	v_exp_f32_e32 v120, v120
	v_rcp_f32_e32 v123, v121
	v_mul_f32_e32 v121, 0x3d372713, v155
	v_mul_f32_e32 v121, v155, v121
	v_fma_f32 v121, v155, v121, v155
	v_mul_f32_e32 v121, 0x3f4c422a, v121
	v_add_f32_e32 v169, 1.0, v169
	v_add_f32_e32 v120, 1.0, v120
	v_mul_f32_e32 v121, 0xc038aa3b, v121
	v_rcp_f32_e32 v122, v169
	v_rcp_f32_e32 v120, v120
	v_exp_f32_e32 v124, v121
	v_mul_f32_e32 v125, 0x3d372713, v176
	v_mul_f32_e32 v125, v176, v125
	v_mul_f32_e32 v126, 0x3d372713, v157
	v_mul_f32_e32 v121, v160, v122
	v_mul_f32_e32 v122, v154, v120
	v_mul_f32_e32 v120, v161, v123
	v_add_f32_e32 v123, 1.0, v124
	v_mul_f32_e32 v124, 0x3d372713, v156
	v_fma_f32 v125, v176, v125, v176
	v_mul_f32_e32 v126, v157, v126
	v_mul_f32_e32 v127, 0x3d372713, v177
	v_mul_f32_e32 v124, v156, v124
	v_mul_f32_e32 v125, 0x3f4c422a, v125
	v_fma_f32 v126, v157, v126, v157
	v_mul_f32_e32 v127, v177, v127
	v_fma_f32 v124, v156, v124, v156
	v_mul_f32_e32 v125, 0xc038aa3b, v125
	v_mul_f32_e32 v126, 0x3f4c422a, v126
	v_fma_f32 v127, v177, v127, v177
	v_mul_f32_e32 v124, 0x3f4c422a, v124
	v_exp_f32_e32 v125, v125
	v_mul_f32_e32 v126, 0xc038aa3b, v126
	v_mul_f32_e32 v127, 0x3f4c422a, v127
	v_mul_f32_e32 v124, 0xc038aa3b, v124
	v_exp_f32_e32 v126, v126
	v_mul_f32_e32 v127, 0xc038aa3b, v127
	v_exp_f32_e32 v124, v124
	v_exp_f32_e32 v127, v127
	v_rcp_f32_e32 v123, v123
	v_add_f32_e32 v125, 1.0, v125
	v_rcp_f32_e32 v154, v125
	v_add_f32_e32 v125, 1.0, v126
	v_add_f32_e32 v124, 1.0, v124
	v_rcp_f32_e32 v126, v125
	v_add_f32_e32 v125, 1.0, v127
	v_mul_f32_e32 v123, v155, v123
	v_rcp_f32_e32 v124, v124
	v_rcp_f32_e32 v155, v125
	v_mul_f32_e32 v127, v176, v154
	v_cvt_pk_bf16_f32 v154, v121, v120
	v_mul_f32_e32 v125, v156, v124
	v_mul_f32_e32 v124, v157, v126
	v_mul_f32_e32 v126, v177, v155
	v_cvt_pk_bf16_f32 v155, v125, v124
	v_cvt_pk_bf16_f32 v156, v122, v123
	v_cvt_pk_bf16_f32 v157, v127, v126
	global_store_dwordx4 v[158:159], v[154:157], off offset:256
	s_cbranch_scc1 .LBB0_604
	v_mul_f32_e32 v119, v119, v119
	v_fmac_f32_e32 v119, v116, v116
	v_mul_f32_e32 v116, v118, v118
	v_fmac_f32_e32 v116, v115, v115
	v_add_f32_e32 v115, v119, v116
	v_mul_f32_e32 v116, v117, v117
	v_fmac_f32_e32 v116, v113, v113
	v_mul_f32_e32 v114, v114, v114
	v_add_f32_e32 v113, v116, v115
	v_fmac_f32_e32 v114, v112, v112
	v_add_f32_e32 v112, v114, v113
	v_mul_f32_e32 v113, v122, v122
	v_fmac_f32_e32 v113, v121, v121
	v_add_f32_e32 v112, v113, v112
	v_mul_f32_e32 v113, v123, v123
	v_fmac_f32_e32 v113, v120, v120
	v_add_f32_e32 v112, v113, v112
	v_mul_f32_e32 v113, v127, v127
	v_fmac_f32_e32 v113, v125, v125
	v_add_f32_e32 v112, v113, v112
	v_mul_f32_e32 v113, v126, v126
	v_fmac_f32_e32 v113, v124, v124
	v_and_b32_e32 v114, 64, v153
	v_add_f32_e32 v112, v113, v112
	v_xor_b32_e32 v113, 16, v153
	v_add_u32_e32 v114, 64, v114
	v_cmp_lt_i32_e32 vcc, v113, v114
	s_nop 1
	v_cndmask_b32_e32 v113, v153, v113, vcc
	v_lshlrev_b32_e32 v113, 2, v113
	ds_bpermute_b32 v113, v113, v112
	s_waitcnt lgkmcnt(0)
	v_add_f32_e32 v112, v112, v113
	v_xor_b32_e32 v113, 32, v153
	v_cmp_lt_i32_e32 vcc, v113, v114
	s_nop 1
	v_cndmask_b32_e32 v113, v153, v113, vcc
	v_lshlrev_b32_e32 v113, 2, v113
	ds_bpermute_b32 v113, v113, v112
	s_and_saveexec_b64 s[0:1], s[8:9]
	s_cbranch_execz .LBB0_603
	v_lshl_add_u64 v[114:115], v[142:143], 2, s[4:5]
	s_waitcnt lgkmcnt(0)
	v_add_f32_e32 v112, v112, v113
	global_atomic_add_f32 v[114:115], v112, off

.LBB0_760:
	ds_read_b128 v[140:143], v145
	v_xor_b32_e32 v161, 64, v145
	ds_read_b128 v[150:153], v161
	ds_read_b128 v[154:157], v145 offset:2048
	ds_read_b128 v[158:161], v161 offset:2048
	s_add_u32 s22, s20, 0xfff00080
	s_addc_u32 s23, s21, -1
	s_cmp_eq_u32 s45, 28
	s_cselect_b32 s25, s1, s23
	s_cselect_b32 s24, s9, s22
	s_cselect_b32 s23, s13, s44
	s_cselect_b32 s22, s15, s43
	v_lshl_add_u64 v[208:209], s[20:21], 0, v[132:133]
	s_add_i32 m0, s29, 0xc000
	ds_read_b128 v[176:179], v146
	v_xor_b32_e32 v207, 64, v146
	ds_read_b128 v[180:183], v207
	ds_read_b128 v[184:187], v146 offset:2048
	ds_read_b128 v[188:191], v207 offset:2048
	ds_read_b128 v[192:195], v146 offset:4096
	ds_read_b128 v[196:199], v207 offset:4096
	ds_read_b128 v[200:203], v146 offset:6144
	ds_read_b128 v[204:207], v207 offset:6144
	global_load_lds_dwordx4 v[208:209], off
	v_lshl_add_u64 v[208:209], s[20:21], 0, v[134:135]
	s_add_i32 m0, s29, 0xe000
	s_nop 0
	global_load_lds_dwordx4 v[208:209], off
	s_waitcnt lgkmcnt(8)
	s_barrier
	s_waitcnt lgkmcnt(0)
	s_setprio 1
	s_waitcnt lgkmcnt(0)
	v_mfma_f32_16x16x32_bf16 v[124:127], v[140:143], v[176:179], v[124:127]
	v_mfma_f32_16x16x32_bf16 v[124:127], v[150:153], v[180:183], v[124:127]
	v_mfma_f32_16x16x32_bf16 v[120:123], v[158:161], v[180:183], v[120:123]
	v_mfma_f32_16x16x32_bf16 v[120:123], v[154:157], v[176:179], v[120:123]
	v_mfma_f32_16x16x32_bf16 v[104:107], v[154:157], v[184:187], v[104:107]
	v_mfma_f32_16x16x32_bf16 v[104:107], v[158:161], v[188:191], v[104:107]
	v_mfma_f32_16x16x32_bf16 v[108:111], v[150:153], v[188:191], v[108:111]
	v_mfma_f32_16x16x32_bf16 v[108:111], v[140:143], v[184:187], v[108:111]
	v_mfma_f32_16x16x32_bf16 v[92:95], v[140:143], v[192:195], v[92:95]
	v_mfma_f32_16x16x32_bf16 v[92:95], v[150:153], v[196:199], v[92:95]
	v_mfma_f32_16x16x32_bf16 v[88:91], v[158:161], v[196:199], v[88:91]
	v_mfma_f32_16x16x32_bf16 v[88:91], v[154:157], v[192:195], v[88:91]
	v_mfma_f32_16x16x32_bf16 v[72:75], v[154:157], v[200:203], v[72:75]
	v_mfma_f32_16x16x32_bf16 v[72:75], v[158:161], v[204:207], v[72:75]
	v_mfma_f32_16x16x32_bf16 v[76:79], v[150:153], v[204:207], v[76:79]
	v_mfma_f32_16x16x32_bf16 v[76:79], v[140:143], v[200:203], v[76:79]
	s_setprio 0
	s_barrier
	s_add_i32 s46, s41, s28
	v_lshl_add_u64 v[216:217], s[22:23], 0, v[164:165]
	s_mov_b32 m0, s46
	ds_read_b128 v[208:211], v147
	v_xor_b32_e32 v243, 64, v147
	ds_read_b128 v[212:215], v243
	ds_read_b128 v[236:239], v147 offset:2048
	ds_read_b128 v[240:243], v243 offset:2048
	global_load_lds_dwordx4 v[216:217], off
	v_lshl_add_u64 v[234:235], s[22:23], 0, v[166:167]
	s_add_i32 m0, s46, 0x2000
	s_nop 0
	global_load_lds_dwordx4 v[234:235], off
	s_barrier
	s_waitcnt lgkmcnt(0)
	s_setprio 1
	s_waitcnt lgkmcnt(0)
	v_mfma_f32_16x16x32_bf16 v[116:119], v[208:211], v[176:179], v[116:119]
	v_mfma_f32_16x16x32_bf16 v[116:119], v[212:215], v[180:183], v[116:119]
	v_mfma_f32_16x16x32_bf16 v[112:115], v[240:243], v[180:183], v[112:115]
	v_mfma_f32_16x16x32_bf16 v[112:115], v[236:239], v[176:179], v[112:115]
	v_mfma_f32_16x16x32_bf16 v[96:99], v[236:239], v[184:187], v[96:99]
	v_mfma_f32_16x16x32_bf16 v[96:99], v[240:243], v[188:191], v[96:99]
	v_mfma_f32_16x16x32_bf16 v[100:103], v[212:215], v[188:191], v[100:103]
	v_mfma_f32_16x16x32_bf16 v[100:103], v[208:211], v[184:187], v[100:103]
	v_mfma_f32_16x16x32_bf16 v[84:87], v[208:211], v[192:195], v[84:87]
	v_mfma_f32_16x16x32_bf16 v[84:87], v[212:215], v[196:199], v[84:87]
	v_mfma_f32_16x16x32_bf16 v[80:83], v[240:243], v[196:199], v[80:83]
	v_mfma_f32_16x16x32_bf16 v[80:83], v[236:239], v[192:195], v[80:83]
	v_mfma_f32_16x16x32_bf16 v[64:67], v[236:239], v[200:203], v[64:67]
	v_mfma_f32_16x16x32_bf16 v[64:67], v[240:243], v[204:207], v[64:67]
	v_mfma_f32_16x16x32_bf16 v[68:71], v[212:215], v[204:207], v[68:71]
	v_mfma_f32_16x16x32_bf16 v[68:71], v[208:211], v[200:203], v[68:71]
	s_setprio 0
	s_mov_b32 m0, s29
	v_lshl_add_u64 v[244:245], s[24:25], 0, v[128:129]
	s_barrier
	ds_read_b128 v[176:179], v146 offset:16384
	v_xor_b32_e32 v207, 64, v146
	ds_read_b128 v[180:183], v207 offset:16384
	ds_read_b128 v[184:187], v146 offset:18432
	ds_read_b128 v[188:191], v207 offset:18432
	ds_read_b128 v[192:195], v146 offset:20480
	ds_read_b128 v[196:199], v207 offset:20480
	ds_read_b128 v[200:203], v146 offset:22528
	ds_read_b128 v[204:207], v207 offset:22528
	global_load_lds_dwordx4 v[244:245], off
	v_lshl_add_u64 v[246:247], s[24:25], 0, v[130:131]
	s_mov_b32 m0, s30
	s_nop 0
	global_load_lds_dwordx4 v[246:247], off
	s_barrier
	s_waitcnt lgkmcnt(0)
	s_setprio 1
	s_waitcnt lgkmcnt(0)
	v_mfma_f32_16x16x32_bf16 v[60:63], v[140:143], v[176:179], v[60:63]
	v_mfma_f32_16x16x32_bf16 v[60:63], v[150:153], v[180:183], v[60:63]
	v_mfma_f32_16x16x32_bf16 v[56:59], v[158:161], v[180:183], v[56:59]
	v_mfma_f32_16x16x32_bf16 v[56:59], v[154:157], v[176:179], v[56:59]
	v_mfma_f32_16x16x32_bf16 v[40:43], v[154:157], v[184:187], v[40:43]
	v_mfma_f32_16x16x32_bf16 v[40:43], v[158:161], v[188:191], v[40:43]
	v_mfma_f32_16x16x32_bf16 v[44:47], v[150:153], v[188:191], v[44:47]
	v_mfma_f32_16x16x32_bf16 v[44:47], v[140:143], v[184:187], v[44:47]
	v_mfma_f32_16x16x32_bf16 v[28:31], v[140:143], v[192:195], v[28:31]
	v_mfma_f32_16x16x32_bf16 v[28:31], v[150:153], v[196:199], v[28:31]
	v_mfma_f32_16x16x32_bf16 v[24:27], v[158:161], v[196:199], v[24:27]
	v_mfma_f32_16x16x32_bf16 v[24:27], v[154:157], v[192:195], v[24:27]
	v_mfma_f32_16x16x32_bf16 v[8:11], v[154:157], v[200:203], v[8:11]
	v_mfma_f32_16x16x32_bf16 v[8:11], v[158:161], v[204:207], v[8:11]
	v_mfma_f32_16x16x32_bf16 v[12:15], v[150:153], v[204:207], v[12:15]
	v_mfma_f32_16x16x32_bf16 v[12:15], v[140:143], v[200:203], v[12:15]
	s_setprio 0
	s_barrier
	s_add_u32 s46, s22, 0x80000
	s_addc_u32 s47, s23, 0
	s_add_i32 s48, s42, s28
	v_lshl_add_u64 v[140:141], s[46:47], 0, v[164:165]
	s_mov_b32 m0, s48
	s_nop 0
	global_load_lds_dwordx4 v[140:141], off
	v_lshl_add_u64 v[140:141], s[46:47], 0, v[166:167]
	s_add_i32 m0, s48, 0x2000
	s_nop 0
	global_load_lds_dwordx4 v[140:141], off
	s_waitcnt vmcnt(6)
	s_barrier
	s_setprio 1
	v_mfma_f32_16x16x32_bf16 v[52:55], v[208:211], v[176:179], v[52:55]
	v_mfma_f32_16x16x32_bf16 v[52:55], v[212:215], v[180:183], v[52:55]
	v_mfma_f32_16x16x32_bf16 v[48:51], v[240:243], v[180:183], v[48:51]
	v_mfma_f32_16x16x32_bf16 v[48:51], v[236:239], v[176:179], v[48:51]
	v_mfma_f32_16x16x32_bf16 v[32:35], v[236:239], v[184:187], v[32:35]
	v_mfma_f32_16x16x32_bf16 v[32:35], v[240:243], v[188:191], v[32:35]
	v_mfma_f32_16x16x32_bf16 v[36:39], v[212:215], v[188:191], v[36:39]
	v_mfma_f32_16x16x32_bf16 v[36:39], v[208:211], v[184:187], v[36:39]
	v_mfma_f32_16x16x32_bf16 v[20:23], v[208:211], v[192:195], v[20:23]
	v_mfma_f32_16x16x32_bf16 v[20:23], v[212:215], v[196:199], v[20:23]
	v_mfma_f32_16x16x32_bf16 v[16:19], v[240:243], v[196:199], v[16:19]
	v_mfma_f32_16x16x32_bf16 v[16:19], v[236:239], v[192:195], v[16:19]
	v_mfma_f32_16x16x32_bf16 v[0:3], v[236:239], v[200:203], v[0:3]
	v_mfma_f32_16x16x32_bf16 v[0:3], v[240:243], v[204:207], v[0:3]
	v_mfma_f32_16x16x32_bf16 v[4:7], v[212:215], v[204:207], v[4:7]
	v_mfma_f32_16x16x32_bf16 v[4:7], v[208:211], v[200:203], v[4:7]
	s_setprio 0
	s_add_i32 s46, 0, 0x18000
	v_add_u32_e32 v149, s46, v144
	s_barrier
	ds_read_b128 v[140:143], v149
	v_xor_b32_e32 v161, 64, v149
	ds_read_b128 v[150:153], v161
	ds_read_b128 v[154:157], v149 offset:2048
	ds_read_b128 v[158:161], v161 offset:2048
	s_add_u32 s24, s24, 0x100000
	s_addc_u32 s25, s25, 0
	s_mov_b32 m0, s31
	v_lshl_add_u64 v[208:209], s[24:25], 0, v[128:129]
	ds_read_b128 v[176:179], v146 offset:32768
	v_xor_b32_e32 v207, 64, v146
	ds_read_b128 v[180:183], v207 offset:32768
	ds_read_b128 v[184:187], v146 offset:34816
	ds_read_b128 v[188:191], v207 offset:34816
	ds_read_b128 v[192:195], v146 offset:36864
	ds_read_b128 v[196:199], v207 offset:36864
	ds_read_b128 v[200:203], v146 offset:38912
	ds_read_b128 v[204:207], v207 offset:38912
	global_load_lds_dwordx4 v[208:209], off
	v_lshl_add_u64 v[208:209], s[24:25], 0, v[130:131]
	s_mov_b32 m0, s33
	s_nop 0
	global_load_lds_dwordx4 v[208:209], off
	s_waitcnt lgkmcnt(8)
	s_barrier
	s_waitcnt lgkmcnt(0)
	s_setprio 1
	s_waitcnt lgkmcnt(0)
	v_mfma_f32_16x16x32_bf16 v[124:127], v[140:143], v[176:179], v[124:127]
	v_mfma_f32_16x16x32_bf16 v[124:127], v[150:153], v[180:183], v[124:127]
	v_mfma_f32_16x16x32_bf16 v[120:123], v[158:161], v[180:183], v[120:123]
	v_mfma_f32_16x16x32_bf16 v[120:123], v[154:157], v[176:179], v[120:123]
	v_mfma_f32_16x16x32_bf16 v[104:107], v[154:157], v[184:187], v[104:107]
	v_mfma_f32_16x16x32_bf16 v[104:107], v[158:161], v[188:191], v[104:107]
	v_mfma_f32_16x16x32_bf16 v[108:111], v[150:153], v[188:191], v[108:111]
	v_mfma_f32_16x16x32_bf16 v[108:111], v[140:143], v[184:187], v[108:111]
	v_mfma_f32_16x16x32_bf16 v[92:95], v[140:143], v[192:195], v[92:95]
	v_mfma_f32_16x16x32_bf16 v[92:95], v[150:153], v[196:199], v[92:95]
	v_mfma_f32_16x16x32_bf16 v[88:91], v[158:161], v[196:199], v[88:91]
	v_mfma_f32_16x16x32_bf16 v[88:91], v[154:157], v[192:195], v[88:91]
	v_mfma_f32_16x16x32_bf16 v[72:75], v[154:157], v[200:203], v[72:75]
	v_mfma_f32_16x16x32_bf16 v[72:75], v[158:161], v[204:207], v[72:75]
	v_mfma_f32_16x16x32_bf16 v[76:79], v[150:153], v[204:207], v[76:79]
	v_mfma_f32_16x16x32_bf16 v[76:79], v[140:143], v[200:203], v[76:79]
	s_setprio 0
	s_barrier
	s_add_i32 s24, 0, 0x1c000
	s_add_i32 s25, s46, s28
	v_add_u32_e32 v149, s24, v144
	v_lshl_add_u64 v[216:217], v[216:217], 0, s[10:11]
	s_mov_b32 m0, s25
	ds_read_b128 v[208:211], v149
	v_xor_b32_e32 v243, 64, v149
	ds_read_b128 v[212:215], v243
	ds_read_b128 v[236:239], v149 offset:2048
	ds_read_b128 v[240:243], v243 offset:2048
	global_load_lds_dwordx4 v[216:217], off
	v_lshl_add_u64 v[216:217], v[234:235], 0, s[10:11]
	s_add_i32 m0, s25, 0x2000
	s_nop 0
	global_load_lds_dwordx4 v[216:217], off
	s_barrier
	s_waitcnt lgkmcnt(0)
	s_setprio 1
	s_waitcnt lgkmcnt(0)
	v_mfma_f32_16x16x32_bf16 v[116:119], v[208:211], v[176:179], v[116:119]
	v_mfma_f32_16x16x32_bf16 v[116:119], v[212:215], v[180:183], v[116:119]
	v_mfma_f32_16x16x32_bf16 v[112:115], v[240:243], v[180:183], v[112:115]
	v_mfma_f32_16x16x32_bf16 v[112:115], v[236:239], v[176:179], v[112:115]
	v_mfma_f32_16x16x32_bf16 v[96:99], v[236:239], v[184:187], v[96:99]
	v_mfma_f32_16x16x32_bf16 v[96:99], v[240:243], v[188:191], v[96:99]
	v_mfma_f32_16x16x32_bf16 v[100:103], v[212:215], v[188:191], v[100:103]
	v_mfma_f32_16x16x32_bf16 v[100:103], v[208:211], v[184:187], v[100:103]
	v_mfma_f32_16x16x32_bf16 v[84:87], v[208:211], v[192:195], v[84:87]
	v_mfma_f32_16x16x32_bf16 v[84:87], v[212:215], v[196:199], v[84:87]
	v_mfma_f32_16x16x32_bf16 v[80:83], v[240:243], v[196:199], v[80:83]
	v_mfma_f32_16x16x32_bf16 v[80:83], v[236:239], v[192:195], v[80:83]
	v_mfma_f32_16x16x32_bf16 v[64:67], v[236:239], v[200:203], v[64:67]
	v_mfma_f32_16x16x32_bf16 v[64:67], v[240:243], v[204:207], v[64:67]
	v_mfma_f32_16x16x32_bf16 v[68:71], v[212:215], v[204:207], v[68:71]
	v_mfma_f32_16x16x32_bf16 v[68:71], v[208:211], v[200:203], v[68:71]
	s_setprio 0
	s_mov_b32 m0, s37
	v_lshl_add_u64 v[216:217], v[244:245], 0, s[10:11]
	s_barrier
	ds_read_b128 v[176:179], v146 offset:49152
	v_xor_b32_e32 v207, 64, v146
	ds_read_b128 v[180:183], v207 offset:49152
	ds_read_b128 v[184:187], v146 offset:51200
	ds_read_b128 v[188:191], v207 offset:51200
	ds_read_b128 v[192:195], v146 offset:53248
	ds_read_b128 v[196:199], v207 offset:53248
	ds_read_b128 v[200:203], v146 offset:55296
	ds_read_b128 v[204:207], v207 offset:55296
	global_load_lds_dwordx4 v[216:217], off
	v_lshl_add_u64 v[216:217], v[246:247], 0, s[10:11]
	s_mov_b32 m0, s38
	s_nop 0
	global_load_lds_dwordx4 v[216:217], off
	s_barrier
	s_waitcnt lgkmcnt(0)
	s_setprio 1
	s_waitcnt lgkmcnt(0)
	v_mfma_f32_16x16x32_bf16 v[60:63], v[140:143], v[176:179], v[60:63]
	v_mfma_f32_16x16x32_bf16 v[60:63], v[150:153], v[180:183], v[60:63]
	v_mfma_f32_16x16x32_bf16 v[56:59], v[158:161], v[180:183], v[56:59]
	v_mfma_f32_16x16x32_bf16 v[56:59], v[154:157], v[176:179], v[56:59]
	v_mfma_f32_16x16x32_bf16 v[40:43], v[154:157], v[184:187], v[40:43]
	v_mfma_f32_16x16x32_bf16 v[40:43], v[158:161], v[188:191], v[40:43]
	v_mfma_f32_16x16x32_bf16 v[44:47], v[150:153], v[188:191], v[44:47]
	v_mfma_f32_16x16x32_bf16 v[44:47], v[140:143], v[184:187], v[44:47]
	v_mfma_f32_16x16x32_bf16 v[28:31], v[140:143], v[192:195], v[28:31]
	v_mfma_f32_16x16x32_bf16 v[28:31], v[150:153], v[196:199], v[28:31]
	v_mfma_f32_16x16x32_bf16 v[24:27], v[158:161], v[196:199], v[24:27]
	v_mfma_f32_16x16x32_bf16 v[24:27], v[154:157], v[192:195], v[24:27]
	v_mfma_f32_16x16x32_bf16 v[8:11], v[154:157], v[200:203], v[8:11]
	v_mfma_f32_16x16x32_bf16 v[8:11], v[158:161], v[204:207], v[8:11]
	v_mfma_f32_16x16x32_bf16 v[12:15], v[150:153], v[204:207], v[12:15]
	v_mfma_f32_16x16x32_bf16 v[12:15], v[140:143], v[200:203], v[12:15]
	s_setprio 0
	s_barrier
	s_add_u32 s22, s22, 0x80080
	s_addc_u32 s23, s23, 0
	s_add_i32 s24, s24, s28
	v_lshl_add_u64 v[140:141], s[22:23], 0, v[164:165]
	s_mov_b32 m0, s24
	s_nop 0
	global_load_lds_dwordx4 v[140:141], off
	v_lshl_add_u64 v[140:141], s[22:23], 0, v[166:167]
	s_add_i32 m0, s24, 0x2000
	s_nop 0
	global_load_lds_dwordx4 v[140:141], off
	s_waitcnt vmcnt(6)
	s_barrier
	s_setprio 1
	v_mfma_f32_16x16x32_bf16 v[52:55], v[208:211], v[176:179], v[52:55]
	v_mfma_f32_16x16x32_bf16 v[52:55], v[212:215], v[180:183], v[52:55]
	v_mfma_f32_16x16x32_bf16 v[48:51], v[240:243], v[180:183], v[48:51]
	v_mfma_f32_16x16x32_bf16 v[48:51], v[236:239], v[176:179], v[48:51]
	v_mfma_f32_16x16x32_bf16 v[32:35], v[236:239], v[184:187], v[32:35]
	v_mfma_f32_16x16x32_bf16 v[32:35], v[240:243], v[188:191], v[32:35]
	v_mfma_f32_16x16x32_bf16 v[36:39], v[212:215], v[188:191], v[36:39]
	v_mfma_f32_16x16x32_bf16 v[36:39], v[208:211], v[184:187], v[36:39]
	v_mfma_f32_16x16x32_bf16 v[20:23], v[208:211], v[192:195], v[20:23]
	v_mfma_f32_16x16x32_bf16 v[20:23], v[212:215], v[196:199], v[20:23]
	v_mfma_f32_16x16x32_bf16 v[16:19], v[240:243], v[196:199], v[16:19]
	v_mfma_f32_16x16x32_bf16 v[16:19], v[236:239], v[192:195], v[16:19]
	v_mfma_f32_16x16x32_bf16 v[0:3], v[236:239], v[200:203], v[0:3]
	v_mfma_f32_16x16x32_bf16 v[0:3], v[240:243], v[204:207], v[0:3]
	v_mfma_f32_16x16x32_bf16 v[4:7], v[212:215], v[204:207], v[4:7]
	v_mfma_f32_16x16x32_bf16 v[4:7], v[208:211], v[200:203], v[4:7]
	s_setprio 0
	s_add_i32 s45, s45, 2
	s_add_u32 s20, s20, 0x100
	s_addc_u32 s21, s21, 0
	s_add_u32 s43, s43, 0x100
	s_addc_u32 s44, s44, 0
	s_cmp_gt_u32 s45, 29
	s_barrier
	s_cbranch_scc0 .LBB0_760
	v_lshl_add_u32 v217, s8, 8, v163
	v_add_u32_e32 v217, s35, v217
	v_lshlrev_b32_e32 v208, 2, v217
	v_lshl_add_u32 v214, v225, 3, s36
	v_lshl_add_u32 v214, s0, 8, v214
	v_lshl_add_u32 v209, v217, 11, v214
	v_lshlrev_b32_e32 v209, 1, v209
	v_lshlrev_b32_e32 v210, 1, v209
	v_lshl_add_u32 v217, v225, 4, v163
	v_xor_b32_e32 v215, 16, v217
	v_lshlrev_b32_e32 v215, 2, v215
	v_xor_b32_e32 v216, 32, v217
	v_lshlrev_b32_e32 v216, 2, v216
	v_add_u32_e32 v211, 0x0, v209
	global_load_dwordx4 v[176:179], v211, s[80:81]
	global_load_dwordx4 v[180:183], v211, s[80:81] offset:256
	v_add_u32_e32 v211, 0x10000, v209
	global_load_dwordx4 v[192:195], v211, s[80:81]
	global_load_dwordx4 v[196:199], v211, s[80:81] offset:256
	s_waitcnt vmcnt(2)
	v_lshlrev_b32_e32 v184, 16, v176
	v_and_b32_e32 v185, 0xffff0000, v176
	v_lshlrev_b32_e32 v186, 16, v177
	v_and_b32_e32 v187, 0xffff0000, v177
	v_lshlrev_b32_e32 v188, 16, v178
	v_and_b32_e32 v189, 0xffff0000, v178
	v_lshlrev_b32_e32 v190, 16, v179
	v_and_b32_e32 v191, 0xffff0000, v179
	v_pk_add_f32 v[124:125], v[124:125], v[184:185]
	v_pk_add_f32 v[126:127], v[126:127], v[186:187]
	v_pk_add_f32 v[120:121], v[120:121], v[188:189]
	v_pk_add_f32 v[122:123], v[122:123], v[190:191]
	v_mul_f32_e32 v213, v124, v124
	v_fmac_f32_e32 v213, v125, v125
	v_fmac_f32_e32 v213, v126, v126
	v_fmac_f32_e32 v213, v127, v127
	v_fmac_f32_e32 v213, v120, v120
	v_fmac_f32_e32 v213, v121, v121
	v_fmac_f32_e32 v213, v122, v122
	v_fmac_f32_e32 v213, v123, v123
	v_cvt_pk_bf16_f32 v176, v124, v125
	v_cvt_pk_bf16_f32 v177, v126, v127
	v_cvt_pk_bf16_f32 v178, v120, v121
	v_cvt_pk_bf16_f32 v179, v122, v123
	v_add_u32_e32 v217, 0x0, v209
	global_store_dwordx4 v217, v[176:179], s[80:81]
	v_lshlrev_b32_e32 v184, 16, v180
	v_and_b32_e32 v185, 0xffff0000, v180
	v_lshlrev_b32_e32 v186, 16, v181
	v_and_b32_e32 v187, 0xffff0000, v181
	v_lshlrev_b32_e32 v188, 16, v182
	v_and_b32_e32 v189, 0xffff0000, v182
	v_lshlrev_b32_e32 v190, 16, v183
	v_and_b32_e32 v191, 0xffff0000, v183
	v_pk_add_f32 v[116:117], v[116:117], v[184:185]
	v_pk_add_f32 v[118:119], v[118:119], v[186:187]
	v_pk_add_f32 v[112:113], v[112:113], v[188:189]
	v_pk_add_f32 v[114:115], v[114:115], v[190:191]
	v_fmac_f32_e32 v213, v116, v116
	v_fmac_f32_e32 v213, v117, v117
	v_fmac_f32_e32 v213, v118, v118
	v_fmac_f32_e32 v213, v119, v119
	v_fmac_f32_e32 v213, v112, v112
	v_fmac_f32_e32 v213, v113, v113
	v_fmac_f32_e32 v213, v114, v114
	v_fmac_f32_e32 v213, v115, v115
	v_cvt_pk_bf16_f32 v180, v116, v117
	v_cvt_pk_bf16_f32 v181, v118, v119
	v_cvt_pk_bf16_f32 v182, v112, v113
	v_cvt_pk_bf16_f32 v183, v114, v115
	global_store_dwordx4 v217, v[180:183], s[80:81] offset:256
	ds_bpermute_b32 v214, v215, v213
	s_waitcnt lgkmcnt(0)
	v_add_f32_e32 v213, v213, v214
	ds_bpermute_b32 v214, v216, v213
	s_waitcnt lgkmcnt(0)
	v_add_f32_e32 v213, v213, v214
	s_mov_b64 exec, 0xffff
	global_atomic_add_f32 v208, v213, s[4:5]
	s_mov_b64 exec, -1
	v_add_u32_e32 v211, 0x20000, v209
	global_load_dwordx4 v[176:179], v211, s[80:81]
	global_load_dwordx4 v[180:183], v211, s[80:81] offset:256
	s_waitcnt vmcnt(5)
	v_lshlrev_b32_e32 v200, 16, v192
	v_and_b32_e32 v201, 0xffff0000, v192
	v_lshlrev_b32_e32 v202, 16, v193
	v_and_b32_e32 v203, 0xffff0000, v193
	v_lshlrev_b32_e32 v204, 16, v194
	v_and_b32_e32 v205, 0xffff0000, v194
	v_lshlrev_b32_e32 v206, 16, v195
	v_and_b32_e32 v207, 0xffff0000, v195
	v_pk_add_f32 v[108:109], v[108:109], v[200:201]
	v_pk_add_f32 v[110:111], v[110:111], v[202:203]
	v_pk_add_f32 v[104:105], v[104:105], v[204:205]
	v_pk_add_f32 v[106:107], v[106:107], v[206:207]
	v_mul_f32_e32 v213, v108, v108
	v_fmac_f32_e32 v213, v109, v109
	v_fmac_f32_e32 v213, v110, v110
	v_fmac_f32_e32 v213, v111, v111
	v_fmac_f32_e32 v213, v104, v104
	v_fmac_f32_e32 v213, v105, v105
	v_fmac_f32_e32 v213, v106, v106
	v_fmac_f32_e32 v213, v107, v107
	v_cvt_pk_bf16_f32 v192, v108, v109
	v_cvt_pk_bf16_f32 v193, v110, v111
	v_cvt_pk_bf16_f32 v194, v104, v105
	v_cvt_pk_bf16_f32 v195, v106, v107
	v_add_u32_e32 v217, 0x10000, v209
	global_store_dwordx4 v217, v[192:195], s[80:81]
	v_lshlrev_b32_e32 v200, 16, v196
	v_and_b32_e32 v201, 0xffff0000, v196
	v_lshlrev_b32_e32 v202, 16, v197
	v_and_b32_e32 v203, 0xffff0000, v197
	v_lshlrev_b32_e32 v204, 16, v198
	v_and_b32_e32 v205, 0xffff0000, v198
	v_lshlrev_b32_e32 v206, 16, v199
	v_and_b32_e32 v207, 0xffff0000, v199
	v_pk_add_f32 v[100:101], v[100:101], v[200:201]
	v_pk_add_f32 v[102:103], v[102:103], v[202:203]
	v_pk_add_f32 v[96:97], v[96:97], v[204:205]
	v_pk_add_f32 v[98:99], v[98:99], v[206:207]
	v_fmac_f32_e32 v213, v100, v100
	v_fmac_f32_e32 v213, v101, v101
	v_fmac_f32_e32 v213, v102, v102
	v_fmac_f32_e32 v213, v103, v103
	v_fmac_f32_e32 v213, v96, v96
	v_fmac_f32_e32 v213, v97, v97
	v_fmac_f32_e32 v213, v98, v98
	v_fmac_f32_e32 v213, v99, v99
	v_cvt_pk_bf16_f32 v196, v100, v101
	v_cvt_pk_bf16_f32 v197, v102, v103
	v_cvt_pk_bf16_f32 v198, v96, v97
	v_cvt_pk_bf16_f32 v199, v98, v99
	global_store_dwordx4 v217, v[196:199], s[80:81] offset:256
	ds_bpermute_b32 v214, v215, v213
	s_waitcnt lgkmcnt(0)
	v_add_f32_e32 v213, v213, v214
	ds_bpermute_b32 v214, v216, v213
	s_waitcnt lgkmcnt(0)
	v_add_f32_e32 v213, v213, v214
	s_mov_b64 exec, 0xffff
	global_atomic_add_f32 v208, v213, s[4:5] offset:64
	s_mov_b64 exec, -1
	v_add_u32_e32 v211, 0x30000, v209
	global_load_dwordx4 v[192:195], v211, s[80:81]
	global_load_dwordx4 v[196:199], v211, s[80:81] offset:256
	s_waitcnt vmcnt(5)
	v_lshlrev_b32_e32 v184, 16, v176
	v_and_b32_e32 v185, 0xffff0000, v176
	v_lshlrev_b32_e32 v186, 16, v177
	v_and_b32_e32 v187, 0xffff0000, v177
	v_lshlrev_b32_e32 v188, 16, v178
	v_and_b32_e32 v189, 0xffff0000, v178
	v_lshlrev_b32_e32 v190, 16, v179
	v_and_b32_e32 v191, 0xffff0000, v179
	v_pk_add_f32 v[92:93], v[92:93], v[184:185]
	v_pk_add_f32 v[94:95], v[94:95], v[186:187]
	v_pk_add_f32 v[88:89], v[88:89], v[188:189]
	v_pk_add_f32 v[90:91], v[90:91], v[190:191]
	v_mul_f32_e32 v213, v92, v92
	v_fmac_f32_e32 v213, v93, v93
	v_fmac_f32_e32 v213, v94, v94
	v_fmac_f32_e32 v213, v95, v95
	v_fmac_f32_e32 v213, v88, v88
	v_fmac_f32_e32 v213, v89, v89
	v_fmac_f32_e32 v213, v90, v90
	v_fmac_f32_e32 v213, v91, v91
	v_cvt_pk_bf16_f32 v176, v92, v93
	v_cvt_pk_bf16_f32 v177, v94, v95
	v_cvt_pk_bf16_f32 v178, v88, v89
	v_cvt_pk_bf16_f32 v179, v90, v91
	v_add_u32_e32 v217, 0x20000, v209
	global_store_dwordx4 v217, v[176:179], s[80:81]
	v_lshlrev_b32_e32 v184, 16, v180
	v_and_b32_e32 v185, 0xffff0000, v180
	v_lshlrev_b32_e32 v186, 16, v181
	v_and_b32_e32 v187, 0xffff0000, v181
	v_lshlrev_b32_e32 v188, 16, v182
	v_and_b32_e32 v189, 0xffff0000, v182
	v_lshlrev_b32_e32 v190, 16, v183
	v_and_b32_e32 v191, 0xffff0000, v183
	v_pk_add_f32 v[84:85], v[84:85], v[184:185]
	v_pk_add_f32 v[86:87], v[86:87], v[186:187]
	v_pk_add_f32 v[80:81], v[80:81], v[188:189]
	v_pk_add_f32 v[82:83], v[82:83], v[190:191]
	v_fmac_f32_e32 v213, v84, v84
	v_fmac_f32_e32 v213, v85, v85
	v_fmac_f32_e32 v213, v86, v86
	v_fmac_f32_e32 v213, v87, v87
	v_fmac_f32_e32 v213, v80, v80
	v_fmac_f32_e32 v213, v81, v81
	v_fmac_f32_e32 v213, v82, v82
	v_fmac_f32_e32 v213, v83, v83
	v_cvt_pk_bf16_f32 v180, v84, v85
	v_cvt_pk_bf16_f32 v181, v86, v87
	v_cvt_pk_bf16_f32 v182, v80, v81
	v_cvt_pk_bf16_f32 v183, v82, v83
	global_store_dwordx4 v217, v[180:183], s[80:81] offset:256
	ds_bpermute_b32 v214, v215, v213
	s_waitcnt lgkmcnt(0)
	v_add_f32_e32 v213, v213, v214
	ds_bpermute_b32 v214, v216, v213
	s_waitcnt lgkmcnt(0)
	v_add_f32_e32 v213, v213, v214
	s_mov_b64 exec, 0xffff
	global_atomic_add_f32 v208, v213, s[4:5] offset:128
	s_mov_b64 exec, -1
	v_add_u32_e32 v211, 0x80000, v209
	global_load_dwordx4 v[176:179], v211, s[80:81]
	global_load_dwordx4 v[180:183], v211, s[80:81] offset:256
	s_waitcnt vmcnt(5)
	v_lshlrev_b32_e32 v200, 16, v192
	v_and_b32_e32 v201, 0xffff0000, v192
	v_lshlrev_b32_e32 v202, 16, v193
	v_and_b32_e32 v203, 0xffff0000, v193
	v_lshlrev_b32_e32 v204, 16, v194
	v_and_b32_e32 v205, 0xffff0000, v194
	v_lshlrev_b32_e32 v206, 16, v195
	v_and_b32_e32 v207, 0xffff0000, v195
	v_pk_add_f32 v[76:77], v[76:77], v[200:201]
	v_pk_add_f32 v[78:79], v[78:79], v[202:203]
	v_pk_add_f32 v[72:73], v[72:73], v[204:205]
	v_pk_add_f32 v[74:75], v[74:75], v[206:207]
	v_mul_f32_e32 v213, v76, v76
	v_fmac_f32_e32 v213, v77, v77
	v_fmac_f32_e32 v213, v78, v78
	v_fmac_f32_e32 v213, v79, v79
	v_fmac_f32_e32 v213, v72, v72
	v_fmac_f32_e32 v213, v73, v73
	v_fmac_f32_e32 v213, v74, v74
	v_fmac_f32_e32 v213, v75, v75
	v_cvt_pk_bf16_f32 v192, v76, v77
	v_cvt_pk_bf16_f32 v193, v78, v79
	v_cvt_pk_bf16_f32 v194, v72, v73
	v_cvt_pk_bf16_f32 v195, v74, v75
	v_add_u32_e32 v217, 0x30000, v209
	global_store_dwordx4 v217, v[192:195], s[80:81]
	v_lshlrev_b32_e32 v200, 16, v196
	v_and_b32_e32 v201, 0xffff0000, v196
	v_lshlrev_b32_e32 v202, 16, v197
	v_and_b32_e32 v203, 0xffff0000, v197
	v_lshlrev_b32_e32 v204, 16, v198
	v_and_b32_e32 v205, 0xffff0000, v198
	v_lshlrev_b32_e32 v206, 16, v199
	v_and_b32_e32 v207, 0xffff0000, v199
	v_pk_add_f32 v[68:69], v[68:69], v[200:201]
	v_pk_add_f32 v[70:71], v[70:71], v[202:203]
	v_pk_add_f32 v[64:65], v[64:65], v[204:205]
	v_pk_add_f32 v[66:67], v[66:67], v[206:207]
	v_fmac_f32_e32 v213, v68, v68
	v_fmac_f32_e32 v213, v69, v69
	v_fmac_f32_e32 v213, v70, v70
	v_fmac_f32_e32 v213, v71, v71
	v_fmac_f32_e32 v213, v64, v64
	v_fmac_f32_e32 v213, v65, v65
	v_fmac_f32_e32 v213, v66, v66
	v_fmac_f32_e32 v213, v67, v67
	v_cvt_pk_bf16_f32 v196, v68, v69
	v_cvt_pk_bf16_f32 v197, v70, v71
	v_cvt_pk_bf16_f32 v198, v64, v65
	v_cvt_pk_bf16_f32 v199, v66, v67
	global_store_dwordx4 v217, v[196:199], s[80:81] offset:256
	ds_bpermute_b32 v214, v215, v213
	s_waitcnt lgkmcnt(0)
	v_add_f32_e32 v213, v213, v214
	ds_bpermute_b32 v214, v216, v213
	s_waitcnt lgkmcnt(0)
	v_add_f32_e32 v213, v213, v214
	s_mov_b64 exec, 0xffff
	global_atomic_add_f32 v208, v213, s[4:5] offset:192
	s_mov_b64 exec, -1
	v_add_u32_e32 v211, 0x90000, v209
	global_load_dwordx4 v[192:195], v211, s[80:81]
	global_load_dwordx4 v[196:199], v211, s[80:81] offset:256
	s_waitcnt vmcnt(5)
	v_lshlrev_b32_e32 v184, 16, v176
	v_and_b32_e32 v185, 0xffff0000, v176
	v_lshlrev_b32_e32 v186, 16, v177
	v_and_b32_e32 v187, 0xffff0000, v177
	v_lshlrev_b32_e32 v188, 16, v178
	v_and_b32_e32 v189, 0xffff0000, v178
	v_lshlrev_b32_e32 v190, 16, v179
	v_and_b32_e32 v191, 0xffff0000, v179
	v_pk_add_f32 v[60:61], v[60:61], v[184:185]
	v_pk_add_f32 v[62:63], v[62:63], v[186:187]
	v_pk_add_f32 v[56:57], v[56:57], v[188:189]
	v_pk_add_f32 v[58:59], v[58:59], v[190:191]
	v_mul_f32_e32 v213, v60, v60
	v_fmac_f32_e32 v213, v61, v61
	v_fmac_f32_e32 v213, v62, v62
	v_fmac_f32_e32 v213, v63, v63
	v_fmac_f32_e32 v213, v56, v56
	v_fmac_f32_e32 v213, v57, v57
	v_fmac_f32_e32 v213, v58, v58
	v_fmac_f32_e32 v213, v59, v59
	v_cvt_pk_bf16_f32 v176, v60, v61
	v_cvt_pk_bf16_f32 v177, v62, v63
	v_cvt_pk_bf16_f32 v178, v56, v57
	v_cvt_pk_bf16_f32 v179, v58, v59
	v_add_u32_e32 v217, 0x80000, v209
	global_store_dwordx4 v217, v[176:179], s[80:81]
	v_lshlrev_b32_e32 v184, 16, v180
	v_and_b32_e32 v185, 0xffff0000, v180
	v_lshlrev_b32_e32 v186, 16, v181
	v_and_b32_e32 v187, 0xffff0000, v181
	v_lshlrev_b32_e32 v188, 16, v182
	v_and_b32_e32 v189, 0xffff0000, v182
	v_lshlrev_b32_e32 v190, 16, v183
	v_and_b32_e32 v191, 0xffff0000, v183
	v_pk_add_f32 v[52:53], v[52:53], v[184:185]
	v_pk_add_f32 v[54:55], v[54:55], v[186:187]
	v_pk_add_f32 v[48:49], v[48:49], v[188:189]
	v_pk_add_f32 v[50:51], v[50:51], v[190:191]
	v_fmac_f32_e32 v213, v52, v52
	v_fmac_f32_e32 v213, v53, v53
	v_fmac_f32_e32 v213, v54, v54
	v_fmac_f32_e32 v213, v55, v55
	v_fmac_f32_e32 v213, v48, v48
	v_fmac_f32_e32 v213, v49, v49
	v_fmac_f32_e32 v213, v50, v50
	v_fmac_f32_e32 v213, v51, v51
	v_cvt_pk_bf16_f32 v180, v52, v53
	v_cvt_pk_bf16_f32 v181, v54, v55
	v_cvt_pk_bf16_f32 v182, v48, v49
	v_cvt_pk_bf16_f32 v183, v50, v51
	global_store_dwordx4 v217, v[180:183], s[80:81] offset:256
	ds_bpermute_b32 v214, v215, v213
	s_waitcnt lgkmcnt(0)
	v_add_f32_e32 v213, v213, v214
	ds_bpermute_b32 v214, v216, v213
	s_waitcnt lgkmcnt(0)
	v_add_f32_e32 v213, v213, v214
	s_mov_b64 exec, 0xffff
	global_atomic_add_f32 v208, v213, s[4:5] offset:512
	s_mov_b64 exec, -1
	v_add_u32_e32 v211, 0xa0000, v209
	global_load_dwordx4 v[176:179], v211, s[80:81]
	global_load_dwordx4 v[180:183], v211, s[80:81] offset:256
	s_waitcnt vmcnt(5)
	v_lshlrev_b32_e32 v200, 16, v192
	v_and_b32_e32 v201, 0xffff0000, v192
	v_lshlrev_b32_e32 v202, 16, v193
	v_and_b32_e32 v203, 0xffff0000, v193
	v_lshlrev_b32_e32 v204, 16, v194
	v_and_b32_e32 v205, 0xffff0000, v194
	v_lshlrev_b32_e32 v206, 16, v195
	v_and_b32_e32 v207, 0xffff0000, v195
	v_pk_add_f32 v[44:45], v[44:45], v[200:201]
	v_pk_add_f32 v[46:47], v[46:47], v[202:203]
	v_pk_add_f32 v[40:41], v[40:41], v[204:205]
	v_pk_add_f32 v[42:43], v[42:43], v[206:207]
	v_mul_f32_e32 v213, v44, v44
	v_fmac_f32_e32 v213, v45, v45
	v_fmac_f32_e32 v213, v46, v46
	v_fmac_f32_e32 v213, v47, v47
	v_fmac_f32_e32 v213, v40, v40
	v_fmac_f32_e32 v213, v41, v41
	v_fmac_f32_e32 v213, v42, v42
	v_fmac_f32_e32 v213, v43, v43
	v_cvt_pk_bf16_f32 v192, v44, v45
	v_cvt_pk_bf16_f32 v193, v46, v47
	v_cvt_pk_bf16_f32 v194, v40, v41
	v_cvt_pk_bf16_f32 v195, v42, v43
	v_add_u32_e32 v217, 0x90000, v209
	global_store_dwordx4 v217, v[192:195], s[80:81]
	v_lshlrev_b32_e32 v200, 16, v196
	v_and_b32_e32 v201, 0xffff0000, v196
	v_lshlrev_b32_e32 v202, 16, v197
	v_and_b32_e32 v203, 0xffff0000, v197
	v_lshlrev_b32_e32 v204, 16, v198
	v_and_b32_e32 v205, 0xffff0000, v198
	v_lshlrev_b32_e32 v206, 16, v199
	v_and_b32_e32 v207, 0xffff0000, v199
	v_pk_add_f32 v[36:37], v[36:37], v[200:201]
	v_pk_add_f32 v[38:39], v[38:39], v[202:203]
	v_pk_add_f32 v[32:33], v[32:33], v[204:205]
	v_pk_add_f32 v[34:35], v[34:35], v[206:207]
	v_fmac_f32_e32 v213, v36, v36
	v_fmac_f32_e32 v213, v37, v37
	v_fmac_f32_e32 v213, v38, v38
	v_fmac_f32_e32 v213, v39, v39
	v_fmac_f32_e32 v213, v32, v32
	v_fmac_f32_e32 v213, v33, v33
	v_fmac_f32_e32 v213, v34, v34
	v_fmac_f32_e32 v213, v35, v35
	v_cvt_pk_bf16_f32 v196, v36, v37
	v_cvt_pk_bf16_f32 v197, v38, v39
	v_cvt_pk_bf16_f32 v198, v32, v33
	v_cvt_pk_bf16_f32 v199, v34, v35
	global_store_dwordx4 v217, v[196:199], s[80:81] offset:256
	ds_bpermute_b32 v214, v215, v213
	s_waitcnt lgkmcnt(0)
	v_add_f32_e32 v213, v213, v214
	ds_bpermute_b32 v214, v216, v213
	s_waitcnt lgkmcnt(0)
	v_add_f32_e32 v213, v213, v214
	s_mov_b64 exec, 0xffff
	global_atomic_add_f32 v208, v213, s[4:5] offset:576
	s_mov_b64 exec, -1
	v_add_u32_e32 v211, 0xb0000, v209
	global_load_dwordx4 v[192:195], v211, s[80:81]
	global_load_dwordx4 v[196:199], v211, s[80:81] offset:256
	s_waitcnt vmcnt(5)
	v_lshlrev_b32_e32 v184, 16, v176
	v_and_b32_e32 v185, 0xffff0000, v176
	v_lshlrev_b32_e32 v186, 16, v177
	v_and_b32_e32 v187, 0xffff0000, v177
	v_lshlrev_b32_e32 v188, 16, v178
	v_and_b32_e32 v189, 0xffff0000, v178
	v_lshlrev_b32_e32 v190, 16, v179
	v_and_b32_e32 v191, 0xffff0000, v179
	v_pk_add_f32 v[28:29], v[28:29], v[184:185]
	v_pk_add_f32 v[30:31], v[30:31], v[186:187]
	v_pk_add_f32 v[24:25], v[24:25], v[188:189]
	v_pk_add_f32 v[26:27], v[26:27], v[190:191]
	v_mul_f32_e32 v213, v28, v28
	v_fmac_f32_e32 v213, v29, v29
	v_fmac_f32_e32 v213, v30, v30
	v_fmac_f32_e32 v213, v31, v31
	v_fmac_f32_e32 v213, v24, v24
	v_fmac_f32_e32 v213, v25, v25
	v_fmac_f32_e32 v213, v26, v26
	v_fmac_f32_e32 v213, v27, v27
	v_cvt_pk_bf16_f32 v176, v28, v29
	v_cvt_pk_bf16_f32 v177, v30, v31
	v_cvt_pk_bf16_f32 v178, v24, v25
	v_cvt_pk_bf16_f32 v179, v26, v27
	v_add_u32_e32 v217, 0xa0000, v209
	global_store_dwordx4 v217, v[176:179], s[80:81]
	v_lshlrev_b32_e32 v184, 16, v180
	v_and_b32_e32 v185, 0xffff0000, v180
	v_lshlrev_b32_e32 v186, 16, v181
	v_and_b32_e32 v187, 0xffff0000, v181
	v_lshlrev_b32_e32 v188, 16, v182
	v_and_b32_e32 v189, 0xffff0000, v182
	v_lshlrev_b32_e32 v190, 16, v183
	v_and_b32_e32 v191, 0xffff0000, v183
	v_pk_add_f32 v[20:21], v[20:21], v[184:185]
	v_pk_add_f32 v[22:23], v[22:23], v[186:187]
	v_pk_add_f32 v[16:17], v[16:17], v[188:189]
	v_pk_add_f32 v[18:19], v[18:19], v[190:191]
	v_fmac_f32_e32 v213, v20, v20
	v_fmac_f32_e32 v213, v21, v21
	v_fmac_f32_e32 v213, v22, v22
	v_fmac_f32_e32 v213, v23, v23
	v_fmac_f32_e32 v213, v16, v16
	v_fmac_f32_e32 v213, v17, v17
	v_fmac_f32_e32 v213, v18, v18
	v_fmac_f32_e32 v213, v19, v19
	v_cvt_pk_bf16_f32 v180, v20, v21
	v_cvt_pk_bf16_f32 v181, v22, v23
	v_cvt_pk_bf16_f32 v182, v16, v17
	v_cvt_pk_bf16_f32 v183, v18, v19
	global_store_dwordx4 v217, v[180:183], s[80:81] offset:256
	ds_bpermute_b32 v214, v215, v213
	s_waitcnt lgkmcnt(0)
	v_add_f32_e32 v213, v213, v214
	ds_bpermute_b32 v214, v216, v213
	s_waitcnt lgkmcnt(0)
	v_add_f32_e32 v213, v213, v214
	s_mov_b64 exec, 0xffff
	global_atomic_add_f32 v208, v213, s[4:5] offset:640
	s_mov_b64 exec, -1
	s_waitcnt vmcnt(3)
	v_lshlrev_b32_e32 v200, 16, v192
	v_and_b32_e32 v201, 0xffff0000, v192
	v_lshlrev_b32_e32 v202, 16, v193
	v_and_b32_e32 v203, 0xffff0000, v193
	v_lshlrev_b32_e32 v204, 16, v194
	v_and_b32_e32 v205, 0xffff0000, v194
	v_lshlrev_b32_e32 v206, 16, v195
	v_and_b32_e32 v207, 0xffff0000, v195
	v_pk_add_f32 v[12:13], v[12:13], v[200:201]
	v_pk_add_f32 v[14:15], v[14:15], v[202:203]
	v_pk_add_f32 v[8:9], v[8:9], v[204:205]
	v_pk_add_f32 v[10:11], v[10:11], v[206:207]
	v_mul_f32_e32 v213, v12, v12
	v_fmac_f32_e32 v213, v13, v13
	v_fmac_f32_e32 v213, v14, v14
	v_fmac_f32_e32 v213, v15, v15
	v_fmac_f32_e32 v213, v8, v8
	v_fmac_f32_e32 v213, v9, v9
	v_fmac_f32_e32 v213, v10, v10
	v_fmac_f32_e32 v213, v11, v11
	v_cvt_pk_bf16_f32 v192, v12, v13
	v_cvt_pk_bf16_f32 v193, v14, v15
	v_cvt_pk_bf16_f32 v194, v8, v9
	v_cvt_pk_bf16_f32 v195, v10, v11
	v_add_u32_e32 v217, 0xb0000, v209
	global_store_dwordx4 v217, v[192:195], s[80:81]
	v_lshlrev_b32_e32 v200, 16, v196
	v_and_b32_e32 v201, 0xffff0000, v196
	v_lshlrev_b32_e32 v202, 16, v197
	v_and_b32_e32 v203, 0xffff0000, v197
	v_lshlrev_b32_e32 v204, 16, v198
	v_and_b32_e32 v205, 0xffff0000, v198
	v_lshlrev_b32_e32 v206, 16, v199
	v_and_b32_e32 v207, 0xffff0000, v199
	v_pk_add_f32 v[4:5], v[4:5], v[200:201]
	v_pk_add_f32 v[6:7], v[6:7], v[202:203]
	v_pk_add_f32 v[0:1], v[0:1], v[204:205]
	v_pk_add_f32 v[2:3], v[2:3], v[206:207]
	v_fmac_f32_e32 v213, v4, v4
	v_fmac_f32_e32 v213, v5, v5
	v_fmac_f32_e32 v213, v6, v6
	v_fmac_f32_e32 v213, v7, v7
	v_fmac_f32_e32 v213, v0, v0
	v_fmac_f32_e32 v213, v1, v1
	v_fmac_f32_e32 v213, v2, v2
	v_fmac_f32_e32 v213, v3, v3
	v_cvt_pk_bf16_f32 v196, v4, v5
	v_cvt_pk_bf16_f32 v197, v6, v7
	v_cvt_pk_bf16_f32 v198, v0, v1
	v_cvt_pk_bf16_f32 v199, v2, v3
	global_store_dwordx4 v217, v[196:199], s[80:81] offset:256
	ds_bpermute_b32 v214, v215, v213
	s_waitcnt lgkmcnt(0)
	v_add_f32_e32 v213, v213, v214
	ds_bpermute_b32 v214, v216, v213
	s_waitcnt lgkmcnt(0)
	v_add_f32_e32 v213, v213, v214
	s_mov_b64 exec, 0xffff
	global_atomic_add_f32 v208, v213, s[4:5] offset:704
	s_mov_b64 exec, -1
	s_branch .LBB0_752

.LBB0_840:
	ds_read_b128 v[76:79], v171
	v_xor_b32_e32 v91, 64, v171
	ds_read_b128 v[80:83], v91
	ds_read_b128 v[84:87], v171 offset:2048
	ds_read_b128 v[88:91], v91 offset:2048
	s_add_u32 s10, s8, 0x100
	s_addc_u32 s11, s9, 0
	s_cmp_eq_u32 s67, 28
	s_cselect_b32 s43, s33, s11
	s_cselect_b32 s42, s37, s10
	s_cselect_b32 s13, s35, s66
	s_cselect_b32 s12, s64, s65
	v_lshl_add_u64 v[108:109], s[8:9], 0, v[180:181]
	s_add_i32 m0, s48, 0xc000
	ds_read_b128 v[92:95], v173
	v_xor_b32_e32 v203, 64, v173
	ds_read_b128 v[96:99], v203
	ds_read_b128 v[100:103], v173 offset:2048
	ds_read_b128 v[104:107], v203 offset:2048
	ds_read_b128 v[188:191], v173 offset:4096
	ds_read_b128 v[192:195], v203 offset:4096
	ds_read_b128 v[196:199], v173 offset:6144
	ds_read_b128 v[200:203], v203 offset:6144
	global_load_lds_dwordx4 v[108:109], off
	v_lshl_add_u64 v[108:109], s[8:9], 0, v[182:183]
	s_add_i32 m0, s48, 0xe000
	s_nop 0
	global_load_lds_dwordx4 v[108:109], off
	s_waitcnt lgkmcnt(8)
	s_barrier
	s_waitcnt lgkmcnt(0)
	s_setprio 1
	s_waitcnt lgkmcnt(0)
	v_mfma_f32_16x16x32_bf16 v[158:161], v[76:79], v[92:95], v[158:161]
	v_mfma_f32_16x16x32_bf16 v[158:161], v[80:83], v[96:99], v[158:161]
	v_mfma_f32_16x16x32_bf16 v[60:63], v[88:91], v[96:99], v[60:63]
	v_mfma_f32_16x16x32_bf16 v[60:63], v[84:87], v[92:95], v[60:63]
	v_mfma_f32_16x16x32_bf16 v[52:55], v[84:87], v[100:103], v[52:55]
	v_mfma_f32_16x16x32_bf16 v[52:55], v[88:91], v[104:107], v[52:55]
	v_mfma_f32_16x16x32_bf16 v[150:153], v[80:83], v[104:107], v[150:153]
	v_mfma_f32_16x16x32_bf16 v[150:153], v[76:79], v[100:103], v[150:153]
	v_mfma_f32_16x16x32_bf16 v[146:149], v[76:79], v[188:191], v[146:149]
	v_mfma_f32_16x16x32_bf16 v[146:149], v[80:83], v[192:195], v[146:149]
	v_mfma_f32_16x16x32_bf16 v[48:51], v[88:91], v[192:195], v[48:51]
	v_mfma_f32_16x16x32_bf16 v[48:51], v[84:87], v[188:191], v[48:51]
	v_mfma_f32_16x16x32_bf16 v[40:43], v[84:87], v[196:199], v[40:43]
	v_mfma_f32_16x16x32_bf16 v[40:43], v[88:91], v[200:203], v[40:43]
	v_mfma_f32_16x16x32_bf16 v[138:141], v[80:83], v[200:203], v[138:141]
	v_mfma_f32_16x16x32_bf16 v[138:141], v[76:79], v[196:199], v[138:141]
	s_setprio 0
	s_barrier
	s_add_i32 s8, s60, s46
	v_lshl_add_u64 v[220:221], s[12:13], 0, v[164:165]
	s_mov_b32 m0, s8
	ds_read_b128 v[204:207], v175
	v_xor_b32_e32 v219, 64, v175
	ds_read_b128 v[208:211], v219
	ds_read_b128 v[212:215], v175 offset:2048
	ds_read_b128 v[216:219], v219 offset:2048
	global_load_lds_dwordx4 v[220:221], off
	v_lshl_add_u64 v[238:239], s[12:13], 0, v[166:167]
	s_add_i32 m0, s8, 0x2000
	s_nop 0
	global_load_lds_dwordx4 v[238:239], off
	s_barrier
	s_waitcnt lgkmcnt(0)
	s_setprio 1
	s_waitcnt lgkmcnt(0)
	v_mfma_f32_16x16x32_bf16 v[154:157], v[204:207], v[92:95], v[154:157]
	v_mfma_f32_16x16x32_bf16 v[154:157], v[208:211], v[96:99], v[154:157]
	v_mfma_f32_16x16x32_bf16 v[56:59], v[216:219], v[96:99], v[56:59]
	v_mfma_f32_16x16x32_bf16 v[56:59], v[212:215], v[92:95], v[56:59]
	v_mfma_f32_16x16x32_bf16 v[44:47], v[212:215], v[100:103], v[44:47]
	v_mfma_f32_16x16x32_bf16 v[44:47], v[216:219], v[104:107], v[44:47]
	v_mfma_f32_16x16x32_bf16 v[36:39], v[216:219], v[192:195], v[36:39]
	v_mfma_f32_16x16x32_bf16 v[36:39], v[212:215], v[188:191], v[36:39]
	v_mfma_f32_16x16x32_bf16 v[32:35], v[212:215], v[196:199], v[32:35]
	v_mfma_f32_16x16x32_bf16 v[32:35], v[216:219], v[200:203], v[32:35]
	v_mfma_f32_16x16x32_bf16 v[92:95], v[204:207], v[100:103], v[142:145]
	v_mfma_f32_16x16x32_bf16 v[92:95], v[208:211], v[104:107], v[92:95]
	v_mfma_f32_16x16x32_bf16 v[96:99], v[208:211], v[192:195], v[134:137]
	v_mfma_f32_16x16x32_bf16 v[96:99], v[204:207], v[188:191], v[96:99]
	v_mfma_f32_16x16x32_bf16 v[100:103], v[204:207], v[196:199], v[130:133]
	v_mfma_f32_16x16x32_bf16 v[100:103], v[208:211], v[200:203], v[100:103]
	s_setprio 0
	s_mov_b32 m0, s48
	v_lshl_add_u64 v[240:241], s[42:43], 0, v[178:179]
	s_barrier
	ds_read_b128 v[104:107], v173 offset:16384
	v_xor_b32_e32 v203, 64, v173
	ds_read_b128 v[130:133], v203 offset:16384
	ds_read_b128 v[134:137], v173 offset:18432
	ds_read_b128 v[142:145], v203 offset:18432
	ds_read_b128 v[188:191], v173 offset:20480
	ds_read_b128 v[192:195], v203 offset:20480
	ds_read_b128 v[196:199], v173 offset:22528
	ds_read_b128 v[200:203], v203 offset:22528
	global_load_lds_dwordx4 v[240:241], off
	v_lshl_add_u64 v[242:243], s[42:43], 0, v[176:177]
	s_mov_b32 m0, s49
	s_nop 0
	global_load_lds_dwordx4 v[242:243], off
	s_barrier
	s_waitcnt lgkmcnt(0)
	s_setprio 1
	s_waitcnt lgkmcnt(0)
	v_mfma_f32_16x16x32_bf16 v[126:129], v[76:79], v[104:107], v[126:129]
	v_mfma_f32_16x16x32_bf16 v[126:129], v[80:83], v[130:133], v[126:129]
	v_mfma_f32_16x16x32_bf16 v[28:31], v[88:91], v[130:133], v[28:31]
	v_mfma_f32_16x16x32_bf16 v[28:31], v[84:87], v[104:107], v[28:31]
	v_mfma_f32_16x16x32_bf16 v[24:27], v[84:87], v[134:137], v[24:27]
	v_mfma_f32_16x16x32_bf16 v[24:27], v[88:91], v[142:145], v[24:27]
	v_mfma_f32_16x16x32_bf16 v[122:125], v[80:83], v[142:145], v[122:125]
	v_mfma_f32_16x16x32_bf16 v[122:125], v[76:79], v[134:137], v[122:125]
	v_mfma_f32_16x16x32_bf16 v[114:117], v[76:79], v[188:191], v[114:117]
	v_mfma_f32_16x16x32_bf16 v[114:117], v[80:83], v[192:195], v[114:117]
	v_mfma_f32_16x16x32_bf16 v[20:23], v[88:91], v[192:195], v[20:23]
	v_mfma_f32_16x16x32_bf16 v[20:23], v[84:87], v[188:191], v[20:23]
	v_mfma_f32_16x16x32_bf16 v[4:7], v[84:87], v[196:199], v[4:7]
	v_mfma_f32_16x16x32_bf16 v[4:7], v[88:91], v[200:203], v[4:7]
	v_mfma_f32_16x16x32_bf16 v[72:75], v[80:83], v[200:203], v[72:75]
	v_mfma_f32_16x16x32_bf16 v[72:75], v[76:79], v[196:199], v[72:75]
	s_setprio 0
	s_barrier
	s_add_u32 s8, s12, 0x1600000
	s_addc_u32 s9, s13, 0
	s_add_i32 s68, s61, s46
	v_lshl_add_u64 v[76:77], s[8:9], 0, v[164:165]
	s_mov_b32 m0, s68
	s_nop 0
	global_load_lds_dwordx4 v[76:77], off
	v_lshl_add_u64 v[76:77], s[8:9], 0, v[166:167]
	s_add_i32 m0, s68, 0x2000
	s_nop 0
	global_load_lds_dwordx4 v[76:77], off
	s_waitcnt vmcnt(6)
	s_barrier
	s_setprio 1
	v_mfma_f32_16x16x32_bf16 v[16:19], v[212:215], v[104:107], v[16:19]
	v_mfma_f32_16x16x32_bf16 v[16:19], v[216:219], v[130:133], v[16:19]
	v_mfma_f32_16x16x32_bf16 v[12:15], v[216:219], v[142:145], v[12:15]
	v_mfma_f32_16x16x32_bf16 v[12:15], v[212:215], v[134:137], v[12:15]
	v_mfma_f32_16x16x32_bf16 v[8:11], v[212:215], v[188:191], v[8:11]
	v_mfma_f32_16x16x32_bf16 v[8:11], v[216:219], v[192:195], v[8:11]
	v_mfma_f32_16x16x32_bf16 v[68:71], v[208:211], v[192:195], v[68:71]
	v_mfma_f32_16x16x32_bf16 v[68:71], v[204:207], v[188:191], v[68:71]
	v_mfma_f32_16x16x32_bf16 v[64:67], v[204:207], v[196:199], v[64:67]
	v_mfma_f32_16x16x32_bf16 v[64:67], v[208:211], v[200:203], v[64:67]
	v_mfma_f32_16x16x32_bf16 v[0:3], v[216:219], v[200:203], v[0:3]
	v_mfma_f32_16x16x32_bf16 v[0:3], v[212:215], v[196:199], v[0:3]
	v_mfma_f32_16x16x32_bf16 v[76:79], v[204:207], v[104:107], v[118:121]
	v_mfma_f32_16x16x32_bf16 v[76:79], v[208:211], v[130:133], v[76:79]
	v_mfma_f32_16x16x32_bf16 v[80:83], v[208:211], v[142:145], v[110:113]
	v_mfma_f32_16x16x32_bf16 v[80:83], v[204:207], v[134:137], v[80:83]
	s_setprio 0
	s_add_i32 s68, 0, 0x18000
	v_add_u32_e32 v108, s68, v169
	s_barrier
	ds_read_b128 v[84:87], v108
	v_xor_b32_e32 v111, 64, v108
	ds_read_b128 v[88:91], v111
	ds_read_b128 v[104:107], v108 offset:2048
	ds_read_b128 v[108:111], v111 offset:2048
	s_add_u32 s8, s42, 0x40000
	s_addc_u32 s9, s43, 0
	s_mov_b32 m0, s50
	v_lshl_add_u64 v[112:113], s[8:9], 0, v[178:179]
	ds_read_b128 v[118:121], v173 offset:32768
	v_xor_b32_e32 v207, 64, v173
	ds_read_b128 v[130:133], v207 offset:32768
	ds_read_b128 v[134:137], v173 offset:34816
	ds_read_b128 v[188:191], v207 offset:34816
	ds_read_b128 v[192:195], v173 offset:36864
	ds_read_b128 v[196:199], v207 offset:36864
	ds_read_b128 v[200:203], v173 offset:38912
	ds_read_b128 v[204:207], v207 offset:38912
	global_load_lds_dwordx4 v[112:113], off
	v_lshl_add_u64 v[112:113], s[8:9], 0, v[176:177]
	s_mov_b32 m0, s51
	s_nop 0
	global_load_lds_dwordx4 v[112:113], off
	s_waitcnt lgkmcnt(8)
	s_barrier
	s_waitcnt lgkmcnt(0)
	s_setprio 1
	s_waitcnt lgkmcnt(0)
	v_mfma_f32_16x16x32_bf16 v[142:145], v[84:87], v[118:121], v[158:161]
	v_mfma_f32_16x16x32_bf16 v[158:161], v[88:91], v[130:133], v[142:145]
	v_mfma_f32_16x16x32_bf16 v[60:63], v[108:111], v[130:133], v[60:63]
	v_mfma_f32_16x16x32_bf16 v[60:63], v[104:107], v[118:121], v[60:63]
	v_mfma_f32_16x16x32_bf16 v[52:55], v[104:107], v[134:137], v[52:55]
	v_mfma_f32_16x16x32_bf16 v[52:55], v[108:111], v[188:191], v[52:55]
	v_mfma_f32_16x16x32_bf16 v[48:51], v[108:111], v[196:199], v[48:51]
	v_mfma_f32_16x16x32_bf16 v[48:51], v[104:107], v[192:195], v[48:51]
	v_mfma_f32_16x16x32_bf16 v[40:43], v[104:107], v[200:203], v[40:43]
	v_mfma_f32_16x16x32_bf16 v[40:43], v[108:111], v[204:207], v[40:43]
	v_mfma_f32_16x16x32_bf16 v[138:141], v[88:91], v[204:207], v[138:141]
	v_mfma_f32_16x16x32_bf16 v[138:141], v[84:87], v[200:203], v[138:141]
	v_mfma_f32_16x16x32_bf16 v[142:145], v[84:87], v[134:137], v[150:153]
	v_mfma_f32_16x16x32_bf16 v[150:153], v[88:91], v[188:191], v[142:145]
	v_mfma_f32_16x16x32_bf16 v[142:145], v[84:87], v[192:195], v[146:149]
	v_mfma_f32_16x16x32_bf16 v[146:149], v[88:91], v[196:199], v[142:145]
	s_setprio 0
	s_barrier
	s_add_i32 s42, 0, 0x1c000
	v_add_u32_e32 v112, s42, v169
	s_add_i32 s8, s68, s46
	ds_read_b128 v[208:211], v112
	v_xor_b32_e32 v237, 64, v112
	ds_read_b128 v[212:215], v237
	ds_read_b128 v[216:219], v112 offset:2048
	ds_read_b128 v[234:237], v237 offset:2048
	v_lshl_add_u64 v[112:113], v[220:221], 0, s[18:19]
	s_mov_b32 m0, s8
	s_nop 0
	global_load_lds_dwordx4 v[112:113], off
	v_lshl_add_u64 v[112:113], v[238:239], 0, s[18:19]
	s_add_i32 m0, s8, 0x2000
	s_nop 0
	global_load_lds_dwordx4 v[112:113], off
	s_barrier
	s_waitcnt lgkmcnt(0)
	s_setprio 1
	s_waitcnt lgkmcnt(0)
	v_mfma_f32_16x16x32_bf16 v[142:145], v[208:211], v[118:121], v[154:157]
	v_mfma_f32_16x16x32_bf16 v[154:157], v[212:215], v[130:133], v[142:145]
	v_mfma_f32_16x16x32_bf16 v[56:59], v[234:237], v[130:133], v[56:59]
	v_mfma_f32_16x16x32_bf16 v[56:59], v[216:219], v[118:121], v[56:59]
	v_mfma_f32_16x16x32_bf16 v[44:47], v[216:219], v[134:137], v[44:47]
	v_mfma_f32_16x16x32_bf16 v[44:47], v[234:237], v[188:191], v[44:47]
	v_mfma_f32_16x16x32_bf16 v[36:39], v[234:237], v[196:199], v[36:39]
	v_mfma_f32_16x16x32_bf16 v[36:39], v[216:219], v[192:195], v[36:39]
	v_mfma_f32_16x16x32_bf16 v[32:35], v[216:219], v[200:203], v[32:35]
	v_mfma_f32_16x16x32_bf16 v[32:35], v[234:237], v[204:207], v[32:35]
	v_mfma_f32_16x16x32_bf16 v[92:95], v[208:211], v[134:137], v[92:95]
	v_mfma_f32_16x16x32_bf16 v[142:145], v[212:215], v[188:191], v[92:95]
	v_mfma_f32_16x16x32_bf16 v[92:95], v[208:211], v[192:195], v[96:99]
	v_mfma_f32_16x16x32_bf16 v[134:137], v[212:215], v[196:199], v[92:95]
	v_mfma_f32_16x16x32_bf16 v[92:95], v[208:211], v[200:203], v[100:103]
	v_mfma_f32_16x16x32_bf16 v[130:133], v[212:215], v[204:207], v[92:95]
	s_setprio 0
	s_mov_b32 m0, s54
	v_lshl_add_u64 v[112:113], v[240:241], 0, s[18:19]
	s_barrier
	ds_read_b128 v[92:95], v173 offset:49152
	v_xor_b32_e32 v207, 64, v173
	ds_read_b128 v[96:99], v207 offset:49152
	ds_read_b128 v[100:103], v173 offset:51200
	ds_read_b128 v[188:191], v207 offset:51200
	ds_read_b128 v[192:195], v173 offset:53248
	ds_read_b128 v[196:199], v207 offset:53248
	ds_read_b128 v[200:203], v173 offset:55296
	ds_read_b128 v[204:207], v207 offset:55296
	global_load_lds_dwordx4 v[112:113], off
	v_lshl_add_u64 v[112:113], v[242:243], 0, s[18:19]
	s_mov_b32 m0, s55
	s_nop 0
	global_load_lds_dwordx4 v[112:113], off
	s_barrier
	s_waitcnt lgkmcnt(0)
	s_setprio 1
	s_waitcnt lgkmcnt(0)
	v_mfma_f32_16x16x32_bf16 v[118:121], v[84:87], v[92:95], v[126:129]
	v_mfma_f32_16x16x32_bf16 v[126:129], v[88:91], v[96:99], v[118:121]
	v_mfma_f32_16x16x32_bf16 v[28:31], v[108:111], v[96:99], v[28:31]
	v_mfma_f32_16x16x32_bf16 v[28:31], v[104:107], v[92:95], v[28:31]
	v_mfma_f32_16x16x32_bf16 v[24:27], v[104:107], v[100:103], v[24:27]
	v_mfma_f32_16x16x32_bf16 v[24:27], v[108:111], v[188:191], v[24:27]
	v_mfma_f32_16x16x32_bf16 v[20:23], v[108:111], v[196:199], v[20:23]
	v_mfma_f32_16x16x32_bf16 v[20:23], v[104:107], v[192:195], v[20:23]
	v_mfma_f32_16x16x32_bf16 v[112:115], v[84:87], v[192:195], v[114:117]
	v_mfma_f32_16x16x32_bf16 v[114:117], v[88:91], v[196:199], v[112:115]
	v_mfma_f32_16x16x32_bf16 v[72:75], v[88:91], v[204:207], v[72:75]
	v_mfma_f32_16x16x32_bf16 v[72:75], v[84:87], v[200:203], v[72:75]
	v_mfma_f32_16x16x32_bf16 v[118:121], v[84:87], v[100:103], v[122:125]
	v_mfma_f32_16x16x32_bf16 v[122:125], v[88:91], v[188:191], v[118:121]
	v_mfma_f32_16x16x32_bf16 v[4:7], v[104:107], v[200:203], v[4:7]
	v_mfma_f32_16x16x32_bf16 v[4:7], v[108:111], v[204:207], v[4:7]
	s_setprio 0
	s_barrier
	s_add_u32 s8, s12, 0x1600080
	s_addc_u32 s9, s13, 0
	s_add_i32 s12, s42, s46
	v_lshl_add_u64 v[84:85], s[8:9], 0, v[164:165]
	s_mov_b32 m0, s12
	s_nop 0
	global_load_lds_dwordx4 v[84:85], off
	v_lshl_add_u64 v[84:85], s[8:9], 0, v[166:167]
	s_add_i32 m0, s12, 0x2000
	s_nop 0
	global_load_lds_dwordx4 v[84:85], off
	s_waitcnt vmcnt(6)
	s_barrier
	s_setprio 1
	v_mfma_f32_16x16x32_bf16 v[76:79], v[208:211], v[92:95], v[76:79]
	v_mfma_f32_16x16x32_bf16 v[118:121], v[212:215], v[96:99], v[76:79]
	v_mfma_f32_16x16x32_bf16 v[16:19], v[234:237], v[96:99], v[16:19]
	v_mfma_f32_16x16x32_bf16 v[16:19], v[216:219], v[92:95], v[16:19]
	v_mfma_f32_16x16x32_bf16 v[12:15], v[216:219], v[100:103], v[12:15]
	v_mfma_f32_16x16x32_bf16 v[12:15], v[234:237], v[188:191], v[12:15]
	v_mfma_f32_16x16x32_bf16 v[8:11], v[234:237], v[196:199], v[8:11]
	v_mfma_f32_16x16x32_bf16 v[8:11], v[216:219], v[192:195], v[8:11]
	v_mfma_f32_16x16x32_bf16 v[68:71], v[208:211], v[192:195], v[68:71]
	v_mfma_f32_16x16x32_bf16 v[68:71], v[212:215], v[196:199], v[68:71]
	v_mfma_f32_16x16x32_bf16 v[64:67], v[212:215], v[204:207], v[64:67]
	v_mfma_f32_16x16x32_bf16 v[64:67], v[208:211], v[200:203], v[64:67]
	v_mfma_f32_16x16x32_bf16 v[76:79], v[208:211], v[100:103], v[80:83]
	v_mfma_f32_16x16x32_bf16 v[110:113], v[212:215], v[188:191], v[76:79]
	v_mfma_f32_16x16x32_bf16 v[0:3], v[216:219], v[200:203], v[0:3]
	v_mfma_f32_16x16x32_bf16 v[0:3], v[234:237], v[204:207], v[0:3]
	s_setprio 0
	s_add_i32 s67, s67, 2
	s_add_u32 s65, s65, 0x100
	s_addc_u32 s66, s66, 0
	s_cmp_gt_u32 s67, 29
	s_mov_b64 s[8:9], s[10:11]
	s_barrier
	s_cbranch_scc0 .LBB0_840
	s_lshl_b32 s8, s0, 8
	s_lshl_b32 s1, s1, 7
	v_mov_b32_e32 v80, v225
	v_mov_b32_e32 v193, v163
	s_add_i32 s8, s8, s58
	s_or_b32 s1, s1, s53
	s_lshl_b32 s0, s0, 3
	v_add_u32_e32 v190, s8, v193
	v_lshl_add_u32 v188, v80, 3, s1
	v_ashrrev_i32_e32 v191, 31, v190
	v_ashrrev_i32_e32 v189, 31, v188
	v_lshl_add_u64 v[78:79], v[190:191], 2, s[4:5]
	v_lshlrev_b64 v[90:91], 2, v[188:189]
	global_load_dword v196, v[78:79], off
	global_load_dword v192, v[78:79], off offset:64
	global_load_dword v194, v[78:79], off offset:128
	global_load_dword v200, v[78:79], off offset:192
	global_load_dword v199, v[78:79], off offset:256
	global_load_dword v77, v[78:79], off offset:320
	global_load_dword v76, v[78:79], off offset:384
	global_load_dword v191, v[78:79], off offset:448
	v_lshl_add_u64 v[78:79], s[14:15], 0, v[90:91]
	v_lshl_add_u64 v[80:81], s[20:21], 0, v[90:91]
	global_load_dwordx4 v[102:105], v[78:79], off
	global_load_dwordx4 v[94:97], v[80:81], off
	v_lshl_add_u64 v[78:79], s[22:23], 0, v[90:91]
	global_load_dwordx4 v[98:101], v[78:79], off
	v_lshl_add_u64 v[78:79], s[16:17], 0, v[90:91]
	global_load_dwordx4 v[106:109], v[78:79], off
	v_lshl_add_u64 v[78:79], s[24:25], 0, v[90:91]
	v_lshl_add_u64 v[80:81], s[26:27], 0, v[90:91]
	v_lshl_add_u64 v[82:83], s[28:29], 0, v[90:91]
	v_lshl_add_u64 v[90:91], s[30:31], 0, v[90:91]
	global_load_dwordx4 v[86:89], v[78:79], off
	s_nop 0
	global_load_dwordx4 v[78:81], v[80:81], off
	s_add_i32 s0, s0, s59
	global_load_dwordx4 v[82:85], v[82:83], off
	v_add_u32_e32 v195, s0, v193
	global_load_dwordx4 v[90:93], v[90:91], off
	v_cmp_gt_i32_e64 s[12:13], 2, v193
	s_waitcnt vmcnt(0)
	v_fmamk_f32 v196, v196, 0x3a000000, v230
	v_rsq_f32_e32 v198, v196
	v_mad_i64_i32 v[196:197], s[0:1], v195, s62, 0
	v_lshl_add_u64 v[196:197], s[70:71], 0, v[196:197]
	v_pk_mul_f32 v[160:161], v[160:161], v[198:199] op_sel_hi:[1,0]
	v_pk_mul_f32 v[158:159], v[158:159], v[198:199] op_sel_hi:[1,0]
	v_pk_mul_f32 v[156:157], v[156:157], v[198:199] op_sel_hi:[1,0]
	v_pk_mul_f32 v[154:155], v[154:155], v[198:199] op_sel_hi:[1,0]
	v_lshl_add_u64 v[196:197], v[188:189], 2, v[196:197]
	s_and_saveexec_b64 s[0:1], s[12:13]
	s_cbranch_execz .LBB0_843
	v_add_co_u32_e32 v202, vcc, 0x5000, v196
	global_store_dwordx4 v[196:197], v[158:161], off
	s_nop 0
	v_addc_co_u32_e32 v203, vcc, 0, v197, vcc
	global_store_dwordx4 v[202:203], v[154:157], off offset:2048

.LBB0_985:
	ds_read_b128 v[136:139], v141
	v_xor_b32_e32 v157, 64, v141
	ds_read_b128 v[146:149], v157
	ds_read_b128 v[150:153], v141 offset:2048
	ds_read_b128 v[154:157], v157 offset:2048
	s_add_u32 s14, s0, 0xffea0080
	s_addc_u32 s15, s1, -1
	s_cmpk_eq_i32 s41, 0x54
	s_cselect_b32 s17, s5, s15
	s_cselect_b32 s16, s4, s14
	s_cselect_b32 s15, s7, s40
	s_cselect_b32 s14, s6, s39
	v_lshl_add_u64 v[200:201], s[0:1], 0, v[128:129]
	s_add_i32 m0, s21, 0xc000
	ds_read_b128 v[158:161], v142
	v_xor_b32_e32 v199, 64, v142
	ds_read_b128 v[164:167], v199
	ds_read_b128 v[176:179], v142 offset:2048
	ds_read_b128 v[180:183], v199 offset:2048
	ds_read_b128 v[184:187], v142 offset:4096
	ds_read_b128 v[188:191], v199 offset:4096
	ds_read_b128 v[192:195], v142 offset:6144
	ds_read_b128 v[196:199], v199 offset:6144
	global_load_lds_dwordx4 v[200:201], off
	v_lshl_add_u64 v[200:201], s[0:1], 0, v[130:131]
	s_add_i32 m0, s21, 0xe000
	s_nop 0
	global_load_lds_dwordx4 v[200:201], off
	s_waitcnt lgkmcnt(8)
	s_barrier
	s_waitcnt lgkmcnt(0)
	s_setprio 1
	s_waitcnt lgkmcnt(0)
	v_mfma_f32_16x16x32_bf16 v[124:127], v[136:139], v[158:161], v[124:127]
	v_mfma_f32_16x16x32_bf16 v[124:127], v[146:149], v[164:167], v[124:127]
	v_mfma_f32_16x16x32_bf16 v[120:123], v[154:157], v[164:167], v[120:123]
	v_mfma_f32_16x16x32_bf16 v[120:123], v[150:153], v[158:161], v[120:123]
	v_mfma_f32_16x16x32_bf16 v[104:107], v[150:153], v[176:179], v[104:107]
	v_mfma_f32_16x16x32_bf16 v[104:107], v[154:157], v[180:183], v[104:107]
	v_mfma_f32_16x16x32_bf16 v[108:111], v[146:149], v[180:183], v[108:111]
	v_mfma_f32_16x16x32_bf16 v[108:111], v[136:139], v[176:179], v[108:111]
	v_mfma_f32_16x16x32_bf16 v[92:95], v[136:139], v[184:187], v[92:95]
	v_mfma_f32_16x16x32_bf16 v[92:95], v[146:149], v[188:191], v[92:95]
	v_mfma_f32_16x16x32_bf16 v[88:91], v[154:157], v[188:191], v[88:91]
	v_mfma_f32_16x16x32_bf16 v[88:91], v[150:153], v[184:187], v[88:91]
	v_mfma_f32_16x16x32_bf16 v[72:75], v[150:153], v[192:195], v[72:75]
	v_mfma_f32_16x16x32_bf16 v[72:75], v[154:157], v[196:199], v[72:75]
	v_mfma_f32_16x16x32_bf16 v[76:79], v[146:149], v[196:199], v[76:79]
	v_mfma_f32_16x16x32_bf16 v[76:79], v[136:139], v[192:195], v[76:79]
	s_setprio 0
	s_barrier
	s_add_i32 s42, s33, s20
	v_lshl_add_u64 v[216:217], s[14:15], 0, v[170:171]
	s_mov_b32 m0, s42
	ds_read_b128 v[200:203], v143
	v_xor_b32_e32 v215, 64, v143
	ds_read_b128 v[204:207], v215
	ds_read_b128 v[208:211], v143 offset:2048
	ds_read_b128 v[212:215], v215 offset:2048
	global_load_lds_dwordx4 v[216:217], off
	v_lshl_add_u64 v[218:219], s[14:15], 0, v[174:175]
	s_add_i32 m0, s42, 0x2000
	s_nop 0
	global_load_lds_dwordx4 v[218:219], off
	s_barrier
	s_waitcnt lgkmcnt(0)
	s_setprio 1
	s_waitcnt lgkmcnt(0)
	v_mfma_f32_16x16x32_bf16 v[116:119], v[200:203], v[158:161], v[116:119]
	v_mfma_f32_16x16x32_bf16 v[116:119], v[204:207], v[164:167], v[116:119]
	v_mfma_f32_16x16x32_bf16 v[112:115], v[212:215], v[164:167], v[112:115]
	v_mfma_f32_16x16x32_bf16 v[112:115], v[208:211], v[158:161], v[112:115]
	v_mfma_f32_16x16x32_bf16 v[96:99], v[208:211], v[176:179], v[96:99]
	v_mfma_f32_16x16x32_bf16 v[96:99], v[212:215], v[180:183], v[96:99]
	v_mfma_f32_16x16x32_bf16 v[100:103], v[204:207], v[180:183], v[100:103]
	v_mfma_f32_16x16x32_bf16 v[100:103], v[200:203], v[176:179], v[100:103]
	v_mfma_f32_16x16x32_bf16 v[84:87], v[200:203], v[184:187], v[84:87]
	v_mfma_f32_16x16x32_bf16 v[84:87], v[204:207], v[188:191], v[84:87]
	v_mfma_f32_16x16x32_bf16 v[80:83], v[212:215], v[188:191], v[80:83]
	v_mfma_f32_16x16x32_bf16 v[80:83], v[208:211], v[184:187], v[80:83]
	v_mfma_f32_16x16x32_bf16 v[64:67], v[208:211], v[192:195], v[64:67]
	v_mfma_f32_16x16x32_bf16 v[64:67], v[212:215], v[196:199], v[64:67]
	v_mfma_f32_16x16x32_bf16 v[68:71], v[204:207], v[196:199], v[68:71]
	v_mfma_f32_16x16x32_bf16 v[68:71], v[200:203], v[192:195], v[68:71]
	s_setprio 0
	s_mov_b32 m0, s21
	v_lshl_add_u64 v[220:221], s[16:17], 0, v[168:169]
	s_barrier
	ds_read_b128 v[158:161], v142 offset:16384
	v_xor_b32_e32 v199, 64, v142
	ds_read_b128 v[164:167], v199 offset:16384
	ds_read_b128 v[176:179], v142 offset:18432
	ds_read_b128 v[180:183], v199 offset:18432
	ds_read_b128 v[184:187], v142 offset:20480
	ds_read_b128 v[188:191], v199 offset:20480
	ds_read_b128 v[192:195], v142 offset:22528
	ds_read_b128 v[196:199], v199 offset:22528
	global_load_lds_dwordx4 v[220:221], off
	v_lshl_add_u64 v[222:223], s[16:17], 0, v[172:173]
	s_mov_b32 m0, s22
	s_nop 0
	global_load_lds_dwordx4 v[222:223], off
	s_barrier
	s_waitcnt lgkmcnt(0)
	s_setprio 1
	s_waitcnt lgkmcnt(0)
	v_mfma_f32_16x16x32_bf16 v[60:63], v[136:139], v[158:161], v[60:63]
	v_mfma_f32_16x16x32_bf16 v[60:63], v[146:149], v[164:167], v[60:63]
	v_mfma_f32_16x16x32_bf16 v[56:59], v[154:157], v[164:167], v[56:59]
	v_mfma_f32_16x16x32_bf16 v[56:59], v[150:153], v[158:161], v[56:59]
	v_mfma_f32_16x16x32_bf16 v[40:43], v[150:153], v[176:179], v[40:43]
	v_mfma_f32_16x16x32_bf16 v[40:43], v[154:157], v[180:183], v[40:43]
	v_mfma_f32_16x16x32_bf16 v[44:47], v[146:149], v[180:183], v[44:47]
	v_mfma_f32_16x16x32_bf16 v[44:47], v[136:139], v[176:179], v[44:47]
	v_mfma_f32_16x16x32_bf16 v[28:31], v[136:139], v[184:187], v[28:31]
	v_mfma_f32_16x16x32_bf16 v[28:31], v[146:149], v[188:191], v[28:31]
	v_mfma_f32_16x16x32_bf16 v[24:27], v[154:157], v[188:191], v[24:27]
	v_mfma_f32_16x16x32_bf16 v[24:27], v[150:153], v[184:187], v[24:27]
	v_mfma_f32_16x16x32_bf16 v[8:11], v[150:153], v[192:195], v[8:11]
	v_mfma_f32_16x16x32_bf16 v[8:11], v[154:157], v[196:199], v[8:11]
	v_mfma_f32_16x16x32_bf16 v[12:15], v[146:149], v[196:199], v[12:15]
	v_mfma_f32_16x16x32_bf16 v[12:15], v[136:139], v[192:195], v[12:15]
	s_setprio 0
	s_barrier
	s_add_u32 s42, s14, 0x160000
	s_addc_u32 s43, s15, 0
	s_add_i32 s44, s34, s20
	v_lshl_add_u64 v[136:137], s[42:43], 0, v[170:171]
	s_mov_b32 m0, s44
	s_nop 0
	global_load_lds_dwordx4 v[136:137], off
	v_lshl_add_u64 v[136:137], s[42:43], 0, v[174:175]
	s_add_i32 m0, s44, 0x2000
	s_nop 0
	global_load_lds_dwordx4 v[136:137], off
	s_waitcnt vmcnt(6)
	s_barrier
	s_setprio 1
	v_mfma_f32_16x16x32_bf16 v[52:55], v[200:203], v[158:161], v[52:55]
	v_mfma_f32_16x16x32_bf16 v[52:55], v[204:207], v[164:167], v[52:55]
	v_mfma_f32_16x16x32_bf16 v[48:51], v[212:215], v[164:167], v[48:51]
	v_mfma_f32_16x16x32_bf16 v[48:51], v[208:211], v[158:161], v[48:51]
	v_mfma_f32_16x16x32_bf16 v[32:35], v[208:211], v[176:179], v[32:35]
	v_mfma_f32_16x16x32_bf16 v[32:35], v[212:215], v[180:183], v[32:35]
	v_mfma_f32_16x16x32_bf16 v[36:39], v[204:207], v[180:183], v[36:39]
	v_mfma_f32_16x16x32_bf16 v[36:39], v[200:203], v[176:179], v[36:39]
	v_mfma_f32_16x16x32_bf16 v[20:23], v[200:203], v[184:187], v[20:23]
	v_mfma_f32_16x16x32_bf16 v[20:23], v[204:207], v[188:191], v[20:23]
	v_mfma_f32_16x16x32_bf16 v[16:19], v[212:215], v[188:191], v[16:19]
	v_mfma_f32_16x16x32_bf16 v[16:19], v[208:211], v[184:187], v[16:19]
	v_mfma_f32_16x16x32_bf16 v[0:3], v[208:211], v[192:195], v[0:3]
	v_mfma_f32_16x16x32_bf16 v[0:3], v[212:215], v[196:199], v[0:3]
	v_mfma_f32_16x16x32_bf16 v[4:7], v[204:207], v[196:199], v[4:7]
	v_mfma_f32_16x16x32_bf16 v[4:7], v[200:203], v[192:195], v[4:7]
	s_setprio 0
	s_add_i32 s42, 0, 0x18000
	v_add_u32_e32 v145, s42, v140
	s_barrier
	ds_read_b128 v[136:139], v145
	v_xor_b32_e32 v157, 64, v145
	ds_read_b128 v[146:149], v157
	ds_read_b128 v[150:153], v145 offset:2048
	ds_read_b128 v[154:157], v157 offset:2048
	s_add_u32 s16, s16, 0x160000
	s_addc_u32 s17, s17, 0
	s_mov_b32 m0, s23
	v_lshl_add_u64 v[200:201], s[16:17], 0, v[168:169]
	ds_read_b128 v[158:161], v142 offset:32768
	v_xor_b32_e32 v199, 64, v142
	ds_read_b128 v[164:167], v199 offset:32768
	ds_read_b128 v[176:179], v142 offset:34816
	ds_read_b128 v[180:183], v199 offset:34816
	ds_read_b128 v[184:187], v142 offset:36864
	ds_read_b128 v[188:191], v199 offset:36864
	ds_read_b128 v[192:195], v142 offset:38912
	ds_read_b128 v[196:199], v199 offset:38912
	global_load_lds_dwordx4 v[200:201], off
	v_lshl_add_u64 v[200:201], s[16:17], 0, v[172:173]
	s_mov_b32 m0, s24
	s_nop 0
	global_load_lds_dwordx4 v[200:201], off
	s_waitcnt lgkmcnt(8)
	s_barrier
	s_waitcnt lgkmcnt(0)
	s_setprio 1
	s_waitcnt lgkmcnt(0)
	v_mfma_f32_16x16x32_bf16 v[124:127], v[136:139], v[158:161], v[124:127]
	v_mfma_f32_16x16x32_bf16 v[124:127], v[146:149], v[164:167], v[124:127]
	v_mfma_f32_16x16x32_bf16 v[120:123], v[154:157], v[164:167], v[120:123]
	v_mfma_f32_16x16x32_bf16 v[120:123], v[150:153], v[158:161], v[120:123]
	v_mfma_f32_16x16x32_bf16 v[104:107], v[150:153], v[176:179], v[104:107]
	v_mfma_f32_16x16x32_bf16 v[104:107], v[154:157], v[180:183], v[104:107]
	v_mfma_f32_16x16x32_bf16 v[108:111], v[146:149], v[180:183], v[108:111]
	v_mfma_f32_16x16x32_bf16 v[108:111], v[136:139], v[176:179], v[108:111]
	v_mfma_f32_16x16x32_bf16 v[92:95], v[136:139], v[184:187], v[92:95]
	v_mfma_f32_16x16x32_bf16 v[92:95], v[146:149], v[188:191], v[92:95]
	v_mfma_f32_16x16x32_bf16 v[88:91], v[154:157], v[188:191], v[88:91]
	v_mfma_f32_16x16x32_bf16 v[88:91], v[150:153], v[184:187], v[88:91]
	v_mfma_f32_16x16x32_bf16 v[72:75], v[150:153], v[192:195], v[72:75]
	v_mfma_f32_16x16x32_bf16 v[72:75], v[154:157], v[196:199], v[72:75]
	v_mfma_f32_16x16x32_bf16 v[76:79], v[146:149], v[196:199], v[76:79]
	v_mfma_f32_16x16x32_bf16 v[76:79], v[136:139], v[192:195], v[76:79]
	s_setprio 0
	s_barrier
	s_add_i32 s16, 0, 0x1c000
	s_add_i32 s17, s42, s20
	v_add_u32_e32 v145, s16, v140
	v_lshl_add_u64 v[216:217], v[216:217], 0, s[12:13]
	s_mov_b32 m0, s17
	ds_read_b128 v[200:203], v145
	v_xor_b32_e32 v215, 64, v145
	ds_read_b128 v[204:207], v215
	ds_read_b128 v[208:211], v145 offset:2048
	ds_read_b128 v[212:215], v215 offset:2048
	global_load_lds_dwordx4 v[216:217], off
	v_lshl_add_u64 v[216:217], v[218:219], 0, s[12:13]
	s_add_i32 m0, s17, 0x2000
	s_nop 0
	global_load_lds_dwordx4 v[216:217], off
	s_barrier
	s_waitcnt lgkmcnt(0)
	s_setprio 1
	s_waitcnt lgkmcnt(0)
	v_mfma_f32_16x16x32_bf16 v[116:119], v[200:203], v[158:161], v[116:119]
	v_mfma_f32_16x16x32_bf16 v[116:119], v[204:207], v[164:167], v[116:119]
	v_mfma_f32_16x16x32_bf16 v[112:115], v[212:215], v[164:167], v[112:115]
	v_mfma_f32_16x16x32_bf16 v[112:115], v[208:211], v[158:161], v[112:115]
	v_mfma_f32_16x16x32_bf16 v[96:99], v[208:211], v[176:179], v[96:99]
	v_mfma_f32_16x16x32_bf16 v[96:99], v[212:215], v[180:183], v[96:99]
	v_mfma_f32_16x16x32_bf16 v[100:103], v[204:207], v[180:183], v[100:103]
	v_mfma_f32_16x16x32_bf16 v[100:103], v[200:203], v[176:179], v[100:103]
	v_mfma_f32_16x16x32_bf16 v[84:87], v[200:203], v[184:187], v[84:87]
	v_mfma_f32_16x16x32_bf16 v[84:87], v[204:207], v[188:191], v[84:87]
	v_mfma_f32_16x16x32_bf16 v[80:83], v[212:215], v[188:191], v[80:83]
	v_mfma_f32_16x16x32_bf16 v[80:83], v[208:211], v[184:187], v[80:83]
	v_mfma_f32_16x16x32_bf16 v[64:67], v[208:211], v[192:195], v[64:67]
	v_mfma_f32_16x16x32_bf16 v[64:67], v[212:215], v[196:199], v[64:67]
	v_mfma_f32_16x16x32_bf16 v[68:71], v[204:207], v[196:199], v[68:71]
	v_mfma_f32_16x16x32_bf16 v[68:71], v[200:203], v[192:195], v[68:71]
	s_setprio 0
	s_mov_b32 m0, s28
	v_lshl_add_u64 v[216:217], v[220:221], 0, s[12:13]
	s_barrier
	ds_read_b128 v[158:161], v142 offset:49152
	v_xor_b32_e32 v199, 64, v142
	ds_read_b128 v[164:167], v199 offset:49152
	ds_read_b128 v[176:179], v142 offset:51200
	ds_read_b128 v[180:183], v199 offset:51200
	ds_read_b128 v[184:187], v142 offset:53248
	ds_read_b128 v[188:191], v199 offset:53248
	ds_read_b128 v[192:195], v142 offset:55296
	ds_read_b128 v[196:199], v199 offset:55296
	global_load_lds_dwordx4 v[216:217], off
	v_lshl_add_u64 v[216:217], v[222:223], 0, s[12:13]
	s_mov_b32 m0, s29
	s_nop 0
	global_load_lds_dwordx4 v[216:217], off
	s_barrier
	s_waitcnt lgkmcnt(0)
	s_setprio 1
	s_waitcnt lgkmcnt(0)
	v_mfma_f32_16x16x32_bf16 v[60:63], v[136:139], v[158:161], v[60:63]
	v_mfma_f32_16x16x32_bf16 v[60:63], v[146:149], v[164:167], v[60:63]
	v_mfma_f32_16x16x32_bf16 v[56:59], v[154:157], v[164:167], v[56:59]
	v_mfma_f32_16x16x32_bf16 v[56:59], v[150:153], v[158:161], v[56:59]
	v_mfma_f32_16x16x32_bf16 v[40:43], v[150:153], v[176:179], v[40:43]
	v_mfma_f32_16x16x32_bf16 v[40:43], v[154:157], v[180:183], v[40:43]
	v_mfma_f32_16x16x32_bf16 v[44:47], v[146:149], v[180:183], v[44:47]
	v_mfma_f32_16x16x32_bf16 v[44:47], v[136:139], v[176:179], v[44:47]
	v_mfma_f32_16x16x32_bf16 v[28:31], v[136:139], v[184:187], v[28:31]
	v_mfma_f32_16x16x32_bf16 v[28:31], v[146:149], v[188:191], v[28:31]
	v_mfma_f32_16x16x32_bf16 v[24:27], v[154:157], v[188:191], v[24:27]
	v_mfma_f32_16x16x32_bf16 v[24:27], v[150:153], v[184:187], v[24:27]
	v_mfma_f32_16x16x32_bf16 v[8:11], v[150:153], v[192:195], v[8:11]
	v_mfma_f32_16x16x32_bf16 v[8:11], v[154:157], v[196:199], v[8:11]
	v_mfma_f32_16x16x32_bf16 v[12:15], v[146:149], v[196:199], v[12:15]
	v_mfma_f32_16x16x32_bf16 v[12:15], v[136:139], v[192:195], v[12:15]
	s_setprio 0
	s_barrier
	s_add_u32 s14, s14, 0x160080
	s_addc_u32 s15, s15, 0
	s_add_i32 s16, s16, s20
	v_lshl_add_u64 v[136:137], s[14:15], 0, v[170:171]
	s_mov_b32 m0, s16
	s_nop 0
	global_load_lds_dwordx4 v[136:137], off
	v_lshl_add_u64 v[136:137], s[14:15], 0, v[174:175]
	s_add_i32 m0, s16, 0x2000
	s_nop 0
	global_load_lds_dwordx4 v[136:137], off
	s_waitcnt vmcnt(6)
	s_barrier
	s_setprio 1
	v_mfma_f32_16x16x32_bf16 v[52:55], v[200:203], v[158:161], v[52:55]
	v_mfma_f32_16x16x32_bf16 v[52:55], v[204:207], v[164:167], v[52:55]
	v_mfma_f32_16x16x32_bf16 v[48:51], v[212:215], v[164:167], v[48:51]
	v_mfma_f32_16x16x32_bf16 v[48:51], v[208:211], v[158:161], v[48:51]
	v_mfma_f32_16x16x32_bf16 v[32:35], v[208:211], v[176:179], v[32:35]
	v_mfma_f32_16x16x32_bf16 v[32:35], v[212:215], v[180:183], v[32:35]
	v_mfma_f32_16x16x32_bf16 v[36:39], v[204:207], v[180:183], v[36:39]
	v_mfma_f32_16x16x32_bf16 v[36:39], v[200:203], v[176:179], v[36:39]
	v_mfma_f32_16x16x32_bf16 v[20:23], v[200:203], v[184:187], v[20:23]
	v_mfma_f32_16x16x32_bf16 v[20:23], v[204:207], v[188:191], v[20:23]
	v_mfma_f32_16x16x32_bf16 v[16:19], v[212:215], v[188:191], v[16:19]
	v_mfma_f32_16x16x32_bf16 v[16:19], v[208:211], v[184:187], v[16:19]
	v_mfma_f32_16x16x32_bf16 v[0:3], v[208:211], v[192:195], v[0:3]
	v_mfma_f32_16x16x32_bf16 v[0:3], v[212:215], v[196:199], v[0:3]
	v_mfma_f32_16x16x32_bf16 v[4:7], v[204:207], v[196:199], v[4:7]
	v_mfma_f32_16x16x32_bf16 v[4:7], v[200:203], v[192:195], v[4:7]
	s_setprio 0
	s_add_i32 s41, s41, 2
	s_add_u32 s0, s0, 0x100
	s_addc_u32 s1, s1, 0
	s_add_u32 s39, s39, 0x100
	s_addc_u32 s40, s40, 0
	s_cmpk_gt_u32 s41, 0x55
	s_barrier
	s_cbranch_scc0 .LBB0_985
	v_lshl_add_u32 v217, s38, 8, v163
	v_add_u32_e32 v217, s26, v217
	v_lshlrev_b32_e32 v208, 2, v217
	v_lshl_add_u32 v214, v225, 3, s27
	v_lshl_add_u32 v214, s37, 8, v214
	v_lshl_add_u32 v209, v217, 11, v214
	v_lshlrev_b32_e32 v209, 1, v209
	v_lshlrev_b32_e32 v210, 1, v209
	v_lshl_add_u32 v217, v225, 4, v163
	v_xor_b32_e32 v215, 16, v217
	v_lshlrev_b32_e32 v215, 2, v215
	v_xor_b32_e32 v216, 32, v217
	v_lshlrev_b32_e32 v216, 2, v216
	v_add_u32_e32 v211, 0x0, v209
	global_load_dwordx4 v[176:179], v211, s[80:81]
	global_load_dwordx4 v[180:183], v211, s[80:81] offset:256
	v_add_u32_e32 v211, 0x10000, v209
	global_load_dwordx4 v[192:195], v211, s[80:81]
	global_load_dwordx4 v[196:199], v211, s[80:81] offset:256
	s_waitcnt vmcnt(2)
	v_lshlrev_b32_e32 v184, 16, v176
	v_and_b32_e32 v185, 0xffff0000, v176
	v_lshlrev_b32_e32 v186, 16, v177
	v_and_b32_e32 v187, 0xffff0000, v177
	v_lshlrev_b32_e32 v188, 16, v178
	v_and_b32_e32 v189, 0xffff0000, v178
	v_lshlrev_b32_e32 v190, 16, v179
	v_and_b32_e32 v191, 0xffff0000, v179
	v_pk_add_f32 v[124:125], v[124:125], v[184:185]
	v_pk_add_f32 v[126:127], v[126:127], v[186:187]
	v_pk_add_f32 v[120:121], v[120:121], v[188:189]
	v_pk_add_f32 v[122:123], v[122:123], v[190:191]
	v_mul_f32_e32 v213, v124, v124
	v_fmac_f32_e32 v213, v125, v125
	v_fmac_f32_e32 v213, v126, v126
	v_fmac_f32_e32 v213, v127, v127
	v_fmac_f32_e32 v213, v120, v120
	v_fmac_f32_e32 v213, v121, v121
	v_fmac_f32_e32 v213, v122, v122
	v_fmac_f32_e32 v213, v123, v123
	v_add_u32_e32 v212, 0x0, v210
	global_store_dwordx4 v212, v[124:127], s[90:91]
	global_store_dwordx4 v212, v[120:123], s[90:91] offset:16
	v_lshlrev_b32_e32 v184, 16, v180
	v_and_b32_e32 v185, 0xffff0000, v180
	v_lshlrev_b32_e32 v186, 16, v181
	v_and_b32_e32 v187, 0xffff0000, v181
	v_lshlrev_b32_e32 v188, 16, v182
	v_and_b32_e32 v189, 0xffff0000, v182
	v_lshlrev_b32_e32 v190, 16, v183
	v_and_b32_e32 v191, 0xffff0000, v183
	v_pk_add_f32 v[116:117], v[116:117], v[184:185]
	v_pk_add_f32 v[118:119], v[118:119], v[186:187]
	v_pk_add_f32 v[112:113], v[112:113], v[188:189]
	v_pk_add_f32 v[114:115], v[114:115], v[190:191]
	v_fmac_f32_e32 v213, v116, v116
	v_fmac_f32_e32 v213, v117, v117
	v_fmac_f32_e32 v213, v118, v118
	v_fmac_f32_e32 v213, v119, v119
	v_fmac_f32_e32 v213, v112, v112
	v_fmac_f32_e32 v213, v113, v113
	v_fmac_f32_e32 v213, v114, v114
	v_fmac_f32_e32 v213, v115, v115
	global_store_dwordx4 v212, v[116:119], s[90:91] offset:512
	global_store_dwordx4 v212, v[112:115], s[90:91] offset:528
	ds_bpermute_b32 v214, v215, v213
	s_waitcnt lgkmcnt(0)
	v_add_f32_e32 v213, v213, v214
	ds_bpermute_b32 v214, v216, v213
	s_waitcnt lgkmcnt(0)
	v_add_f32_e32 v213, v213, v214
	s_mov_b64 exec, 0xffff
	global_atomic_add_f32 v208, v213, s[10:11]
	s_mov_b64 exec, -1
	v_add_u32_e32 v211, 0x20000, v209
	global_load_dwordx4 v[176:179], v211, s[80:81]
	global_load_dwordx4 v[180:183], v211, s[80:81] offset:256
	s_waitcnt vmcnt(7)
	v_lshlrev_b32_e32 v200, 16, v192
	v_and_b32_e32 v201, 0xffff0000, v192
	v_lshlrev_b32_e32 v202, 16, v193
	v_and_b32_e32 v203, 0xffff0000, v193
	v_lshlrev_b32_e32 v204, 16, v194
	v_and_b32_e32 v205, 0xffff0000, v194
	v_lshlrev_b32_e32 v206, 16, v195
	v_and_b32_e32 v207, 0xffff0000, v195
	v_pk_add_f32 v[108:109], v[108:109], v[200:201]
	v_pk_add_f32 v[110:111], v[110:111], v[202:203]
	v_pk_add_f32 v[104:105], v[104:105], v[204:205]
	v_pk_add_f32 v[106:107], v[106:107], v[206:207]
	v_mul_f32_e32 v213, v108, v108
	v_fmac_f32_e32 v213, v109, v109
	v_fmac_f32_e32 v213, v110, v110
	v_fmac_f32_e32 v213, v111, v111
	v_fmac_f32_e32 v213, v104, v104
	v_fmac_f32_e32 v213, v105, v105
	v_fmac_f32_e32 v213, v106, v106
	v_fmac_f32_e32 v213, v107, v107
	v_add_u32_e32 v212, 0x20000, v210
	global_store_dwordx4 v212, v[108:111], s[90:91]
	global_store_dwordx4 v212, v[104:107], s[90:91] offset:16
	v_lshlrev_b32_e32 v200, 16, v196
	v_and_b32_e32 v201, 0xffff0000, v196
	v_lshlrev_b32_e32 v202, 16, v197
	v_and_b32_e32 v203, 0xffff0000, v197
	v_lshlrev_b32_e32 v204, 16, v198
	v_and_b32_e32 v205, 0xffff0000, v198
	v_lshlrev_b32_e32 v206, 16, v199
	v_and_b32_e32 v207, 0xffff0000, v199
	v_pk_add_f32 v[100:101], v[100:101], v[200:201]
	v_pk_add_f32 v[102:103], v[102:103], v[202:203]
	v_pk_add_f32 v[96:97], v[96:97], v[204:205]
	v_pk_add_f32 v[98:99], v[98:99], v[206:207]
	v_fmac_f32_e32 v213, v100, v100
	v_fmac_f32_e32 v213, v101, v101
	v_fmac_f32_e32 v213, v102, v102
	v_fmac_f32_e32 v213, v103, v103
	v_fmac_f32_e32 v213, v96, v96
	v_fmac_f32_e32 v213, v97, v97
	v_fmac_f32_e32 v213, v98, v98
	v_fmac_f32_e32 v213, v99, v99
	global_store_dwordx4 v212, v[100:103], s[90:91] offset:512
	global_store_dwordx4 v212, v[96:99], s[90:91] offset:528
	ds_bpermute_b32 v214, v215, v213
	s_waitcnt lgkmcnt(0)
	v_add_f32_e32 v213, v213, v214
	ds_bpermute_b32 v214, v216, v213
	s_waitcnt lgkmcnt(0)
	v_add_f32_e32 v213, v213, v214
	s_mov_b64 exec, 0xffff
	global_atomic_add_f32 v208, v213, s[10:11] offset:64
	s_mov_b64 exec, -1
	v_add_u32_e32 v211, 0x30000, v209
	global_load_dwordx4 v[192:195], v211, s[80:81]
	global_load_dwordx4 v[196:199], v211, s[80:81] offset:256
	s_waitcnt vmcnt(7)
	v_lshlrev_b32_e32 v184, 16, v176
	v_and_b32_e32 v185, 0xffff0000, v176
	v_lshlrev_b32_e32 v186, 16, v177
	v_and_b32_e32 v187, 0xffff0000, v177
	v_lshlrev_b32_e32 v188, 16, v178
	v_and_b32_e32 v189, 0xffff0000, v178
	v_lshlrev_b32_e32 v190, 16, v179
	v_and_b32_e32 v191, 0xffff0000, v179
	v_pk_add_f32 v[92:93], v[92:93], v[184:185]
	v_pk_add_f32 v[94:95], v[94:95], v[186:187]
	v_pk_add_f32 v[88:89], v[88:89], v[188:189]
	v_pk_add_f32 v[90:91], v[90:91], v[190:191]
	v_mul_f32_e32 v213, v92, v92
	v_fmac_f32_e32 v213, v93, v93
	v_fmac_f32_e32 v213, v94, v94
	v_fmac_f32_e32 v213, v95, v95
	v_fmac_f32_e32 v213, v88, v88
	v_fmac_f32_e32 v213, v89, v89
	v_fmac_f32_e32 v213, v90, v90
	v_fmac_f32_e32 v213, v91, v91
	v_add_u32_e32 v212, 0x40000, v210
	global_store_dwordx4 v212, v[92:95], s[90:91]
	global_store_dwordx4 v212, v[88:91], s[90:91] offset:16
	v_lshlrev_b32_e32 v184, 16, v180
	v_and_b32_e32 v185, 0xffff0000, v180
	v_lshlrev_b32_e32 v186, 16, v181
	v_and_b32_e32 v187, 0xffff0000, v181
	v_lshlrev_b32_e32 v188, 16, v182
	v_and_b32_e32 v189, 0xffff0000, v182
	v_lshlrev_b32_e32 v190, 16, v183
	v_and_b32_e32 v191, 0xffff0000, v183
	v_pk_add_f32 v[84:85], v[84:85], v[184:185]
	v_pk_add_f32 v[86:87], v[86:87], v[186:187]
	v_pk_add_f32 v[80:81], v[80:81], v[188:189]
	v_pk_add_f32 v[82:83], v[82:83], v[190:191]
	v_fmac_f32_e32 v213, v84, v84
	v_fmac_f32_e32 v213, v85, v85
	v_fmac_f32_e32 v213, v86, v86
	v_fmac_f32_e32 v213, v87, v87
	v_fmac_f32_e32 v213, v80, v80
	v_fmac_f32_e32 v213, v81, v81
	v_fmac_f32_e32 v213, v82, v82
	v_fmac_f32_e32 v213, v83, v83
	global_store_dwordx4 v212, v[84:87], s[90:91] offset:512
	global_store_dwordx4 v212, v[80:83], s[90:91] offset:528
	ds_bpermute_b32 v214, v215, v213
	s_waitcnt lgkmcnt(0)
	v_add_f32_e32 v213, v213, v214
	ds_bpermute_b32 v214, v216, v213
	s_waitcnt lgkmcnt(0)
	v_add_f32_e32 v213, v213, v214
	s_mov_b64 exec, 0xffff
	global_atomic_add_f32 v208, v213, s[10:11] offset:128
	s_mov_b64 exec, -1
	v_add_u32_e32 v211, 0x80000, v209
	global_load_dwordx4 v[176:179], v211, s[80:81]
	global_load_dwordx4 v[180:183], v211, s[80:81] offset:256
	s_waitcnt vmcnt(7)
	v_lshlrev_b32_e32 v200, 16, v192
	v_and_b32_e32 v201, 0xffff0000, v192
	v_lshlrev_b32_e32 v202, 16, v193
	v_and_b32_e32 v203, 0xffff0000, v193
	v_lshlrev_b32_e32 v204, 16, v194
	v_and_b32_e32 v205, 0xffff0000, v194
	v_lshlrev_b32_e32 v206, 16, v195
	v_and_b32_e32 v207, 0xffff0000, v195
	v_pk_add_f32 v[76:77], v[76:77], v[200:201]
	v_pk_add_f32 v[78:79], v[78:79], v[202:203]
	v_pk_add_f32 v[72:73], v[72:73], v[204:205]
	v_pk_add_f32 v[74:75], v[74:75], v[206:207]
	v_mul_f32_e32 v213, v76, v76
	v_fmac_f32_e32 v213, v77, v77
	v_fmac_f32_e32 v213, v78, v78
	v_fmac_f32_e32 v213, v79, v79
	v_fmac_f32_e32 v213, v72, v72
	v_fmac_f32_e32 v213, v73, v73
	v_fmac_f32_e32 v213, v74, v74
	v_fmac_f32_e32 v213, v75, v75
	v_add_u32_e32 v212, 0x60000, v210
	global_store_dwordx4 v212, v[76:79], s[90:91]
	global_store_dwordx4 v212, v[72:75], s[90:91] offset:16
	v_lshlrev_b32_e32 v200, 16, v196
	v_and_b32_e32 v201, 0xffff0000, v196
	v_lshlrev_b32_e32 v202, 16, v197
	v_and_b32_e32 v203, 0xffff0000, v197
	v_lshlrev_b32_e32 v204, 16, v198
	v_and_b32_e32 v205, 0xffff0000, v198
	v_lshlrev_b32_e32 v206, 16, v199
	v_and_b32_e32 v207, 0xffff0000, v199
	v_pk_add_f32 v[68:69], v[68:69], v[200:201]
	v_pk_add_f32 v[70:71], v[70:71], v[202:203]
	v_pk_add_f32 v[64:65], v[64:65], v[204:205]
	v_pk_add_f32 v[66:67], v[66:67], v[206:207]
	v_fmac_f32_e32 v213, v68, v68
	v_fmac_f32_e32 v213, v69, v69
	v_fmac_f32_e32 v213, v70, v70
	v_fmac_f32_e32 v213, v71, v71
	v_fmac_f32_e32 v213, v64, v64
	v_fmac_f32_e32 v213, v65, v65
	v_fmac_f32_e32 v213, v66, v66
	v_fmac_f32_e32 v213, v67, v67
	global_store_dwordx4 v212, v[68:71], s[90:91] offset:512
	global_store_dwordx4 v212, v[64:67], s[90:91] offset:528
	ds_bpermute_b32 v214, v215, v213
	s_waitcnt lgkmcnt(0)
	v_add_f32_e32 v213, v213, v214
	ds_bpermute_b32 v214, v216, v213
	s_waitcnt lgkmcnt(0)
	v_add_f32_e32 v213, v213, v214
	s_mov_b64 exec, 0xffff
	global_atomic_add_f32 v208, v213, s[10:11] offset:192
	s_mov_b64 exec, -1
	v_add_u32_e32 v211, 0x90000, v209
	global_load_dwordx4 v[192:195], v211, s[80:81]
	global_load_dwordx4 v[196:199], v211, s[80:81] offset:256
	s_waitcnt vmcnt(7)
	v_lshlrev_b32_e32 v184, 16, v176
	v_and_b32_e32 v185, 0xffff0000, v176
	v_lshlrev_b32_e32 v186, 16, v177
	v_and_b32_e32 v187, 0xffff0000, v177
	v_lshlrev_b32_e32 v188, 16, v178
	v_and_b32_e32 v189, 0xffff0000, v178
	v_lshlrev_b32_e32 v190, 16, v179
	v_and_b32_e32 v191, 0xffff0000, v179
	v_pk_add_f32 v[60:61], v[60:61], v[184:185]
	v_pk_add_f32 v[62:63], v[62:63], v[186:187]
	v_pk_add_f32 v[56:57], v[56:57], v[188:189]
	v_pk_add_f32 v[58:59], v[58:59], v[190:191]
	v_mul_f32_e32 v213, v60, v60
	v_fmac_f32_e32 v213, v61, v61
	v_fmac_f32_e32 v213, v62, v62
	v_fmac_f32_e32 v213, v63, v63
	v_fmac_f32_e32 v213, v56, v56
	v_fmac_f32_e32 v213, v57, v57
	v_fmac_f32_e32 v213, v58, v58
	v_fmac_f32_e32 v213, v59, v59
	v_add_u32_e32 v212, 0x100000, v210
	global_store_dwordx4 v212, v[60:63], s[90:91]
	global_store_dwordx4 v212, v[56:59], s[90:91] offset:16
	v_lshlrev_b32_e32 v184, 16, v180
	v_and_b32_e32 v185, 0xffff0000, v180
	v_lshlrev_b32_e32 v186, 16, v181
	v_and_b32_e32 v187, 0xffff0000, v181
	v_lshlrev_b32_e32 v188, 16, v182
	v_and_b32_e32 v189, 0xffff0000, v182
	v_lshlrev_b32_e32 v190, 16, v183
	v_and_b32_e32 v191, 0xffff0000, v183
	v_pk_add_f32 v[52:53], v[52:53], v[184:185]
	v_pk_add_f32 v[54:55], v[54:55], v[186:187]
	v_pk_add_f32 v[48:49], v[48:49], v[188:189]
	v_pk_add_f32 v[50:51], v[50:51], v[190:191]
	v_fmac_f32_e32 v213, v52, v52
	v_fmac_f32_e32 v213, v53, v53
	v_fmac_f32_e32 v213, v54, v54
	v_fmac_f32_e32 v213, v55, v55
	v_fmac_f32_e32 v213, v48, v48
	v_fmac_f32_e32 v213, v49, v49
	v_fmac_f32_e32 v213, v50, v50
	v_fmac_f32_e32 v213, v51, v51
	global_store_dwordx4 v212, v[52:55], s[90:91] offset:512
	global_store_dwordx4 v212, v[48:51], s[90:91] offset:528
	ds_bpermute_b32 v214, v215, v213
	s_waitcnt lgkmcnt(0)
	v_add_f32_e32 v213, v213, v214
	ds_bpermute_b32 v214, v216, v213
	s_waitcnt lgkmcnt(0)
	v_add_f32_e32 v213, v213, v214
	s_mov_b64 exec, 0xffff
	global_atomic_add_f32 v208, v213, s[10:11] offset:512
	s_mov_b64 exec, -1
	v_add_u32_e32 v211, 0xa0000, v209
	global_load_dwordx4 v[176:179], v211, s[80:81]
	global_load_dwordx4 v[180:183], v211, s[80:81] offset:256
	s_waitcnt vmcnt(7)
	v_lshlrev_b32_e32 v200, 16, v192
	v_and_b32_e32 v201, 0xffff0000, v192
	v_lshlrev_b32_e32 v202, 16, v193
	v_and_b32_e32 v203, 0xffff0000, v193
	v_lshlrev_b32_e32 v204, 16, v194
	v_and_b32_e32 v205, 0xffff0000, v194
	v_lshlrev_b32_e32 v206, 16, v195
	v_and_b32_e32 v207, 0xffff0000, v195
	v_pk_add_f32 v[44:45], v[44:45], v[200:201]
	v_pk_add_f32 v[46:47], v[46:47], v[202:203]
	v_pk_add_f32 v[40:41], v[40:41], v[204:205]
	v_pk_add_f32 v[42:43], v[42:43], v[206:207]
	v_mul_f32_e32 v213, v44, v44
	v_fmac_f32_e32 v213, v45, v45
	v_fmac_f32_e32 v213, v46, v46
	v_fmac_f32_e32 v213, v47, v47
	v_fmac_f32_e32 v213, v40, v40
	v_fmac_f32_e32 v213, v41, v41
	v_fmac_f32_e32 v213, v42, v42
	v_fmac_f32_e32 v213, v43, v43
	v_add_u32_e32 v212, 0x120000, v210
	global_store_dwordx4 v212, v[44:47], s[90:91]
	global_store_dwordx4 v212, v[40:43], s[90:91] offset:16
	v_lshlrev_b32_e32 v200, 16, v196
	v_and_b32_e32 v201, 0xffff0000, v196
	v_lshlrev_b32_e32 v202, 16, v197
	v_and_b32_e32 v203, 0xffff0000, v197
	v_lshlrev_b32_e32 v204, 16, v198
	v_and_b32_e32 v205, 0xffff0000, v198
	v_lshlrev_b32_e32 v206, 16, v199
	v_and_b32_e32 v207, 0xffff0000, v199
	v_pk_add_f32 v[36:37], v[36:37], v[200:201]
	v_pk_add_f32 v[38:39], v[38:39], v[202:203]
	v_pk_add_f32 v[32:33], v[32:33], v[204:205]
	v_pk_add_f32 v[34:35], v[34:35], v[206:207]
	v_fmac_f32_e32 v213, v36, v36
	v_fmac_f32_e32 v213, v37, v37
	v_fmac_f32_e32 v213, v38, v38
	v_fmac_f32_e32 v213, v39, v39
	v_fmac_f32_e32 v213, v32, v32
	v_fmac_f32_e32 v213, v33, v33
	v_fmac_f32_e32 v213, v34, v34
	v_fmac_f32_e32 v213, v35, v35
	global_store_dwordx4 v212, v[36:39], s[90:91] offset:512
	global_store_dwordx4 v212, v[32:35], s[90:91] offset:528
	ds_bpermute_b32 v214, v215, v213
	s_waitcnt lgkmcnt(0)
	v_add_f32_e32 v213, v213, v214
	ds_bpermute_b32 v214, v216, v213
	s_waitcnt lgkmcnt(0)
	v_add_f32_e32 v213, v213, v214
	s_mov_b64 exec, 0xffff
	global_atomic_add_f32 v208, v213, s[10:11] offset:576
	s_mov_b64 exec, -1
	v_add_u32_e32 v211, 0xb0000, v209
	global_load_dwordx4 v[192:195], v211, s[80:81]
	global_load_dwordx4 v[196:199], v211, s[80:81] offset:256
	s_waitcnt vmcnt(7)
	v_lshlrev_b32_e32 v184, 16, v176
	v_and_b32_e32 v185, 0xffff0000, v176
	v_lshlrev_b32_e32 v186, 16, v177
	v_and_b32_e32 v187, 0xffff0000, v177
	v_lshlrev_b32_e32 v188, 16, v178
	v_and_b32_e32 v189, 0xffff0000, v178
	v_lshlrev_b32_e32 v190, 16, v179
	v_and_b32_e32 v191, 0xffff0000, v179
	v_pk_add_f32 v[28:29], v[28:29], v[184:185]
	v_pk_add_f32 v[30:31], v[30:31], v[186:187]
	v_pk_add_f32 v[24:25], v[24:25], v[188:189]
	v_pk_add_f32 v[26:27], v[26:27], v[190:191]
	v_mul_f32_e32 v213, v28, v28
	v_fmac_f32_e32 v213, v29, v29
	v_fmac_f32_e32 v213, v30, v30
	v_fmac_f32_e32 v213, v31, v31
	v_fmac_f32_e32 v213, v24, v24
	v_fmac_f32_e32 v213, v25, v25
	v_fmac_f32_e32 v213, v26, v26
	v_fmac_f32_e32 v213, v27, v27
	v_add_u32_e32 v212, 0x140000, v210
	global_store_dwordx4 v212, v[28:31], s[90:91]
	global_store_dwordx4 v212, v[24:27], s[90:91] offset:16
	v_lshlrev_b32_e32 v184, 16, v180
	v_and_b32_e32 v185, 0xffff0000, v180
	v_lshlrev_b32_e32 v186, 16, v181
	v_and_b32_e32 v187, 0xffff0000, v181
	v_lshlrev_b32_e32 v188, 16, v182
	v_and_b32_e32 v189, 0xffff0000, v182
	v_lshlrev_b32_e32 v190, 16, v183
	v_and_b32_e32 v191, 0xffff0000, v183
	v_pk_add_f32 v[20:21], v[20:21], v[184:185]
	v_pk_add_f32 v[22:23], v[22:23], v[186:187]
	v_pk_add_f32 v[16:17], v[16:17], v[188:189]
	v_pk_add_f32 v[18:19], v[18:19], v[190:191]
	v_fmac_f32_e32 v213, v20, v20
	v_fmac_f32_e32 v213, v21, v21
	v_fmac_f32_e32 v213, v22, v22
	v_fmac_f32_e32 v213, v23, v23
	v_fmac_f32_e32 v213, v16, v16
	v_fmac_f32_e32 v213, v17, v17
	v_fmac_f32_e32 v213, v18, v18
	v_fmac_f32_e32 v213, v19, v19
	global_store_dwordx4 v212, v[20:23], s[90:91] offset:512
	global_store_dwordx4 v212, v[16:19], s[90:91] offset:528
	ds_bpermute_b32 v214, v215, v213
	s_waitcnt lgkmcnt(0)
	v_add_f32_e32 v213, v213, v214
	ds_bpermute_b32 v214, v216, v213
	s_waitcnt lgkmcnt(0)
	v_add_f32_e32 v213, v213, v214
	s_mov_b64 exec, 0xffff
	global_atomic_add_f32 v208, v213, s[10:11] offset:640
	s_mov_b64 exec, -1
	s_waitcnt vmcnt(5)
	v_lshlrev_b32_e32 v200, 16, v192
	v_and_b32_e32 v201, 0xffff0000, v192
	v_lshlrev_b32_e32 v202, 16, v193
	v_and_b32_e32 v203, 0xffff0000, v193
	v_lshlrev_b32_e32 v204, 16, v194
	v_and_b32_e32 v205, 0xffff0000, v194
	v_lshlrev_b32_e32 v206, 16, v195
	v_and_b32_e32 v207, 0xffff0000, v195
	v_pk_add_f32 v[12:13], v[12:13], v[200:201]
	v_pk_add_f32 v[14:15], v[14:15], v[202:203]
	v_pk_add_f32 v[8:9], v[8:9], v[204:205]
	v_pk_add_f32 v[10:11], v[10:11], v[206:207]
	v_mul_f32_e32 v213, v12, v12
	v_fmac_f32_e32 v213, v13, v13
	v_fmac_f32_e32 v213, v14, v14
	v_fmac_f32_e32 v213, v15, v15
	v_fmac_f32_e32 v213, v8, v8
	v_fmac_f32_e32 v213, v9, v9
	v_fmac_f32_e32 v213, v10, v10
	v_fmac_f32_e32 v213, v11, v11
	v_add_u32_e32 v212, 0x160000, v210
	global_store_dwordx4 v212, v[12:15], s[90:91]
	global_store_dwordx4 v212, v[8:11], s[90:91] offset:16
	v_lshlrev_b32_e32 v200, 16, v196
	v_and_b32_e32 v201, 0xffff0000, v196
	v_lshlrev_b32_e32 v202, 16, v197
	v_and_b32_e32 v203, 0xffff0000, v197
	v_lshlrev_b32_e32 v204, 16, v198
	v_and_b32_e32 v205, 0xffff0000, v198
	v_lshlrev_b32_e32 v206, 16, v199
	v_and_b32_e32 v207, 0xffff0000, v199
	v_pk_add_f32 v[4:5], v[4:5], v[200:201]
	v_pk_add_f32 v[6:7], v[6:7], v[202:203]
	v_pk_add_f32 v[0:1], v[0:1], v[204:205]
	v_pk_add_f32 v[2:3], v[2:3], v[206:207]
	v_fmac_f32_e32 v213, v4, v4
	v_fmac_f32_e32 v213, v5, v5
	v_fmac_f32_e32 v213, v6, v6
	v_fmac_f32_e32 v213, v7, v7
	v_fmac_f32_e32 v213, v0, v0
	v_fmac_f32_e32 v213, v1, v1
	v_fmac_f32_e32 v213, v2, v2
	v_fmac_f32_e32 v213, v3, v3
	global_store_dwordx4 v212, v[4:7], s[90:91] offset:512
	global_store_dwordx4 v212, v[0:3], s[90:91] offset:528
	ds_bpermute_b32 v214, v215, v213
	s_waitcnt lgkmcnt(0)
	v_add_f32_e32 v213, v213, v214
	ds_bpermute_b32 v214, v216, v213
	s_waitcnt lgkmcnt(0)
	v_add_f32_e32 v213, v213, v214
	s_mov_b64 exec, 0xffff
	global_atomic_add_f32 v208, v213, s[10:11] offset:704
	s_mov_b64 exec, -1
	s_branch .LBB0_973
